# merge: operands staged by LDS-DMA into a swizzled lane-linear image (3 buffers, counted vmcnt), whole tile as one 32-step stream, 12 fragment slots
# speedup vs baseline: 1.0110x; 1.0083x over previous
.LBB0_1004:
	v_and_b32_e32 v2, 7, v192
	v_lshrrev_b32_e32 v3, 3, v192
	v_bfe_u32 v4, v192, 4, 3
	v_xor_b32_e32 v2, v2, v4
	v_lshlrev_b32_e32 v2, 4, v2
	v_mul_u32_u24_e32 v4, 0x3e00, v3
	v_add_u32_e32 v188, v4, v2
	v_add_u32_e32 v189, 0xf8000, v188
	v_add_u32_e32 v190, 0x1f0000, v188
	v_add_u32_e32 v191, 0x2e8000, v188
	v_and_b32_e32 v4, 35, v3
	v_bfe_u32 v5, v3, 4, 1
	v_lshl_or_b32 v4, v5, 2, v4
	v_bfe_u32 v5, v3, 2, 2
	v_lshl_or_b32 v4, v5, 3, v4
	v_lshl_or_b32 v205, v4, 10, v2
	v_add_u32_e32 v206, 0x10000, v205
	v_bfe_u32 v2, v192, 1, 3
	v_bfe_u32 v3, v192, 4, 2
	v_xor_b32_e32 v2, v2, v3
	v_lshlrev_b32_e32 v2, 4, v2
	v_and_b32_e32 v3, 15, v192
	v_lshrrev_b32_e32 v4, 7, v192
	v_lshl_or_b32 v4, v4, 6, v3
	v_lshl_or_b32 v207, v4, 7, v2
	v_xor_b32_e32 v119, 64, v207
	v_add_u32_e32 v0, 0x10000, v207
	v_add_u32_e32 v255, 0x10000, v119
	v_bfe_u32 v4, v192, 6, 1
	v_lshl_or_b32 v4, v4, 6, v3
	v_lshl_or_b32 v4, v4, 7, v2
	v_add_u32_e32 v90, 0x18000, v4
	v_xor_b32_e32 v91, 64, v90
	v_lshrrev_b32_e32 v5, 6, v192
	s_nop 0
	v_readfirstlane_b32 s67, v5
	s_lshl_b32 s67, s67, 10
	s_add_u32 s80, s46, 0xc00
	s_addc_u32 s81, s47, 0
	s_mov_b32 s96, s48
	s_mov_b32 s97, s49
	s_add_i32 m0, s67, 0x0
	s_nop 0
	global_load_lds_dwordx4 v188, s[80:81]
	s_add_i32 m0, s67, 0x2000
	s_nop 0
	global_load_lds_dwordx4 v189, s[80:81]
	s_add_i32 m0, s67, 0x4000
	s_nop 0
	global_load_lds_dwordx4 v190, s[80:81]
	s_add_i32 m0, s67, 0x6000
	s_nop 0
	global_load_lds_dwordx4 v191, s[80:81]
	s_add_i32 m0, s67, 0x18000
	s_nop 0
	global_load_lds_dwordx4 v205, s[96:97]
	s_add_i32 m0, s67, 0x1a000
	s_nop 0
	global_load_lds_dwordx4 v206, s[96:97]
	s_add_u32 s80, s80, 0x80
	s_addc_u32 s81, s81, 0
	s_add_u32 s96, s96, 0x80
	s_addc_u32 s97, s97, 0
	s_add_i32 m0, s67, 0x8000
	s_nop 0
	global_load_lds_dwordx4 v188, s[80:81]
	s_add_i32 m0, s67, 0xa000
	s_nop 0
	global_load_lds_dwordx4 v189, s[80:81]
	s_add_i32 m0, s67, 0xc000
	s_nop 0
	global_load_lds_dwordx4 v190, s[80:81]
	s_add_i32 m0, s67, 0xe000
	s_nop 0
	global_load_lds_dwordx4 v191, s[80:81]
	s_add_i32 m0, s67, 0x1c000
	s_nop 0
	global_load_lds_dwordx4 v205, s[96:97]
	s_add_i32 m0, s67, 0x1e000
	s_nop 0
	global_load_lds_dwordx4 v206, s[96:97]
	s_add_u32 s80, s80, 0x80
	s_addc_u32 s81, s81, 0
	s_add_u32 s96, s96, 0x80
	s_addc_u32 s97, s97, 0
	s_add_i32 m0, s67, 0x10000
	s_nop 0
	global_load_lds_dwordx4 v188, s[80:81]
	s_add_i32 m0, s67, 0x12000
	s_nop 0
	global_load_lds_dwordx4 v189, s[80:81]
	s_add_i32 m0, s67, 0x14000
	s_nop 0
	global_load_lds_dwordx4 v190, s[80:81]
	s_add_i32 m0, s67, 0x16000
	s_nop 0
	global_load_lds_dwordx4 v191, s[80:81]
	s_add_i32 m0, s67, 0x20400
	s_nop 0
	global_load_lds_dwordx4 v205, s[96:97]
	s_add_i32 m0, s67, 0x22400
	s_nop 0
	global_load_lds_dwordx4 v206, s[96:97]
	s_add_u32 s80, s80, 0x80
	s_addc_u32 s81, s81, 0
	s_add_u32 s96, s96, 0x80
	s_addc_u32 s97, s97, 0
	s_waitcnt vmcnt(12)
	s_barrier
	ds_read_b128 v[82:85], v90 offset:0
	ds_read_b128 v[86:89], v90 offset:2048
	ds_read_b128 v[208:211], v90 offset:4096
	ds_read_b128 v[212:215], v90 offset:6144
	ds_read_b128 v[66:69], v207 offset:0
	ds_read_b128 v[70:73], v207 offset:2048
	ds_read_b128 v[74:77], v207 offset:4096
	ds_read_b128 v[78:81], v207 offset:6144
	ds_read_b128 v[216:219], v91 offset:0
	ds_read_b128 v[220:223], v91 offset:2048
	ds_read_b128 v[224:227], v91 offset:4096
	ds_read_b128 v[228:231], v91 offset:6144
	s_waitcnt lgkmcnt(7)
	v_mfma_f32_16x16x32_bf16 v[6:9], v[82:85], v[66:69], 0
	v_mfma_f32_16x16x32_bf16 v[30:33], v[86:89], v[66:69], 0
	v_mfma_f32_16x16x32_bf16 v[38:41], v[208:211], v[66:69], 0
	v_mfma_f32_16x16x32_bf16 v[42:45], v[212:215], v[66:69], 0
	ds_read_b128 v[66:69], v119 offset:0
	s_waitcnt lgkmcnt(7)
	v_mfma_f32_16x16x32_bf16 v[46:49], v[82:85], v[70:73], 0
	v_mfma_f32_16x16x32_bf16 v[26:29], v[86:89], v[70:73], 0
	v_mfma_f32_16x16x32_bf16 v[14:17], v[208:211], v[70:73], 0
	v_mfma_f32_16x16x32_bf16 v[10:13], v[212:215], v[70:73], 0
	ds_read_b128 v[70:73], v119 offset:2048
	s_waitcnt lgkmcnt(7)
	v_mfma_f32_16x16x32_bf16 v[34:37], v[82:85], v[74:77], 0
	v_mfma_f32_16x16x32_bf16 v[22:25], v[86:89], v[74:77], 0
	v_mfma_f32_16x16x32_bf16 v[18:21], v[208:211], v[74:77], 0
	v_mfma_f32_16x16x32_bf16 v[62:65], v[212:215], v[74:77], 0
	ds_read_b128 v[74:77], v119 offset:4096
	s_waitcnt lgkmcnt(7)
	v_mfma_f32_16x16x32_bf16 v[58:61], v[82:85], v[78:81], 0
	v_mfma_f32_16x16x32_bf16 v[54:57], v[86:89], v[78:81], 0
	v_mfma_f32_16x16x32_bf16 v[50:53], v[208:211], v[78:81], 0
	v_mfma_f32_16x16x32_bf16 v[2:5], v[212:215], v[78:81], 0
	ds_read_b128 v[78:81], v119 offset:6144
	s_waitcnt lgkmcnt(3)
	v_mfma_f32_16x16x32_bf16 v[6:9], v[216:219], v[66:69], v[6:9]
	v_mfma_f32_16x16x32_bf16 v[30:33], v[220:223], v[66:69], v[30:33]
	v_mfma_f32_16x16x32_bf16 v[38:41], v[224:227], v[66:69], v[38:41]
	v_mfma_f32_16x16x32_bf16 v[42:45], v[228:231], v[66:69], v[42:45]
	s_waitcnt lgkmcnt(2)
	v_mfma_f32_16x16x32_bf16 v[46:49], v[216:219], v[70:73], v[46:49]
	v_mfma_f32_16x16x32_bf16 v[26:29], v[220:223], v[70:73], v[26:29]
	v_mfma_f32_16x16x32_bf16 v[14:17], v[224:227], v[70:73], v[14:17]
	v_mfma_f32_16x16x32_bf16 v[10:13], v[228:231], v[70:73], v[10:13]
	s_waitcnt vmcnt(6)
	s_waitcnt lgkmcnt(0)
	s_barrier
	s_add_i32 m0, s67, 0x0
	s_nop 0
	global_load_lds_dwordx4 v188, s[80:81]
	s_add_i32 m0, s67, 0x2000
	s_nop 0
	global_load_lds_dwordx4 v189, s[80:81]
	s_add_i32 m0, s67, 0x4000
	s_nop 0
	global_load_lds_dwordx4 v190, s[80:81]
	s_add_i32 m0, s67, 0x6000
	s_nop 0
	global_load_lds_dwordx4 v191, s[80:81]
	s_add_i32 m0, s67, 0x18000
	s_nop 0
	global_load_lds_dwordx4 v205, s[96:97]
	s_add_i32 m0, s67, 0x1a000
	s_nop 0
	global_load_lds_dwordx4 v206, s[96:97]
	s_add_u32 s80, s80, 0x80
	s_addc_u32 s81, s81, 0
	s_add_u32 s96, s96, 0x80
	s_addc_u32 s97, s97, 0
	ds_read_b128 v[82:85], v90 offset:16384
	ds_read_b128 v[86:89], v90 offset:18432
	ds_read_b128 v[208:211], v90 offset:20480
	ds_read_b128 v[212:215], v90 offset:22528
	ds_read_b128 v[66:69], v207 offset:32768
	ds_read_b128 v[70:73], v207 offset:34816
	v_mfma_f32_16x16x32_bf16 v[34:37], v[216:219], v[74:77], v[34:37]
	v_mfma_f32_16x16x32_bf16 v[22:25], v[220:223], v[74:77], v[22:25]
	v_mfma_f32_16x16x32_bf16 v[18:21], v[224:227], v[74:77], v[18:21]
	v_mfma_f32_16x16x32_bf16 v[62:65], v[228:231], v[74:77], v[62:65]
	ds_read_b128 v[74:77], v207 offset:36864
	v_mfma_f32_16x16x32_bf16 v[58:61], v[216:219], v[78:81], v[58:61]
	v_mfma_f32_16x16x32_bf16 v[54:57], v[220:223], v[78:81], v[54:57]
	v_mfma_f32_16x16x32_bf16 v[50:53], v[224:227], v[78:81], v[50:53]
	v_mfma_f32_16x16x32_bf16 v[2:5], v[228:231], v[78:81], v[2:5]
	ds_read_b128 v[78:81], v207 offset:38912
	ds_read_b128 v[216:219], v91 offset:16384
	ds_read_b128 v[220:223], v91 offset:18432
	ds_read_b128 v[224:227], v91 offset:20480
	ds_read_b128 v[228:231], v91 offset:22528
	s_waitcnt lgkmcnt(7)
	v_mfma_f32_16x16x32_bf16 v[6:9], v[82:85], v[66:69], v[6:9]
	v_mfma_f32_16x16x32_bf16 v[30:33], v[86:89], v[66:69], v[30:33]
	v_mfma_f32_16x16x32_bf16 v[38:41], v[208:211], v[66:69], v[38:41]
	v_mfma_f32_16x16x32_bf16 v[42:45], v[212:215], v[66:69], v[42:45]
	ds_read_b128 v[66:69], v119 offset:32768
	s_waitcnt lgkmcnt(7)
	v_mfma_f32_16x16x32_bf16 v[46:49], v[82:85], v[70:73], v[46:49]
	v_mfma_f32_16x16x32_bf16 v[26:29], v[86:89], v[70:73], v[26:29]
	v_mfma_f32_16x16x32_bf16 v[14:17], v[208:211], v[70:73], v[14:17]
	v_mfma_f32_16x16x32_bf16 v[10:13], v[212:215], v[70:73], v[10:13]
	ds_read_b128 v[70:73], v119 offset:34816
	s_waitcnt lgkmcnt(7)
	v_mfma_f32_16x16x32_bf16 v[34:37], v[82:85], v[74:77], v[34:37]
	v_mfma_f32_16x16x32_bf16 v[22:25], v[86:89], v[74:77], v[22:25]
	v_mfma_f32_16x16x32_bf16 v[18:21], v[208:211], v[74:77], v[18:21]
	v_mfma_f32_16x16x32_bf16 v[62:65], v[212:215], v[74:77], v[62:65]
	ds_read_b128 v[74:77], v119 offset:36864
	s_waitcnt lgkmcnt(7)
	v_mfma_f32_16x16x32_bf16 v[58:61], v[82:85], v[78:81], v[58:61]
	v_mfma_f32_16x16x32_bf16 v[54:57], v[86:89], v[78:81], v[54:57]
	v_mfma_f32_16x16x32_bf16 v[50:53], v[208:211], v[78:81], v[50:53]
	v_mfma_f32_16x16x32_bf16 v[2:5], v[212:215], v[78:81], v[2:5]
	ds_read_b128 v[78:81], v119 offset:38912
	s_waitcnt lgkmcnt(3)
	v_mfma_f32_16x16x32_bf16 v[6:9], v[216:219], v[66:69], v[6:9]
	v_mfma_f32_16x16x32_bf16 v[30:33], v[220:223], v[66:69], v[30:33]
	v_mfma_f32_16x16x32_bf16 v[38:41], v[224:227], v[66:69], v[38:41]
	v_mfma_f32_16x16x32_bf16 v[42:45], v[228:231], v[66:69], v[42:45]
	s_waitcnt lgkmcnt(2)
	v_mfma_f32_16x16x32_bf16 v[46:49], v[216:219], v[70:73], v[46:49]
	v_mfma_f32_16x16x32_bf16 v[26:29], v[220:223], v[70:73], v[26:29]
	v_mfma_f32_16x16x32_bf16 v[14:17], v[224:227], v[70:73], v[14:17]
	v_mfma_f32_16x16x32_bf16 v[10:13], v[228:231], v[70:73], v[10:13]
	s_waitcnt vmcnt(6)
	s_waitcnt lgkmcnt(0)
	s_barrier
	s_add_i32 m0, s67, 0x8000
	s_nop 0
	global_load_lds_dwordx4 v188, s[80:81]
	s_add_i32 m0, s67, 0xa000
	s_nop 0
	global_load_lds_dwordx4 v189, s[80:81]
	s_add_i32 m0, s67, 0xc000
	s_nop 0
	global_load_lds_dwordx4 v190, s[80:81]
	s_add_i32 m0, s67, 0xe000
	s_nop 0
	global_load_lds_dwordx4 v191, s[80:81]
	s_add_i32 m0, s67, 0x1c000
	s_nop 0
	global_load_lds_dwordx4 v205, s[96:97]
	s_add_i32 m0, s67, 0x1e000
	s_nop 0
	global_load_lds_dwordx4 v206, s[96:97]
	s_add_u32 s80, s80, 0x80
	s_addc_u32 s81, s81, 0
	s_add_u32 s96, s96, 0x80
	s_addc_u32 s97, s97, 0
	ds_read_b128 v[82:85], v90 offset:33792
	ds_read_b128 v[86:89], v90 offset:35840
	ds_read_b128 v[208:211], v90 offset:37888
	ds_read_b128 v[212:215], v90 offset:39936
	ds_read_b128 v[66:69], v0 offset:0
	ds_read_b128 v[70:73], v0 offset:2048
	v_mfma_f32_16x16x32_bf16 v[34:37], v[216:219], v[74:77], v[34:37]
	v_mfma_f32_16x16x32_bf16 v[22:25], v[220:223], v[74:77], v[22:25]
	v_mfma_f32_16x16x32_bf16 v[18:21], v[224:227], v[74:77], v[18:21]
	v_mfma_f32_16x16x32_bf16 v[62:65], v[228:231], v[74:77], v[62:65]
	ds_read_b128 v[74:77], v0 offset:4096
	v_mfma_f32_16x16x32_bf16 v[58:61], v[216:219], v[78:81], v[58:61]
	v_mfma_f32_16x16x32_bf16 v[54:57], v[220:223], v[78:81], v[54:57]
	v_mfma_f32_16x16x32_bf16 v[50:53], v[224:227], v[78:81], v[50:53]
	v_mfma_f32_16x16x32_bf16 v[2:5], v[228:231], v[78:81], v[2:5]
	ds_read_b128 v[78:81], v0 offset:6144
	ds_read_b128 v[216:219], v91 offset:33792
	ds_read_b128 v[220:223], v91 offset:35840
	ds_read_b128 v[224:227], v91 offset:37888
	ds_read_b128 v[228:231], v91 offset:39936
	s_waitcnt lgkmcnt(7)
	v_mfma_f32_16x16x32_bf16 v[6:9], v[82:85], v[66:69], v[6:9]
	v_mfma_f32_16x16x32_bf16 v[30:33], v[86:89], v[66:69], v[30:33]
	v_mfma_f32_16x16x32_bf16 v[38:41], v[208:211], v[66:69], v[38:41]
	v_mfma_f32_16x16x32_bf16 v[42:45], v[212:215], v[66:69], v[42:45]
	ds_read_b128 v[66:69], v255 offset:0
	s_waitcnt lgkmcnt(7)
	v_mfma_f32_16x16x32_bf16 v[46:49], v[82:85], v[70:73], v[46:49]
	v_mfma_f32_16x16x32_bf16 v[26:29], v[86:89], v[70:73], v[26:29]
	v_mfma_f32_16x16x32_bf16 v[14:17], v[208:211], v[70:73], v[14:17]
	v_mfma_f32_16x16x32_bf16 v[10:13], v[212:215], v[70:73], v[10:13]
	ds_read_b128 v[70:73], v255 offset:2048
	s_waitcnt lgkmcnt(7)
	v_mfma_f32_16x16x32_bf16 v[34:37], v[82:85], v[74:77], v[34:37]
	v_mfma_f32_16x16x32_bf16 v[22:25], v[86:89], v[74:77], v[22:25]
	v_mfma_f32_16x16x32_bf16 v[18:21], v[208:211], v[74:77], v[18:21]
	v_mfma_f32_16x16x32_bf16 v[62:65], v[212:215], v[74:77], v[62:65]
	ds_read_b128 v[74:77], v255 offset:4096
	s_waitcnt lgkmcnt(7)
	v_mfma_f32_16x16x32_bf16 v[58:61], v[82:85], v[78:81], v[58:61]
	v_mfma_f32_16x16x32_bf16 v[54:57], v[86:89], v[78:81], v[54:57]
	v_mfma_f32_16x16x32_bf16 v[50:53], v[208:211], v[78:81], v[50:53]
	v_mfma_f32_16x16x32_bf16 v[2:5], v[212:215], v[78:81], v[2:5]
	ds_read_b128 v[78:81], v255 offset:6144
	s_waitcnt lgkmcnt(3)
	v_mfma_f32_16x16x32_bf16 v[6:9], v[216:219], v[66:69], v[6:9]
	v_mfma_f32_16x16x32_bf16 v[30:33], v[220:223], v[66:69], v[30:33]
	v_mfma_f32_16x16x32_bf16 v[38:41], v[224:227], v[66:69], v[38:41]
	v_mfma_f32_16x16x32_bf16 v[42:45], v[228:231], v[66:69], v[42:45]
	s_waitcnt lgkmcnt(2)
	v_mfma_f32_16x16x32_bf16 v[46:49], v[216:219], v[70:73], v[46:49]
	v_mfma_f32_16x16x32_bf16 v[26:29], v[220:223], v[70:73], v[26:29]
	v_mfma_f32_16x16x32_bf16 v[14:17], v[224:227], v[70:73], v[14:17]
	v_mfma_f32_16x16x32_bf16 v[10:13], v[228:231], v[70:73], v[10:13]
	s_waitcnt vmcnt(6)
	s_waitcnt lgkmcnt(0)
	s_barrier
	s_add_i32 m0, s67, 0x10000
	s_nop 0
	global_load_lds_dwordx4 v188, s[80:81]
	s_add_i32 m0, s67, 0x12000
	s_nop 0
	global_load_lds_dwordx4 v189, s[80:81]
	s_add_i32 m0, s67, 0x14000
	s_nop 0
	global_load_lds_dwordx4 v190, s[80:81]
	s_add_i32 m0, s67, 0x16000
	s_nop 0
	global_load_lds_dwordx4 v191, s[80:81]
	s_add_i32 m0, s67, 0x20400
	s_nop 0
	global_load_lds_dwordx4 v205, s[96:97]
	s_add_i32 m0, s67, 0x22400
	s_nop 0
	global_load_lds_dwordx4 v206, s[96:97]
	s_add_u32 s80, s80, 0x80
	s_addc_u32 s81, s81, 0
	s_add_u32 s96, s96, 0x80
	s_addc_u32 s97, s97, 0
	ds_read_b128 v[82:85], v90 offset:0
	ds_read_b128 v[86:89], v90 offset:2048
	ds_read_b128 v[208:211], v90 offset:4096
	ds_read_b128 v[212:215], v90 offset:6144
	ds_read_b128 v[66:69], v207 offset:0
	ds_read_b128 v[70:73], v207 offset:2048
	v_mfma_f32_16x16x32_bf16 v[34:37], v[216:219], v[74:77], v[34:37]
	v_mfma_f32_16x16x32_bf16 v[22:25], v[220:223], v[74:77], v[22:25]
	v_mfma_f32_16x16x32_bf16 v[18:21], v[224:227], v[74:77], v[18:21]
	v_mfma_f32_16x16x32_bf16 v[62:65], v[228:231], v[74:77], v[62:65]
	ds_read_b128 v[74:77], v207 offset:4096
	v_mfma_f32_16x16x32_bf16 v[58:61], v[216:219], v[78:81], v[58:61]
	v_mfma_f32_16x16x32_bf16 v[54:57], v[220:223], v[78:81], v[54:57]
	v_mfma_f32_16x16x32_bf16 v[50:53], v[224:227], v[78:81], v[50:53]
	v_mfma_f32_16x16x32_bf16 v[2:5], v[228:231], v[78:81], v[2:5]
	ds_read_b128 v[78:81], v207 offset:6144
	ds_read_b128 v[216:219], v91 offset:0
	ds_read_b128 v[220:223], v91 offset:2048
	ds_read_b128 v[224:227], v91 offset:4096
	ds_read_b128 v[228:231], v91 offset:6144
	s_waitcnt lgkmcnt(7)
	v_mfma_f32_16x16x32_bf16 v[6:9], v[82:85], v[66:69], v[6:9]
	v_mfma_f32_16x16x32_bf16 v[30:33], v[86:89], v[66:69], v[30:33]
	v_mfma_f32_16x16x32_bf16 v[38:41], v[208:211], v[66:69], v[38:41]
	v_mfma_f32_16x16x32_bf16 v[42:45], v[212:215], v[66:69], v[42:45]
	ds_read_b128 v[66:69], v119 offset:0
	s_waitcnt lgkmcnt(7)
	v_mfma_f32_16x16x32_bf16 v[46:49], v[82:85], v[70:73], v[46:49]
	v_mfma_f32_16x16x32_bf16 v[26:29], v[86:89], v[70:73], v[26:29]
	v_mfma_f32_16x16x32_bf16 v[14:17], v[208:211], v[70:73], v[14:17]
	v_mfma_f32_16x16x32_bf16 v[10:13], v[212:215], v[70:73], v[10:13]
	ds_read_b128 v[70:73], v119 offset:2048
	s_waitcnt lgkmcnt(7)
	v_mfma_f32_16x16x32_bf16 v[34:37], v[82:85], v[74:77], v[34:37]
	v_mfma_f32_16x16x32_bf16 v[22:25], v[86:89], v[74:77], v[22:25]
	v_mfma_f32_16x16x32_bf16 v[18:21], v[208:211], v[74:77], v[18:21]
	v_mfma_f32_16x16x32_bf16 v[62:65], v[212:215], v[74:77], v[62:65]
	ds_read_b128 v[74:77], v119 offset:4096
	s_waitcnt lgkmcnt(7)
	v_mfma_f32_16x16x32_bf16 v[58:61], v[82:85], v[78:81], v[58:61]
	v_mfma_f32_16x16x32_bf16 v[54:57], v[86:89], v[78:81], v[54:57]
	v_mfma_f32_16x16x32_bf16 v[50:53], v[208:211], v[78:81], v[50:53]
	v_mfma_f32_16x16x32_bf16 v[2:5], v[212:215], v[78:81], v[2:5]
	ds_read_b128 v[78:81], v119 offset:6144
	s_waitcnt lgkmcnt(3)
	v_mfma_f32_16x16x32_bf16 v[6:9], v[216:219], v[66:69], v[6:9]
	v_mfma_f32_16x16x32_bf16 v[30:33], v[220:223], v[66:69], v[30:33]
	v_mfma_f32_16x16x32_bf16 v[38:41], v[224:227], v[66:69], v[38:41]
	v_mfma_f32_16x16x32_bf16 v[42:45], v[228:231], v[66:69], v[42:45]
	s_waitcnt lgkmcnt(2)
	v_mfma_f32_16x16x32_bf16 v[46:49], v[216:219], v[70:73], v[46:49]
	v_mfma_f32_16x16x32_bf16 v[26:29], v[220:223], v[70:73], v[26:29]
	v_mfma_f32_16x16x32_bf16 v[14:17], v[224:227], v[70:73], v[14:17]
	v_mfma_f32_16x16x32_bf16 v[10:13], v[228:231], v[70:73], v[10:13]
	s_waitcnt vmcnt(6)
	s_waitcnt lgkmcnt(0)
	s_barrier
	s_add_i32 m0, s67, 0x0
	s_nop 0
	global_load_lds_dwordx4 v188, s[80:81]
	s_add_i32 m0, s67, 0x2000
	s_nop 0
	global_load_lds_dwordx4 v189, s[80:81]
	s_add_i32 m0, s67, 0x4000
	s_nop 0
	global_load_lds_dwordx4 v190, s[80:81]
	s_add_i32 m0, s67, 0x6000
	s_nop 0
	global_load_lds_dwordx4 v191, s[80:81]
	s_add_i32 m0, s67, 0x18000
	s_nop 0
	global_load_lds_dwordx4 v205, s[96:97]
	s_add_i32 m0, s67, 0x1a000
	s_nop 0
	global_load_lds_dwordx4 v206, s[96:97]
	s_add_u32 s80, s80, 0x80
	s_addc_u32 s81, s81, 0
	s_add_u32 s96, s96, 0x80
	s_addc_u32 s97, s97, 0
	s_movk_i32 s10, 0x0
	s_mov_b32 s11, 0
	v_lshl_add_u64 v[248:249], v[128:129], 0, s[10:11]
	global_load_dwordx2 v[232:233], v[248:249], off
	global_load_dwordx2 v[234:235], v[248:249], off offset:32
	v_lshl_add_u64 v[248:249], v[132:133], 0, s[10:11]
	global_load_dwordx2 v[236:237], v[248:249], off
	global_load_dwordx2 v[238:239], v[248:249], off offset:32
	v_lshl_add_u64 v[248:249], v[152:153], 0, s[10:11]
	global_load_dwordx2 v[240:241], v[248:249], off
	global_load_dwordx2 v[242:243], v[248:249], off offset:32
	v_lshl_add_u64 v[248:249], v[154:155], 0, s[10:11]
	global_load_dwordx2 v[244:245], v[248:249], off
	global_load_dwordx2 v[246:247], v[248:249], off offset:32
	ds_read_b128 v[82:85], v90 offset:16384
	ds_read_b128 v[86:89], v90 offset:18432
	ds_read_b128 v[208:211], v90 offset:20480
	ds_read_b128 v[212:215], v90 offset:22528
	ds_read_b128 v[66:69], v207 offset:32768
	ds_read_b128 v[70:73], v207 offset:34816
	v_mfma_f32_16x16x32_bf16 v[34:37], v[216:219], v[74:77], v[34:37]
	v_mfma_f32_16x16x32_bf16 v[22:25], v[220:223], v[74:77], v[22:25]
	v_mfma_f32_16x16x32_bf16 v[18:21], v[224:227], v[74:77], v[18:21]
	v_mfma_f32_16x16x32_bf16 v[62:65], v[228:231], v[74:77], v[62:65]
	ds_read_b128 v[74:77], v207 offset:36864
	v_mfma_f32_16x16x32_bf16 v[58:61], v[216:219], v[78:81], v[58:61]
	v_mfma_f32_16x16x32_bf16 v[54:57], v[220:223], v[78:81], v[54:57]
	v_mfma_f32_16x16x32_bf16 v[50:53], v[224:227], v[78:81], v[50:53]
	v_mfma_f32_16x16x32_bf16 v[2:5], v[228:231], v[78:81], v[2:5]
	ds_read_b128 v[78:81], v207 offset:38912
	ds_read_b128 v[216:219], v91 offset:16384
	ds_read_b128 v[220:223], v91 offset:18432
	ds_read_b128 v[224:227], v91 offset:20480
	ds_read_b128 v[228:231], v91 offset:22528
	s_waitcnt lgkmcnt(7)
	v_mfma_f32_16x16x32_bf16 v[6:9], v[82:85], v[66:69], v[6:9]
	v_mfma_f32_16x16x32_bf16 v[30:33], v[86:89], v[66:69], v[30:33]
	v_mfma_f32_16x16x32_bf16 v[38:41], v[208:211], v[66:69], v[38:41]
	v_mfma_f32_16x16x32_bf16 v[42:45], v[212:215], v[66:69], v[42:45]
	ds_read_b128 v[66:69], v119 offset:32768
	s_waitcnt lgkmcnt(7)
	v_mfma_f32_16x16x32_bf16 v[46:49], v[82:85], v[70:73], v[46:49]
	v_mfma_f32_16x16x32_bf16 v[26:29], v[86:89], v[70:73], v[26:29]
	v_mfma_f32_16x16x32_bf16 v[14:17], v[208:211], v[70:73], v[14:17]
	v_mfma_f32_16x16x32_bf16 v[10:13], v[212:215], v[70:73], v[10:13]
	ds_read_b128 v[70:73], v119 offset:34816
	s_waitcnt lgkmcnt(7)
	v_mfma_f32_16x16x32_bf16 v[34:37], v[82:85], v[74:77], v[34:37]
	v_mfma_f32_16x16x32_bf16 v[22:25], v[86:89], v[74:77], v[22:25]
	v_mfma_f32_16x16x32_bf16 v[18:21], v[208:211], v[74:77], v[18:21]
	v_mfma_f32_16x16x32_bf16 v[62:65], v[212:215], v[74:77], v[62:65]
	ds_read_b128 v[74:77], v119 offset:36864
	s_waitcnt lgkmcnt(7)
	v_mfma_f32_16x16x32_bf16 v[58:61], v[82:85], v[78:81], v[58:61]
	v_mfma_f32_16x16x32_bf16 v[54:57], v[86:89], v[78:81], v[54:57]
	v_mfma_f32_16x16x32_bf16 v[50:53], v[208:211], v[78:81], v[50:53]
	v_mfma_f32_16x16x32_bf16 v[2:5], v[212:215], v[78:81], v[2:5]
	ds_read_b128 v[78:81], v119 offset:38912
	s_waitcnt lgkmcnt(3)
	v_mfma_f32_16x16x32_bf16 v[6:9], v[216:219], v[66:69], v[6:9]
	v_mfma_f32_16x16x32_bf16 v[30:33], v[220:223], v[66:69], v[30:33]
	v_mfma_f32_16x16x32_bf16 v[38:41], v[224:227], v[66:69], v[38:41]
	v_mfma_f32_16x16x32_bf16 v[42:45], v[228:231], v[66:69], v[42:45]
	s_waitcnt lgkmcnt(2)
	v_mfma_f32_16x16x32_bf16 v[46:49], v[216:219], v[70:73], v[46:49]
	v_mfma_f32_16x16x32_bf16 v[26:29], v[220:223], v[70:73], v[26:29]
	v_mfma_f32_16x16x32_bf16 v[14:17], v[224:227], v[70:73], v[14:17]
	v_mfma_f32_16x16x32_bf16 v[10:13], v[228:231], v[70:73], v[10:13]
	s_waitcnt vmcnt(14)
	s_waitcnt lgkmcnt(0)
	s_barrier
	s_add_i32 m0, s67, 0x8000
	s_nop 0
	global_load_lds_dwordx4 v188, s[80:81]
	s_add_i32 m0, s67, 0xa000
	s_nop 0
	global_load_lds_dwordx4 v189, s[80:81]
	s_add_i32 m0, s67, 0xc000
	s_nop 0
	global_load_lds_dwordx4 v190, s[80:81]
	s_add_i32 m0, s67, 0xe000
	s_nop 0
	global_load_lds_dwordx4 v191, s[80:81]
	s_add_i32 m0, s67, 0x1c000
	s_nop 0
	global_load_lds_dwordx4 v205, s[96:97]
	s_add_i32 m0, s67, 0x1e000
	s_nop 0
	global_load_lds_dwordx4 v206, s[96:97]
	s_add_u32 s80, s80, 0x80
	s_addc_u32 s81, s81, 0
	s_add_u32 s96, s96, 0xffc80
	s_addc_u32 s97, s97, 0
	ds_read_b128 v[82:85], v90 offset:33792
	ds_read_b128 v[86:89], v90 offset:35840
	ds_read_b128 v[208:211], v90 offset:37888
	ds_read_b128 v[212:215], v90 offset:39936
	ds_read_b128 v[66:69], v0 offset:0
	ds_read_b128 v[70:73], v0 offset:2048
	v_mfma_f32_16x16x32_bf16 v[34:37], v[216:219], v[74:77], v[34:37]
	v_mfma_f32_16x16x32_bf16 v[22:25], v[220:223], v[74:77], v[22:25]
	v_mfma_f32_16x16x32_bf16 v[18:21], v[224:227], v[74:77], v[18:21]
	v_mfma_f32_16x16x32_bf16 v[62:65], v[228:231], v[74:77], v[62:65]
	ds_read_b128 v[74:77], v0 offset:4096
	v_mfma_f32_16x16x32_bf16 v[58:61], v[216:219], v[78:81], v[58:61]
	v_mfma_f32_16x16x32_bf16 v[54:57], v[220:223], v[78:81], v[54:57]
	v_mfma_f32_16x16x32_bf16 v[50:53], v[224:227], v[78:81], v[50:53]
	v_mfma_f32_16x16x32_bf16 v[2:5], v[228:231], v[78:81], v[2:5]
	ds_read_b128 v[78:81], v0 offset:6144
	ds_read_b128 v[216:219], v91 offset:33792
	ds_read_b128 v[220:223], v91 offset:35840
	ds_read_b128 v[224:227], v91 offset:37888
	ds_read_b128 v[228:231], v91 offset:39936
	s_waitcnt lgkmcnt(7)
	v_mfma_f32_16x16x32_bf16 v[6:9], v[82:85], v[66:69], v[6:9]
	v_mfma_f32_16x16x32_bf16 v[30:33], v[86:89], v[66:69], v[30:33]
	v_mfma_f32_16x16x32_bf16 v[38:41], v[208:211], v[66:69], v[38:41]
	v_mfma_f32_16x16x32_bf16 v[42:45], v[212:215], v[66:69], v[42:45]
	ds_read_b128 v[66:69], v255 offset:0
	s_waitcnt lgkmcnt(7)
	v_mfma_f32_16x16x32_bf16 v[46:49], v[82:85], v[70:73], v[46:49]
	v_mfma_f32_16x16x32_bf16 v[26:29], v[86:89], v[70:73], v[26:29]
	v_mfma_f32_16x16x32_bf16 v[14:17], v[208:211], v[70:73], v[14:17]
	v_mfma_f32_16x16x32_bf16 v[10:13], v[212:215], v[70:73], v[10:13]
	ds_read_b128 v[70:73], v255 offset:2048
	s_waitcnt lgkmcnt(7)
	v_mfma_f32_16x16x32_bf16 v[34:37], v[82:85], v[74:77], v[34:37]
	v_mfma_f32_16x16x32_bf16 v[22:25], v[86:89], v[74:77], v[22:25]
	v_mfma_f32_16x16x32_bf16 v[18:21], v[208:211], v[74:77], v[18:21]
	v_mfma_f32_16x16x32_bf16 v[62:65], v[212:215], v[74:77], v[62:65]
	ds_read_b128 v[74:77], v255 offset:4096
	s_waitcnt lgkmcnt(7)
	v_mfma_f32_16x16x32_bf16 v[58:61], v[82:85], v[78:81], v[58:61]
	v_mfma_f32_16x16x32_bf16 v[54:57], v[86:89], v[78:81], v[54:57]
	v_mfma_f32_16x16x32_bf16 v[50:53], v[208:211], v[78:81], v[50:53]
	v_mfma_f32_16x16x32_bf16 v[2:5], v[212:215], v[78:81], v[2:5]
	ds_read_b128 v[78:81], v255 offset:6144
	s_waitcnt lgkmcnt(3)
	v_mfma_f32_16x16x32_bf16 v[6:9], v[216:219], v[66:69], v[6:9]
	v_mfma_f32_16x16x32_bf16 v[30:33], v[220:223], v[66:69], v[30:33]
	v_mfma_f32_16x16x32_bf16 v[38:41], v[224:227], v[66:69], v[38:41]
	v_mfma_f32_16x16x32_bf16 v[42:45], v[228:231], v[66:69], v[42:45]
	s_waitcnt lgkmcnt(2)
	v_mfma_f32_16x16x32_bf16 v[46:49], v[216:219], v[70:73], v[46:49]
	v_mfma_f32_16x16x32_bf16 v[26:29], v[220:223], v[70:73], v[26:29]
	v_mfma_f32_16x16x32_bf16 v[14:17], v[224:227], v[70:73], v[14:17]
	v_mfma_f32_16x16x32_bf16 v[10:13], v[228:231], v[70:73], v[10:13]
	s_waitcnt vmcnt(14)
	s_waitcnt lgkmcnt(0)
	s_barrier
	s_add_i32 m0, s67, 0x10000
	s_nop 0
	global_load_lds_dwordx4 v188, s[80:81]
	s_add_i32 m0, s67, 0x12000
	s_nop 0
	global_load_lds_dwordx4 v189, s[80:81]
	s_add_i32 m0, s67, 0x14000
	s_nop 0
	global_load_lds_dwordx4 v190, s[80:81]
	s_add_i32 m0, s67, 0x16000
	s_nop 0
	global_load_lds_dwordx4 v191, s[80:81]
	s_add_i32 m0, s67, 0x20400
	s_nop 0
	global_load_lds_dwordx4 v205, s[96:97]
	s_add_i32 m0, s67, 0x22400
	s_nop 0
	global_load_lds_dwordx4 v206, s[96:97]
	s_add_u32 s80, s80, 0x80
	s_addc_u32 s81, s81, 0
	s_add_u32 s96, s96, 0x80
	s_addc_u32 s97, s97, 0
	ds_read_b128 v[82:85], v90 offset:0
	ds_read_b128 v[86:89], v90 offset:2048
	ds_read_b128 v[208:211], v90 offset:4096
	ds_read_b128 v[212:215], v90 offset:6144
	ds_read_b128 v[66:69], v207 offset:0
	ds_read_b128 v[70:73], v207 offset:2048
	v_mfma_f32_16x16x32_bf16 v[34:37], v[216:219], v[74:77], v[34:37]
	v_mfma_f32_16x16x32_bf16 v[22:25], v[220:223], v[74:77], v[22:25]
	v_mfma_f32_16x16x32_bf16 v[18:21], v[224:227], v[74:77], v[18:21]
	v_mfma_f32_16x16x32_bf16 v[62:65], v[228:231], v[74:77], v[62:65]
	ds_read_b128 v[74:77], v207 offset:4096
	v_mfma_f32_16x16x32_bf16 v[58:61], v[216:219], v[78:81], v[58:61]
	v_mfma_f32_16x16x32_bf16 v[54:57], v[220:223], v[78:81], v[54:57]
	v_mfma_f32_16x16x32_bf16 v[50:53], v[224:227], v[78:81], v[50:53]
	v_mfma_f32_16x16x32_bf16 v[2:5], v[228:231], v[78:81], v[2:5]
	ds_read_b128 v[78:81], v207 offset:6144
	ds_read_b128 v[216:219], v91 offset:0
	ds_read_b128 v[220:223], v91 offset:2048
	ds_read_b128 v[224:227], v91 offset:4096
	ds_read_b128 v[228:231], v91 offset:6144
	s_waitcnt lgkmcnt(7)
	v_mfma_f32_16x16x32_bf16 v[6:9], v[82:85], v[66:69], v[6:9]
	v_mfma_f32_16x16x32_bf16 v[30:33], v[86:89], v[66:69], v[30:33]
	v_mfma_f32_16x16x32_bf16 v[38:41], v[208:211], v[66:69], v[38:41]
	v_mfma_f32_16x16x32_bf16 v[42:45], v[212:215], v[66:69], v[42:45]
	ds_read_b128 v[66:69], v119 offset:0
	s_waitcnt lgkmcnt(7)
	v_mfma_f32_16x16x32_bf16 v[46:49], v[82:85], v[70:73], v[46:49]
	v_mfma_f32_16x16x32_bf16 v[26:29], v[86:89], v[70:73], v[26:29]
	v_mfma_f32_16x16x32_bf16 v[14:17], v[208:211], v[70:73], v[14:17]
	v_mfma_f32_16x16x32_bf16 v[10:13], v[212:215], v[70:73], v[10:13]
	ds_read_b128 v[70:73], v119 offset:2048
	s_waitcnt lgkmcnt(7)
	v_mfma_f32_16x16x32_bf16 v[34:37], v[82:85], v[74:77], v[34:37]
	v_mfma_f32_16x16x32_bf16 v[22:25], v[86:89], v[74:77], v[22:25]
	v_mfma_f32_16x16x32_bf16 v[18:21], v[208:211], v[74:77], v[18:21]
	v_mfma_f32_16x16x32_bf16 v[62:65], v[212:215], v[74:77], v[62:65]
	ds_read_b128 v[74:77], v119 offset:4096
	s_waitcnt lgkmcnt(7)
	v_mfma_f32_16x16x32_bf16 v[58:61], v[82:85], v[78:81], v[58:61]
	v_mfma_f32_16x16x32_bf16 v[54:57], v[86:89], v[78:81], v[54:57]
	v_mfma_f32_16x16x32_bf16 v[50:53], v[208:211], v[78:81], v[50:53]
	v_mfma_f32_16x16x32_bf16 v[2:5], v[212:215], v[78:81], v[2:5]
	ds_read_b128 v[78:81], v119 offset:6144
	s_waitcnt lgkmcnt(3)
	v_mfma_f32_16x16x32_bf16 v[6:9], v[216:219], v[66:69], v[6:9]
	v_mfma_f32_16x16x32_bf16 v[30:33], v[220:223], v[66:69], v[30:33]
	v_mfma_f32_16x16x32_bf16 v[38:41], v[224:227], v[66:69], v[38:41]
	v_mfma_f32_16x16x32_bf16 v[42:45], v[228:231], v[66:69], v[42:45]
	s_waitcnt lgkmcnt(2)
	v_mfma_f32_16x16x32_bf16 v[46:49], v[216:219], v[70:73], v[46:49]
	v_mfma_f32_16x16x32_bf16 v[26:29], v[220:223], v[70:73], v[26:29]
	v_mfma_f32_16x16x32_bf16 v[14:17], v[224:227], v[70:73], v[14:17]
	v_mfma_f32_16x16x32_bf16 v[10:13], v[228:231], v[70:73], v[10:13]
	s_waitcnt vmcnt(6)
	s_waitcnt lgkmcnt(0)
	s_barrier
	s_add_i32 m0, s67, 0x0
	s_nop 0
	global_load_lds_dwordx4 v188, s[80:81]
	s_add_i32 m0, s67, 0x2000
	s_nop 0
	global_load_lds_dwordx4 v189, s[80:81]
	s_add_i32 m0, s67, 0x4000
	s_nop 0
	global_load_lds_dwordx4 v190, s[80:81]
	s_add_i32 m0, s67, 0x6000
	s_nop 0
	global_load_lds_dwordx4 v191, s[80:81]
	s_add_i32 m0, s67, 0x18000
	s_nop 0
	global_load_lds_dwordx4 v205, s[96:97]
	s_add_i32 m0, s67, 0x1a000
	s_nop 0
	global_load_lds_dwordx4 v206, s[96:97]
	s_add_u32 s80, s80, 0x80
	s_addc_u32 s81, s81, 0
	s_add_u32 s96, s96, 0x80
	s_addc_u32 s97, s97, 0
	ds_read_b128 v[82:85], v90 offset:16384
	ds_read_b128 v[86:89], v90 offset:18432
	ds_read_b128 v[208:211], v90 offset:20480
	ds_read_b128 v[212:215], v90 offset:22528
	ds_read_b128 v[66:69], v207 offset:32768
	ds_read_b128 v[70:73], v207 offset:34816
	v_mfma_f32_16x16x32_bf16 v[34:37], v[216:219], v[74:77], v[34:37]
	v_mfma_f32_16x16x32_bf16 v[22:25], v[220:223], v[74:77], v[22:25]
	v_mfma_f32_16x16x32_bf16 v[18:21], v[224:227], v[74:77], v[18:21]
	v_mfma_f32_16x16x32_bf16 v[62:65], v[228:231], v[74:77], v[62:65]
	ds_read_b128 v[74:77], v207 offset:36864
	v_mfma_f32_16x16x32_bf16 v[58:61], v[216:219], v[78:81], v[58:61]
	v_mfma_f32_16x16x32_bf16 v[54:57], v[220:223], v[78:81], v[54:57]
	v_mfma_f32_16x16x32_bf16 v[50:53], v[224:227], v[78:81], v[50:53]
	v_mfma_f32_16x16x32_bf16 v[2:5], v[228:231], v[78:81], v[2:5]
	ds_read_b128 v[78:81], v207 offset:38912
	ds_read_b128 v[216:219], v91 offset:16384
	ds_read_b128 v[220:223], v91 offset:18432
	ds_read_b128 v[224:227], v91 offset:20480
	ds_read_b128 v[228:231], v91 offset:22528
	s_waitcnt lgkmcnt(7)
	v_mfma_f32_16x16x32_bf16 v[6:9], v[82:85], v[66:69], v[6:9]
	v_mfma_f32_16x16x32_bf16 v[30:33], v[86:89], v[66:69], v[30:33]
	v_mfma_f32_16x16x32_bf16 v[38:41], v[208:211], v[66:69], v[38:41]
	v_mfma_f32_16x16x32_bf16 v[42:45], v[212:215], v[66:69], v[42:45]
	ds_read_b128 v[66:69], v119 offset:32768
	s_waitcnt lgkmcnt(7)
	v_mfma_f32_16x16x32_bf16 v[46:49], v[82:85], v[70:73], v[46:49]
	v_mfma_f32_16x16x32_bf16 v[26:29], v[86:89], v[70:73], v[26:29]
	v_mfma_f32_16x16x32_bf16 v[14:17], v[208:211], v[70:73], v[14:17]
	v_mfma_f32_16x16x32_bf16 v[10:13], v[212:215], v[70:73], v[10:13]
	ds_read_b128 v[70:73], v119 offset:34816
	s_waitcnt lgkmcnt(7)
	v_mfma_f32_16x16x32_bf16 v[34:37], v[82:85], v[74:77], v[34:37]
	v_mfma_f32_16x16x32_bf16 v[22:25], v[86:89], v[74:77], v[22:25]
	v_mfma_f32_16x16x32_bf16 v[18:21], v[208:211], v[74:77], v[18:21]
	v_mfma_f32_16x16x32_bf16 v[62:65], v[212:215], v[74:77], v[62:65]
	ds_read_b128 v[74:77], v119 offset:36864
	s_waitcnt lgkmcnt(7)
	v_mfma_f32_16x16x32_bf16 v[58:61], v[82:85], v[78:81], v[58:61]
	v_mfma_f32_16x16x32_bf16 v[54:57], v[86:89], v[78:81], v[54:57]
	v_mfma_f32_16x16x32_bf16 v[50:53], v[208:211], v[78:81], v[50:53]
	v_mfma_f32_16x16x32_bf16 v[2:5], v[212:215], v[78:81], v[2:5]
	ds_read_b128 v[78:81], v119 offset:38912
	s_waitcnt lgkmcnt(3)
	v_mfma_f32_16x16x32_bf16 v[6:9], v[216:219], v[66:69], v[6:9]
	s_waitcnt vmcnt(18)
	v_mfma_f32_16x16x32_bf16 v[30:33], v[220:223], v[66:69], v[30:33]
	v_mfma_f32_16x16x32_bf16 v[38:41], v[224:227], v[66:69], v[38:41]
	v_mfma_f32_16x16x32_bf16 v[42:45], v[228:231], v[66:69], v[42:45]
	v_cvt_f32_ubyte0_e32 v248, v232
	v_cvt_f32_ubyte1_e32 v249, v232
	v_cvt_f32_ubyte2_e32 v250, v232
	v_cvt_f32_ubyte3_e32 v251, v232
	v_mul_f32_e32 v248, s34, v248
	v_mul_f32_e32 v249, s34, v249
	v_mul_f32_e32 v250, s34, v250
	v_mul_f32_e32 v251, s34, v251
	v_fma_f32 v184, v6, v248, v184
	v_fma_f32 v185, v7, v249, v185
	v_fma_f32 v186, v8, v250, v186
	v_fma_f32 v187, v9, v251, v187
	s_waitcnt lgkmcnt(2)
	v_mfma_f32_16x16x32_bf16 v[46:49], v[216:219], v[70:73], v[46:49]
	v_cvt_f32_ubyte0_e32 v248, v233
	v_cvt_f32_ubyte1_e32 v249, v233
	v_cvt_f32_ubyte2_e32 v250, v233
	v_cvt_f32_ubyte3_e32 v251, v233
	v_mul_f32_e32 v248, s34, v248
	v_mul_f32_e32 v249, s34, v249
	v_mul_f32_e32 v250, s34, v250
	v_mul_f32_e32 v251, s34, v251
	v_fma_f32 v180, v30, v248, v180
	v_fma_f32 v181, v31, v249, v181
	v_fma_f32 v182, v32, v250, v182
	v_fma_f32 v183, v33, v251, v183
	v_mfma_f32_16x16x32_bf16 v[26:29], v[220:223], v[70:73], v[26:29]
	v_cvt_f32_ubyte0_e32 v248, v234
	v_cvt_f32_ubyte1_e32 v249, v234
	v_cvt_f32_ubyte2_e32 v250, v234
	v_cvt_f32_ubyte3_e32 v251, v234
	v_mul_f32_e32 v248, s34, v248
	v_mul_f32_e32 v249, s34, v249
	v_mul_f32_e32 v250, s34, v250
	v_mul_f32_e32 v251, s34, v251
	v_fma_f32 v176, v38, v248, v176
	v_fma_f32 v177, v39, v249, v177
	v_fma_f32 v178, v40, v250, v178
	v_fma_f32 v179, v41, v251, v179
	v_mfma_f32_16x16x32_bf16 v[14:17], v[224:227], v[70:73], v[14:17]
	v_cvt_f32_ubyte0_e32 v248, v235
	v_cvt_f32_ubyte1_e32 v249, v235
	v_cvt_f32_ubyte2_e32 v250, v235
	v_cvt_f32_ubyte3_e32 v251, v235
	v_mul_f32_e32 v248, s34, v248
	v_mul_f32_e32 v249, s34, v249
	v_mul_f32_e32 v250, s34, v250
	v_mul_f32_e32 v251, s34, v251
	v_fma_f32 v172, v42, v248, v172
	v_fma_f32 v173, v43, v249, v173
	v_fma_f32 v174, v44, v250, v174
	v_fma_f32 v175, v45, v251, v175
	v_mfma_f32_16x16x32_bf16 v[10:13], v[228:231], v[70:73], v[10:13]
	v_cvt_f32_ubyte0_e32 v248, v236
	v_cvt_f32_ubyte1_e32 v249, v236
	v_cvt_f32_ubyte2_e32 v250, v236
	v_cvt_f32_ubyte3_e32 v251, v236
	v_mul_f32_e32 v248, s34, v248
	v_mul_f32_e32 v249, s34, v249
	v_mul_f32_e32 v250, s34, v250
	v_mul_f32_e32 v251, s34, v251
	v_fma_f32 v168, v46, v248, v168
	v_fma_f32 v169, v47, v249, v169
	v_fma_f32 v170, v48, v250, v170
	v_fma_f32 v171, v49, v251, v171
	s_waitcnt vmcnt(6)
	s_waitcnt lgkmcnt(0)
	s_barrier
	s_add_i32 m0, s67, 0x8000
	s_nop 0
	global_load_lds_dwordx4 v188, s[80:81]
	s_add_i32 m0, s67, 0xa000
	s_nop 0
	global_load_lds_dwordx4 v189, s[80:81]
	s_add_i32 m0, s67, 0xc000
	s_nop 0
	global_load_lds_dwordx4 v190, s[80:81]
	s_add_i32 m0, s67, 0xe000
	s_nop 0
	global_load_lds_dwordx4 v191, s[80:81]
	s_add_i32 m0, s67, 0x1c000
	s_nop 0
	global_load_lds_dwordx4 v205, s[96:97]
	s_add_i32 m0, s67, 0x1e000
	s_nop 0
	global_load_lds_dwordx4 v206, s[96:97]
	s_add_u32 s80, s80, 0x80
	s_addc_u32 s81, s81, 0
	s_add_u32 s96, s96, 0x80
	s_addc_u32 s97, s97, 0
	ds_read_b128 v[82:85], v90 offset:33792
	ds_read_b128 v[86:89], v90 offset:35840
	ds_read_b128 v[208:211], v90 offset:37888
	ds_read_b128 v[212:215], v90 offset:39936
	ds_read_b128 v[66:69], v0 offset:0
	ds_read_b128 v[70:73], v0 offset:2048
	v_mfma_f32_16x16x32_bf16 v[34:37], v[216:219], v[74:77], v[34:37]
	v_cvt_f32_ubyte0_e32 v248, v237
	v_cvt_f32_ubyte1_e32 v249, v237
	v_cvt_f32_ubyte2_e32 v250, v237
	v_cvt_f32_ubyte3_e32 v251, v237
	v_mul_f32_e32 v248, s34, v248
	v_mul_f32_e32 v249, s34, v249
	v_mul_f32_e32 v250, s34, v250
	v_mul_f32_e32 v251, s34, v251
	v_fma_f32 v164, v26, v248, v164
	v_fma_f32 v165, v27, v249, v165
	v_fma_f32 v166, v28, v250, v166
	v_fma_f32 v167, v29, v251, v167
	v_mfma_f32_16x16x32_bf16 v[22:25], v[220:223], v[74:77], v[22:25]
	v_cvt_f32_ubyte0_e32 v248, v238
	v_cvt_f32_ubyte1_e32 v249, v238
	v_cvt_f32_ubyte2_e32 v250, v238
	v_cvt_f32_ubyte3_e32 v251, v238
	v_mul_f32_e32 v248, s34, v248
	v_mul_f32_e32 v249, s34, v249
	v_mul_f32_e32 v250, s34, v250
	v_mul_f32_e32 v251, s34, v251
	v_fma_f32 v160, v14, v248, v160
	v_fma_f32 v161, v15, v249, v161
	v_fma_f32 v162, v16, v250, v162
	v_fma_f32 v163, v17, v251, v163
	v_mfma_f32_16x16x32_bf16 v[18:21], v[224:227], v[74:77], v[18:21]
	v_cvt_f32_ubyte0_e32 v248, v239
	v_cvt_f32_ubyte1_e32 v249, v239
	v_cvt_f32_ubyte2_e32 v250, v239
	v_cvt_f32_ubyte3_e32 v251, v239
	v_mul_f32_e32 v248, s34, v248
	v_mul_f32_e32 v249, s34, v249
	v_mul_f32_e32 v250, s34, v250
	v_mul_f32_e32 v251, s34, v251
	v_fma_f32 v156, v10, v248, v156
	v_fma_f32 v157, v11, v249, v157
	v_fma_f32 v158, v12, v250, v158
	v_fma_f32 v159, v13, v251, v159
	v_mfma_f32_16x16x32_bf16 v[62:65], v[228:231], v[74:77], v[62:65]
	v_cvt_f32_ubyte0_e32 v248, v240
	v_cvt_f32_ubyte1_e32 v249, v240
	v_cvt_f32_ubyte2_e32 v250, v240
	v_cvt_f32_ubyte3_e32 v251, v240
	v_mul_f32_e32 v248, s34, v248
	v_mul_f32_e32 v249, s34, v249
	v_mul_f32_e32 v250, s34, v250
	v_mul_f32_e32 v251, s34, v251
	v_fma_f32 v136, v34, v248, v136
	v_fma_f32 v137, v35, v249, v137
	v_fma_f32 v150, v36, v250, v150
	v_fma_f32 v151, v37, v251, v151
	ds_read_b128 v[74:77], v0 offset:4096
	v_mfma_f32_16x16x32_bf16 v[58:61], v[216:219], v[78:81], v[58:61]
	v_cvt_f32_ubyte0_e32 v248, v241
	v_cvt_f32_ubyte1_e32 v249, v241
	v_cvt_f32_ubyte2_e32 v250, v241
	v_cvt_f32_ubyte3_e32 v251, v241
	v_mul_f32_e32 v248, s34, v248
	v_mul_f32_e32 v249, s34, v249
	v_mul_f32_e32 v250, s34, v250
	v_mul_f32_e32 v251, s34, v251
	v_fma_f32 v130, v22, v248, v130
	v_fma_f32 v131, v23, v249, v131
	v_fma_f32 v134, v24, v250, v134
	v_fma_f32 v135, v25, v251, v135
	v_mfma_f32_16x16x32_bf16 v[54:57], v[220:223], v[78:81], v[54:57]
	v_cvt_f32_ubyte0_e32 v248, v242
	v_cvt_f32_ubyte1_e32 v249, v242
	v_cvt_f32_ubyte2_e32 v250, v242
	v_cvt_f32_ubyte3_e32 v251, v242
	v_mul_f32_e32 v248, s34, v248
	v_mul_f32_e32 v249, s34, v249
	v_mul_f32_e32 v250, s34, v250
	v_mul_f32_e32 v251, s34, v251
	v_fma_f32 v124, v18, v248, v124
	v_fma_f32 v125, v19, v249, v125
	v_fma_f32 v126, v20, v250, v126
	v_fma_f32 v127, v21, v251, v127
	v_mfma_f32_16x16x32_bf16 v[50:53], v[224:227], v[78:81], v[50:53]
	v_cvt_f32_ubyte0_e32 v248, v243
	v_cvt_f32_ubyte1_e32 v249, v243
	v_cvt_f32_ubyte2_e32 v250, v243
	v_cvt_f32_ubyte3_e32 v251, v243
	v_mul_f32_e32 v248, s34, v248
	v_mul_f32_e32 v249, s34, v249
	v_mul_f32_e32 v250, s34, v250
	v_mul_f32_e32 v251, s34, v251
	v_fma_f32 v120, v62, v248, v120
	v_fma_f32 v121, v63, v249, v121
	v_fma_f32 v122, v64, v250, v122
	v_fma_f32 v123, v65, v251, v123
	v_mfma_f32_16x16x32_bf16 v[2:5], v[228:231], v[78:81], v[2:5]
	v_cvt_f32_ubyte0_e32 v248, v244
	v_cvt_f32_ubyte1_e32 v249, v244
	v_cvt_f32_ubyte2_e32 v250, v244
	v_cvt_f32_ubyte3_e32 v251, v244
	v_mul_f32_e32 v248, s34, v248
	v_mul_f32_e32 v249, s34, v249
	v_mul_f32_e32 v250, s34, v250
	v_mul_f32_e32 v251, s34, v251
	v_fma_f32 v114, v58, v248, v114
	v_fma_f32 v115, v59, v249, v115
	v_fma_f32 v116, v60, v250, v116
	v_fma_f32 v117, v61, v251, v117
	ds_read_b128 v[78:81], v0 offset:6144
	s_nop 7
	s_nop 3
	v_cvt_f32_ubyte0_e32 v248, v245
	v_cvt_f32_ubyte1_e32 v249, v245
	v_cvt_f32_ubyte2_e32 v250, v245
	v_cvt_f32_ubyte3_e32 v251, v245
	v_mul_f32_e32 v248, s34, v248
	v_mul_f32_e32 v249, s34, v249
	v_mul_f32_e32 v250, s34, v250
	v_mul_f32_e32 v251, s34, v251
	v_fma_f32 v106, v54, v248, v106
	v_fma_f32 v107, v55, v249, v107
	v_fma_f32 v108, v56, v250, v108
	v_fma_f32 v109, v57, v251, v109
	v_cvt_f32_ubyte0_e32 v248, v246
	v_cvt_f32_ubyte1_e32 v249, v246
	v_cvt_f32_ubyte2_e32 v250, v246
	v_cvt_f32_ubyte3_e32 v251, v246
	v_mul_f32_e32 v248, s34, v248
	v_mul_f32_e32 v249, s34, v249
	v_mul_f32_e32 v250, s34, v250
	v_mul_f32_e32 v251, s34, v251
	v_fma_f32 v100, v50, v248, v100
	v_fma_f32 v101, v51, v249, v101
	v_fma_f32 v102, v52, v250, v102
	v_fma_f32 v103, v53, v251, v103
	v_cvt_f32_ubyte0_e32 v248, v247
	v_cvt_f32_ubyte1_e32 v249, v247
	v_cvt_f32_ubyte2_e32 v250, v247
	v_cvt_f32_ubyte3_e32 v251, v247
	v_mul_f32_e32 v248, s34, v248
	v_mul_f32_e32 v249, s34, v249
	v_mul_f32_e32 v250, s34, v250
	v_mul_f32_e32 v251, s34, v251
	v_fma_f32 v96, v2, v248, v96
	v_fma_f32 v97, v3, v249, v97
	v_fma_f32 v98, v4, v250, v98
	v_fma_f32 v99, v5, v251, v99
	ds_read_b128 v[216:219], v91 offset:33792
	ds_read_b128 v[220:223], v91 offset:35840
	ds_read_b128 v[224:227], v91 offset:37888
	ds_read_b128 v[228:231], v91 offset:39936
	s_waitcnt lgkmcnt(7)
	v_mfma_f32_16x16x32_bf16 v[6:9], v[82:85], v[66:69], 0
	v_mfma_f32_16x16x32_bf16 v[30:33], v[86:89], v[66:69], 0
	v_mfma_f32_16x16x32_bf16 v[38:41], v[208:211], v[66:69], 0
	v_mfma_f32_16x16x32_bf16 v[42:45], v[212:215], v[66:69], 0
	ds_read_b128 v[66:69], v255 offset:0
	s_waitcnt lgkmcnt(7)
	v_mfma_f32_16x16x32_bf16 v[46:49], v[82:85], v[70:73], 0
	v_mfma_f32_16x16x32_bf16 v[26:29], v[86:89], v[70:73], 0
	v_mfma_f32_16x16x32_bf16 v[14:17], v[208:211], v[70:73], 0
	v_mfma_f32_16x16x32_bf16 v[10:13], v[212:215], v[70:73], 0
	ds_read_b128 v[70:73], v255 offset:2048
	s_waitcnt lgkmcnt(7)
	v_mfma_f32_16x16x32_bf16 v[34:37], v[82:85], v[74:77], 0
	v_mfma_f32_16x16x32_bf16 v[22:25], v[86:89], v[74:77], 0
	v_mfma_f32_16x16x32_bf16 v[18:21], v[208:211], v[74:77], 0
	v_mfma_f32_16x16x32_bf16 v[62:65], v[212:215], v[74:77], 0
	ds_read_b128 v[74:77], v255 offset:4096
	s_waitcnt lgkmcnt(7)
	v_mfma_f32_16x16x32_bf16 v[58:61], v[82:85], v[78:81], 0
	v_mfma_f32_16x16x32_bf16 v[54:57], v[86:89], v[78:81], 0
	v_mfma_f32_16x16x32_bf16 v[50:53], v[208:211], v[78:81], 0
	v_mfma_f32_16x16x32_bf16 v[2:5], v[212:215], v[78:81], 0
	ds_read_b128 v[78:81], v255 offset:6144
	s_waitcnt lgkmcnt(3)
	v_mfma_f32_16x16x32_bf16 v[6:9], v[216:219], v[66:69], v[6:9]
	v_mfma_f32_16x16x32_bf16 v[30:33], v[220:223], v[66:69], v[30:33]
	v_mfma_f32_16x16x32_bf16 v[38:41], v[224:227], v[66:69], v[38:41]
	v_mfma_f32_16x16x32_bf16 v[42:45], v[228:231], v[66:69], v[42:45]
	s_waitcnt lgkmcnt(2)
	v_mfma_f32_16x16x32_bf16 v[46:49], v[216:219], v[70:73], v[46:49]
	v_mfma_f32_16x16x32_bf16 v[26:29], v[220:223], v[70:73], v[26:29]
	v_mfma_f32_16x16x32_bf16 v[14:17], v[224:227], v[70:73], v[14:17]
	v_mfma_f32_16x16x32_bf16 v[10:13], v[228:231], v[70:73], v[10:13]
	s_waitcnt vmcnt(6)
	s_waitcnt lgkmcnt(0)
	s_barrier
	s_add_i32 m0, s67, 0x10000
	s_nop 0
	global_load_lds_dwordx4 v188, s[80:81]
	s_add_i32 m0, s67, 0x12000
	s_nop 0
	global_load_lds_dwordx4 v189, s[80:81]
	s_add_i32 m0, s67, 0x14000
	s_nop 0
	global_load_lds_dwordx4 v190, s[80:81]
	s_add_i32 m0, s67, 0x16000
	s_nop 0
	global_load_lds_dwordx4 v191, s[80:81]
	s_add_i32 m0, s67, 0x20400
	s_nop 0
	global_load_lds_dwordx4 v205, s[96:97]
	s_add_i32 m0, s67, 0x22400
	s_nop 0
	global_load_lds_dwordx4 v206, s[96:97]
	s_add_u32 s80, s80, 0x80
	s_addc_u32 s81, s81, 0
	s_add_u32 s96, s96, 0x80
	s_addc_u32 s97, s97, 0
	ds_read_b128 v[82:85], v90 offset:0
	ds_read_b128 v[86:89], v90 offset:2048
	ds_read_b128 v[208:211], v90 offset:4096
	ds_read_b128 v[212:215], v90 offset:6144
	ds_read_b128 v[66:69], v207 offset:0
	ds_read_b128 v[70:73], v207 offset:2048
	v_mfma_f32_16x16x32_bf16 v[34:37], v[216:219], v[74:77], v[34:37]
	v_mfma_f32_16x16x32_bf16 v[22:25], v[220:223], v[74:77], v[22:25]
	v_mfma_f32_16x16x32_bf16 v[18:21], v[224:227], v[74:77], v[18:21]
	v_mfma_f32_16x16x32_bf16 v[62:65], v[228:231], v[74:77], v[62:65]
	ds_read_b128 v[74:77], v207 offset:4096
	v_mfma_f32_16x16x32_bf16 v[58:61], v[216:219], v[78:81], v[58:61]
	v_mfma_f32_16x16x32_bf16 v[54:57], v[220:223], v[78:81], v[54:57]
	v_mfma_f32_16x16x32_bf16 v[50:53], v[224:227], v[78:81], v[50:53]
	v_mfma_f32_16x16x32_bf16 v[2:5], v[228:231], v[78:81], v[2:5]
	ds_read_b128 v[78:81], v207 offset:6144
	ds_read_b128 v[216:219], v91 offset:0
	ds_read_b128 v[220:223], v91 offset:2048
	ds_read_b128 v[224:227], v91 offset:4096
	ds_read_b128 v[228:231], v91 offset:6144
	s_waitcnt lgkmcnt(7)
	v_mfma_f32_16x16x32_bf16 v[6:9], v[82:85], v[66:69], v[6:9]
	v_mfma_f32_16x16x32_bf16 v[30:33], v[86:89], v[66:69], v[30:33]
	v_mfma_f32_16x16x32_bf16 v[38:41], v[208:211], v[66:69], v[38:41]
	v_mfma_f32_16x16x32_bf16 v[42:45], v[212:215], v[66:69], v[42:45]
	ds_read_b128 v[66:69], v119 offset:0
	s_waitcnt lgkmcnt(7)
	v_mfma_f32_16x16x32_bf16 v[46:49], v[82:85], v[70:73], v[46:49]
	v_mfma_f32_16x16x32_bf16 v[26:29], v[86:89], v[70:73], v[26:29]
	v_mfma_f32_16x16x32_bf16 v[14:17], v[208:211], v[70:73], v[14:17]
	v_mfma_f32_16x16x32_bf16 v[10:13], v[212:215], v[70:73], v[10:13]
	ds_read_b128 v[70:73], v119 offset:2048
	s_waitcnt lgkmcnt(7)
	v_mfma_f32_16x16x32_bf16 v[34:37], v[82:85], v[74:77], v[34:37]
	v_mfma_f32_16x16x32_bf16 v[22:25], v[86:89], v[74:77], v[22:25]
	v_mfma_f32_16x16x32_bf16 v[18:21], v[208:211], v[74:77], v[18:21]
	v_mfma_f32_16x16x32_bf16 v[62:65], v[212:215], v[74:77], v[62:65]
	ds_read_b128 v[74:77], v119 offset:4096
	s_waitcnt lgkmcnt(7)
	v_mfma_f32_16x16x32_bf16 v[58:61], v[82:85], v[78:81], v[58:61]
	v_mfma_f32_16x16x32_bf16 v[54:57], v[86:89], v[78:81], v[54:57]
	v_mfma_f32_16x16x32_bf16 v[50:53], v[208:211], v[78:81], v[50:53]
	v_mfma_f32_16x16x32_bf16 v[2:5], v[212:215], v[78:81], v[2:5]
	ds_read_b128 v[78:81], v119 offset:6144
	s_waitcnt lgkmcnt(3)
	v_mfma_f32_16x16x32_bf16 v[6:9], v[216:219], v[66:69], v[6:9]
	v_mfma_f32_16x16x32_bf16 v[30:33], v[220:223], v[66:69], v[30:33]
	v_mfma_f32_16x16x32_bf16 v[38:41], v[224:227], v[66:69], v[38:41]
	v_mfma_f32_16x16x32_bf16 v[42:45], v[228:231], v[66:69], v[42:45]
	s_waitcnt lgkmcnt(2)
	v_mfma_f32_16x16x32_bf16 v[46:49], v[216:219], v[70:73], v[46:49]
	v_mfma_f32_16x16x32_bf16 v[26:29], v[220:223], v[70:73], v[26:29]
	v_mfma_f32_16x16x32_bf16 v[14:17], v[224:227], v[70:73], v[14:17]
	v_mfma_f32_16x16x32_bf16 v[10:13], v[228:231], v[70:73], v[10:13]
	s_waitcnt vmcnt(6)
	s_waitcnt lgkmcnt(0)
	s_barrier
	s_add_i32 m0, s67, 0x0
	s_nop 0
	global_load_lds_dwordx4 v188, s[80:81]
	s_add_i32 m0, s67, 0x2000
	s_nop 0
	global_load_lds_dwordx4 v189, s[80:81]
	s_add_i32 m0, s67, 0x4000
	s_nop 0
	global_load_lds_dwordx4 v190, s[80:81]
	s_add_i32 m0, s67, 0x6000
	s_nop 0
	global_load_lds_dwordx4 v191, s[80:81]
	s_add_i32 m0, s67, 0x18000
	s_nop 0
	global_load_lds_dwordx4 v205, s[96:97]
	s_add_i32 m0, s67, 0x1a000
	s_nop 0
	global_load_lds_dwordx4 v206, s[96:97]
	s_add_u32 s80, s80, 0x80
	s_addc_u32 s81, s81, 0
	s_add_u32 s96, s96, 0x80
	s_addc_u32 s97, s97, 0
	ds_read_b128 v[82:85], v90 offset:16384
	ds_read_b128 v[86:89], v90 offset:18432
	ds_read_b128 v[208:211], v90 offset:20480
	ds_read_b128 v[212:215], v90 offset:22528
	ds_read_b128 v[66:69], v207 offset:32768
	ds_read_b128 v[70:73], v207 offset:34816
	v_mfma_f32_16x16x32_bf16 v[34:37], v[216:219], v[74:77], v[34:37]
	v_mfma_f32_16x16x32_bf16 v[22:25], v[220:223], v[74:77], v[22:25]
	v_mfma_f32_16x16x32_bf16 v[18:21], v[224:227], v[74:77], v[18:21]
	v_mfma_f32_16x16x32_bf16 v[62:65], v[228:231], v[74:77], v[62:65]
	ds_read_b128 v[74:77], v207 offset:36864
	v_mfma_f32_16x16x32_bf16 v[58:61], v[216:219], v[78:81], v[58:61]
	v_mfma_f32_16x16x32_bf16 v[54:57], v[220:223], v[78:81], v[54:57]
	v_mfma_f32_16x16x32_bf16 v[50:53], v[224:227], v[78:81], v[50:53]
	v_mfma_f32_16x16x32_bf16 v[2:5], v[228:231], v[78:81], v[2:5]
	ds_read_b128 v[78:81], v207 offset:38912
	ds_read_b128 v[216:219], v91 offset:16384
	ds_read_b128 v[220:223], v91 offset:18432
	ds_read_b128 v[224:227], v91 offset:20480
	ds_read_b128 v[228:231], v91 offset:22528
	s_waitcnt lgkmcnt(7)
	v_mfma_f32_16x16x32_bf16 v[6:9], v[82:85], v[66:69], v[6:9]
	v_mfma_f32_16x16x32_bf16 v[30:33], v[86:89], v[66:69], v[30:33]
	v_mfma_f32_16x16x32_bf16 v[38:41], v[208:211], v[66:69], v[38:41]
	v_mfma_f32_16x16x32_bf16 v[42:45], v[212:215], v[66:69], v[42:45]
	ds_read_b128 v[66:69], v119 offset:32768
	s_waitcnt lgkmcnt(7)
	v_mfma_f32_16x16x32_bf16 v[46:49], v[82:85], v[70:73], v[46:49]
	v_mfma_f32_16x16x32_bf16 v[26:29], v[86:89], v[70:73], v[26:29]
	v_mfma_f32_16x16x32_bf16 v[14:17], v[208:211], v[70:73], v[14:17]
	v_mfma_f32_16x16x32_bf16 v[10:13], v[212:215], v[70:73], v[10:13]
	ds_read_b128 v[70:73], v119 offset:34816
	s_waitcnt lgkmcnt(7)
	v_mfma_f32_16x16x32_bf16 v[34:37], v[82:85], v[74:77], v[34:37]
	v_mfma_f32_16x16x32_bf16 v[22:25], v[86:89], v[74:77], v[22:25]
	v_mfma_f32_16x16x32_bf16 v[18:21], v[208:211], v[74:77], v[18:21]
	v_mfma_f32_16x16x32_bf16 v[62:65], v[212:215], v[74:77], v[62:65]
	ds_read_b128 v[74:77], v119 offset:36864
	s_waitcnt lgkmcnt(7)
	v_mfma_f32_16x16x32_bf16 v[58:61], v[82:85], v[78:81], v[58:61]
	v_mfma_f32_16x16x32_bf16 v[54:57], v[86:89], v[78:81], v[54:57]
	v_mfma_f32_16x16x32_bf16 v[50:53], v[208:211], v[78:81], v[50:53]
	v_mfma_f32_16x16x32_bf16 v[2:5], v[212:215], v[78:81], v[2:5]
	ds_read_b128 v[78:81], v119 offset:38912
	s_waitcnt lgkmcnt(3)
	v_mfma_f32_16x16x32_bf16 v[6:9], v[216:219], v[66:69], v[6:9]
	v_mfma_f32_16x16x32_bf16 v[30:33], v[220:223], v[66:69], v[30:33]
	v_mfma_f32_16x16x32_bf16 v[38:41], v[224:227], v[66:69], v[38:41]
	v_mfma_f32_16x16x32_bf16 v[42:45], v[228:231], v[66:69], v[42:45]
	s_waitcnt lgkmcnt(2)
	v_mfma_f32_16x16x32_bf16 v[46:49], v[216:219], v[70:73], v[46:49]
	v_mfma_f32_16x16x32_bf16 v[26:29], v[220:223], v[70:73], v[26:29]
	v_mfma_f32_16x16x32_bf16 v[14:17], v[224:227], v[70:73], v[14:17]
	v_mfma_f32_16x16x32_bf16 v[10:13], v[228:231], v[70:73], v[10:13]
	s_waitcnt vmcnt(6)
	s_waitcnt lgkmcnt(0)
	s_barrier
	s_add_i32 m0, s67, 0x8000
	s_nop 0
	global_load_lds_dwordx4 v188, s[80:81]
	s_add_i32 m0, s67, 0xa000
	s_nop 0
	global_load_lds_dwordx4 v189, s[80:81]
	s_add_i32 m0, s67, 0xc000
	s_nop 0
	global_load_lds_dwordx4 v190, s[80:81]
	s_add_i32 m0, s67, 0xe000
	s_nop 0
	global_load_lds_dwordx4 v191, s[80:81]
	s_add_i32 m0, s67, 0x1c000
	s_nop 0
	global_load_lds_dwordx4 v205, s[96:97]
	s_add_i32 m0, s67, 0x1e000
	s_nop 0
	global_load_lds_dwordx4 v206, s[96:97]
	s_add_u32 s80, s80, 0x80
	s_addc_u32 s81, s81, 0
	s_add_u32 s96, s96, 0x80
	s_addc_u32 s97, s97, 0
	ds_read_b128 v[82:85], v90 offset:33792
	ds_read_b128 v[86:89], v90 offset:35840
	ds_read_b128 v[208:211], v90 offset:37888
	ds_read_b128 v[212:215], v90 offset:39936
	ds_read_b128 v[66:69], v0 offset:0
	ds_read_b128 v[70:73], v0 offset:2048
	v_mfma_f32_16x16x32_bf16 v[34:37], v[216:219], v[74:77], v[34:37]
	v_mfma_f32_16x16x32_bf16 v[22:25], v[220:223], v[74:77], v[22:25]
	v_mfma_f32_16x16x32_bf16 v[18:21], v[224:227], v[74:77], v[18:21]
	v_mfma_f32_16x16x32_bf16 v[62:65], v[228:231], v[74:77], v[62:65]
	ds_read_b128 v[74:77], v0 offset:4096
	v_mfma_f32_16x16x32_bf16 v[58:61], v[216:219], v[78:81], v[58:61]
	v_mfma_f32_16x16x32_bf16 v[54:57], v[220:223], v[78:81], v[54:57]
	v_mfma_f32_16x16x32_bf16 v[50:53], v[224:227], v[78:81], v[50:53]
	v_mfma_f32_16x16x32_bf16 v[2:5], v[228:231], v[78:81], v[2:5]
	ds_read_b128 v[78:81], v0 offset:6144
	ds_read_b128 v[216:219], v91 offset:33792
	ds_read_b128 v[220:223], v91 offset:35840
	ds_read_b128 v[224:227], v91 offset:37888
	ds_read_b128 v[228:231], v91 offset:39936
	s_waitcnt lgkmcnt(7)
	v_mfma_f32_16x16x32_bf16 v[6:9], v[82:85], v[66:69], v[6:9]
	v_mfma_f32_16x16x32_bf16 v[30:33], v[86:89], v[66:69], v[30:33]
	v_mfma_f32_16x16x32_bf16 v[38:41], v[208:211], v[66:69], v[38:41]
	v_mfma_f32_16x16x32_bf16 v[42:45], v[212:215], v[66:69], v[42:45]
	ds_read_b128 v[66:69], v255 offset:0
	s_waitcnt lgkmcnt(7)
	v_mfma_f32_16x16x32_bf16 v[46:49], v[82:85], v[70:73], v[46:49]
	v_mfma_f32_16x16x32_bf16 v[26:29], v[86:89], v[70:73], v[26:29]
	v_mfma_f32_16x16x32_bf16 v[14:17], v[208:211], v[70:73], v[14:17]
	v_mfma_f32_16x16x32_bf16 v[10:13], v[212:215], v[70:73], v[10:13]
	ds_read_b128 v[70:73], v255 offset:2048
	s_waitcnt lgkmcnt(7)
	v_mfma_f32_16x16x32_bf16 v[34:37], v[82:85], v[74:77], v[34:37]
	v_mfma_f32_16x16x32_bf16 v[22:25], v[86:89], v[74:77], v[22:25]
	v_mfma_f32_16x16x32_bf16 v[18:21], v[208:211], v[74:77], v[18:21]
	v_mfma_f32_16x16x32_bf16 v[62:65], v[212:215], v[74:77], v[62:65]
	ds_read_b128 v[74:77], v255 offset:4096
	s_waitcnt lgkmcnt(7)
	v_mfma_f32_16x16x32_bf16 v[58:61], v[82:85], v[78:81], v[58:61]
	v_mfma_f32_16x16x32_bf16 v[54:57], v[86:89], v[78:81], v[54:57]
	v_mfma_f32_16x16x32_bf16 v[50:53], v[208:211], v[78:81], v[50:53]
	v_mfma_f32_16x16x32_bf16 v[2:5], v[212:215], v[78:81], v[2:5]
	ds_read_b128 v[78:81], v255 offset:6144
	s_waitcnt lgkmcnt(3)
	v_mfma_f32_16x16x32_bf16 v[6:9], v[216:219], v[66:69], v[6:9]
	v_mfma_f32_16x16x32_bf16 v[30:33], v[220:223], v[66:69], v[30:33]
	v_mfma_f32_16x16x32_bf16 v[38:41], v[224:227], v[66:69], v[38:41]
	v_mfma_f32_16x16x32_bf16 v[42:45], v[228:231], v[66:69], v[42:45]
	s_waitcnt lgkmcnt(2)
	v_mfma_f32_16x16x32_bf16 v[46:49], v[216:219], v[70:73], v[46:49]
	v_mfma_f32_16x16x32_bf16 v[26:29], v[220:223], v[70:73], v[26:29]
	v_mfma_f32_16x16x32_bf16 v[14:17], v[224:227], v[70:73], v[14:17]
	v_mfma_f32_16x16x32_bf16 v[10:13], v[228:231], v[70:73], v[10:13]
	s_waitcnt vmcnt(6)
	s_waitcnt lgkmcnt(0)
	s_barrier
	s_add_i32 m0, s67, 0x10000
	s_nop 0
	global_load_lds_dwordx4 v188, s[80:81]
	s_add_i32 m0, s67, 0x12000
	s_nop 0
	global_load_lds_dwordx4 v189, s[80:81]
	s_add_i32 m0, s67, 0x14000
	s_nop 0
	global_load_lds_dwordx4 v190, s[80:81]
	s_add_i32 m0, s67, 0x16000
	s_nop 0
	global_load_lds_dwordx4 v191, s[80:81]
	s_add_i32 m0, s67, 0x20400
	s_nop 0
	global_load_lds_dwordx4 v205, s[96:97]
	s_add_i32 m0, s67, 0x22400
	s_nop 0
	global_load_lds_dwordx4 v206, s[96:97]
	s_add_u32 s80, s80, 0x80
	s_addc_u32 s81, s81, 0
	s_add_u32 s96, s96, 0x80
	s_addc_u32 s97, s97, 0
	s_movk_i32 s10, 0x400
	s_mov_b32 s11, 0
	v_lshl_add_u64 v[248:249], v[128:129], 0, s[10:11]
	global_load_dwordx2 v[232:233], v[248:249], off
	global_load_dwordx2 v[234:235], v[248:249], off offset:32
	v_lshl_add_u64 v[248:249], v[132:133], 0, s[10:11]
	global_load_dwordx2 v[236:237], v[248:249], off
	global_load_dwordx2 v[238:239], v[248:249], off offset:32
	v_lshl_add_u64 v[248:249], v[152:153], 0, s[10:11]
	global_load_dwordx2 v[240:241], v[248:249], off
	global_load_dwordx2 v[242:243], v[248:249], off offset:32
	v_lshl_add_u64 v[248:249], v[154:155], 0, s[10:11]
	global_load_dwordx2 v[244:245], v[248:249], off
	global_load_dwordx2 v[246:247], v[248:249], off offset:32
	ds_read_b128 v[82:85], v90 offset:0
	ds_read_b128 v[86:89], v90 offset:2048
	ds_read_b128 v[208:211], v90 offset:4096
	ds_read_b128 v[212:215], v90 offset:6144
	ds_read_b128 v[66:69], v207 offset:0
	ds_read_b128 v[70:73], v207 offset:2048
	v_mfma_f32_16x16x32_bf16 v[34:37], v[216:219], v[74:77], v[34:37]
	v_mfma_f32_16x16x32_bf16 v[22:25], v[220:223], v[74:77], v[22:25]
	v_mfma_f32_16x16x32_bf16 v[18:21], v[224:227], v[74:77], v[18:21]
	v_mfma_f32_16x16x32_bf16 v[62:65], v[228:231], v[74:77], v[62:65]
	ds_read_b128 v[74:77], v207 offset:4096
	v_mfma_f32_16x16x32_bf16 v[58:61], v[216:219], v[78:81], v[58:61]
	v_mfma_f32_16x16x32_bf16 v[54:57], v[220:223], v[78:81], v[54:57]
	v_mfma_f32_16x16x32_bf16 v[50:53], v[224:227], v[78:81], v[50:53]
	v_mfma_f32_16x16x32_bf16 v[2:5], v[228:231], v[78:81], v[2:5]
	ds_read_b128 v[78:81], v207 offset:6144
	ds_read_b128 v[216:219], v91 offset:0
	ds_read_b128 v[220:223], v91 offset:2048
	ds_read_b128 v[224:227], v91 offset:4096
	ds_read_b128 v[228:231], v91 offset:6144
	s_waitcnt lgkmcnt(7)
	v_mfma_f32_16x16x32_bf16 v[6:9], v[82:85], v[66:69], v[6:9]
	v_mfma_f32_16x16x32_bf16 v[30:33], v[86:89], v[66:69], v[30:33]
	v_mfma_f32_16x16x32_bf16 v[38:41], v[208:211], v[66:69], v[38:41]
	v_mfma_f32_16x16x32_bf16 v[42:45], v[212:215], v[66:69], v[42:45]
	ds_read_b128 v[66:69], v119 offset:0
	s_waitcnt lgkmcnt(7)
	v_mfma_f32_16x16x32_bf16 v[46:49], v[82:85], v[70:73], v[46:49]
	v_mfma_f32_16x16x32_bf16 v[26:29], v[86:89], v[70:73], v[26:29]
	v_mfma_f32_16x16x32_bf16 v[14:17], v[208:211], v[70:73], v[14:17]
	v_mfma_f32_16x16x32_bf16 v[10:13], v[212:215], v[70:73], v[10:13]
	ds_read_b128 v[70:73], v119 offset:2048
	s_waitcnt lgkmcnt(7)
	v_mfma_f32_16x16x32_bf16 v[34:37], v[82:85], v[74:77], v[34:37]
	v_mfma_f32_16x16x32_bf16 v[22:25], v[86:89], v[74:77], v[22:25]
	v_mfma_f32_16x16x32_bf16 v[18:21], v[208:211], v[74:77], v[18:21]
	v_mfma_f32_16x16x32_bf16 v[62:65], v[212:215], v[74:77], v[62:65]
	ds_read_b128 v[74:77], v119 offset:4096
	s_waitcnt lgkmcnt(7)
	v_mfma_f32_16x16x32_bf16 v[58:61], v[82:85], v[78:81], v[58:61]
	v_mfma_f32_16x16x32_bf16 v[54:57], v[86:89], v[78:81], v[54:57]
	v_mfma_f32_16x16x32_bf16 v[50:53], v[208:211], v[78:81], v[50:53]
	v_mfma_f32_16x16x32_bf16 v[2:5], v[212:215], v[78:81], v[2:5]
	ds_read_b128 v[78:81], v119 offset:6144
	s_waitcnt lgkmcnt(3)
	v_mfma_f32_16x16x32_bf16 v[6:9], v[216:219], v[66:69], v[6:9]
	v_mfma_f32_16x16x32_bf16 v[30:33], v[220:223], v[66:69], v[30:33]
	v_mfma_f32_16x16x32_bf16 v[38:41], v[224:227], v[66:69], v[38:41]
	v_mfma_f32_16x16x32_bf16 v[42:45], v[228:231], v[66:69], v[42:45]
	s_waitcnt lgkmcnt(2)
	v_mfma_f32_16x16x32_bf16 v[46:49], v[216:219], v[70:73], v[46:49]
	v_mfma_f32_16x16x32_bf16 v[26:29], v[220:223], v[70:73], v[26:29]
	v_mfma_f32_16x16x32_bf16 v[14:17], v[224:227], v[70:73], v[14:17]
	v_mfma_f32_16x16x32_bf16 v[10:13], v[228:231], v[70:73], v[10:13]
	s_waitcnt vmcnt(14)
	s_waitcnt lgkmcnt(0)
	s_barrier
	s_add_i32 m0, s67, 0x0
	s_nop 0
	global_load_lds_dwordx4 v188, s[80:81]
	s_add_i32 m0, s67, 0x2000
	s_nop 0
	global_load_lds_dwordx4 v189, s[80:81]
	s_add_i32 m0, s67, 0x4000
	s_nop 0
	global_load_lds_dwordx4 v190, s[80:81]
	s_add_i32 m0, s67, 0x6000
	s_nop 0
	global_load_lds_dwordx4 v191, s[80:81]
	s_add_i32 m0, s67, 0x18000
	s_nop 0
	global_load_lds_dwordx4 v205, s[96:97]
	s_add_i32 m0, s67, 0x1a000
	s_nop 0
	global_load_lds_dwordx4 v206, s[96:97]
	s_add_u32 s80, s80, 0x280
	s_addc_u32 s81, s81, 0
	s_add_u32 s96, s96, 0xffc80
	s_addc_u32 s97, s97, 0
	ds_read_b128 v[82:85], v90 offset:16384
	ds_read_b128 v[86:89], v90 offset:18432
	ds_read_b128 v[208:211], v90 offset:20480
	ds_read_b128 v[212:215], v90 offset:22528
	ds_read_b128 v[66:69], v207 offset:32768
	ds_read_b128 v[70:73], v207 offset:34816
	v_mfma_f32_16x16x32_bf16 v[34:37], v[216:219], v[74:77], v[34:37]
	v_mfma_f32_16x16x32_bf16 v[22:25], v[220:223], v[74:77], v[22:25]
	v_mfma_f32_16x16x32_bf16 v[18:21], v[224:227], v[74:77], v[18:21]
	v_mfma_f32_16x16x32_bf16 v[62:65], v[228:231], v[74:77], v[62:65]
	ds_read_b128 v[74:77], v207 offset:36864
	v_mfma_f32_16x16x32_bf16 v[58:61], v[216:219], v[78:81], v[58:61]
	v_mfma_f32_16x16x32_bf16 v[54:57], v[220:223], v[78:81], v[54:57]
	v_mfma_f32_16x16x32_bf16 v[50:53], v[224:227], v[78:81], v[50:53]
	v_mfma_f32_16x16x32_bf16 v[2:5], v[228:231], v[78:81], v[2:5]
	ds_read_b128 v[78:81], v207 offset:38912
	ds_read_b128 v[216:219], v91 offset:16384
	ds_read_b128 v[220:223], v91 offset:18432
	ds_read_b128 v[224:227], v91 offset:20480
	ds_read_b128 v[228:231], v91 offset:22528
	s_waitcnt lgkmcnt(7)
	v_mfma_f32_16x16x32_bf16 v[6:9], v[82:85], v[66:69], v[6:9]
	v_mfma_f32_16x16x32_bf16 v[30:33], v[86:89], v[66:69], v[30:33]
	v_mfma_f32_16x16x32_bf16 v[38:41], v[208:211], v[66:69], v[38:41]
	v_mfma_f32_16x16x32_bf16 v[42:45], v[212:215], v[66:69], v[42:45]
	ds_read_b128 v[66:69], v119 offset:32768
	s_waitcnt lgkmcnt(7)
	v_mfma_f32_16x16x32_bf16 v[46:49], v[82:85], v[70:73], v[46:49]
	v_mfma_f32_16x16x32_bf16 v[26:29], v[86:89], v[70:73], v[26:29]
	v_mfma_f32_16x16x32_bf16 v[14:17], v[208:211], v[70:73], v[14:17]
	v_mfma_f32_16x16x32_bf16 v[10:13], v[212:215], v[70:73], v[10:13]
	ds_read_b128 v[70:73], v119 offset:34816
	s_waitcnt lgkmcnt(7)
	v_mfma_f32_16x16x32_bf16 v[34:37], v[82:85], v[74:77], v[34:37]
	v_mfma_f32_16x16x32_bf16 v[22:25], v[86:89], v[74:77], v[22:25]
	v_mfma_f32_16x16x32_bf16 v[18:21], v[208:211], v[74:77], v[18:21]
	v_mfma_f32_16x16x32_bf16 v[62:65], v[212:215], v[74:77], v[62:65]
	ds_read_b128 v[74:77], v119 offset:36864
	s_waitcnt lgkmcnt(7)
	v_mfma_f32_16x16x32_bf16 v[58:61], v[82:85], v[78:81], v[58:61]
	v_mfma_f32_16x16x32_bf16 v[54:57], v[86:89], v[78:81], v[54:57]
	v_mfma_f32_16x16x32_bf16 v[50:53], v[208:211], v[78:81], v[50:53]
	v_mfma_f32_16x16x32_bf16 v[2:5], v[212:215], v[78:81], v[2:5]
	ds_read_b128 v[78:81], v119 offset:38912
	s_waitcnt lgkmcnt(3)
	v_mfma_f32_16x16x32_bf16 v[6:9], v[216:219], v[66:69], v[6:9]
	v_mfma_f32_16x16x32_bf16 v[30:33], v[220:223], v[66:69], v[30:33]
	v_mfma_f32_16x16x32_bf16 v[38:41], v[224:227], v[66:69], v[38:41]
	v_mfma_f32_16x16x32_bf16 v[42:45], v[228:231], v[66:69], v[42:45]
	s_waitcnt lgkmcnt(2)
	v_mfma_f32_16x16x32_bf16 v[46:49], v[216:219], v[70:73], v[46:49]
	v_mfma_f32_16x16x32_bf16 v[26:29], v[220:223], v[70:73], v[26:29]
	v_mfma_f32_16x16x32_bf16 v[14:17], v[224:227], v[70:73], v[14:17]
	v_mfma_f32_16x16x32_bf16 v[10:13], v[228:231], v[70:73], v[10:13]
	s_waitcnt vmcnt(14)
	s_waitcnt lgkmcnt(0)
	s_barrier
	s_add_i32 m0, s67, 0x8000
	s_nop 0
	global_load_lds_dwordx4 v188, s[80:81]
	s_add_i32 m0, s67, 0xa000
	s_nop 0
	global_load_lds_dwordx4 v189, s[80:81]
	s_add_i32 m0, s67, 0xc000
	s_nop 0
	global_load_lds_dwordx4 v190, s[80:81]
	s_add_i32 m0, s67, 0xe000
	s_nop 0
	global_load_lds_dwordx4 v191, s[80:81]
	s_add_i32 m0, s67, 0x1c000
	s_nop 0
	global_load_lds_dwordx4 v205, s[96:97]
	s_add_i32 m0, s67, 0x1e000
	s_nop 0
	global_load_lds_dwordx4 v206, s[96:97]
	s_add_u32 s80, s80, 0x80
	s_addc_u32 s81, s81, 0
	s_add_u32 s96, s96, 0x80
	s_addc_u32 s97, s97, 0
	ds_read_b128 v[82:85], v90 offset:33792
	ds_read_b128 v[86:89], v90 offset:35840
	ds_read_b128 v[208:211], v90 offset:37888
	ds_read_b128 v[212:215], v90 offset:39936
	ds_read_b128 v[66:69], v0 offset:0
	ds_read_b128 v[70:73], v0 offset:2048
	v_mfma_f32_16x16x32_bf16 v[34:37], v[216:219], v[74:77], v[34:37]
	v_mfma_f32_16x16x32_bf16 v[22:25], v[220:223], v[74:77], v[22:25]
	v_mfma_f32_16x16x32_bf16 v[18:21], v[224:227], v[74:77], v[18:21]
	v_mfma_f32_16x16x32_bf16 v[62:65], v[228:231], v[74:77], v[62:65]
	ds_read_b128 v[74:77], v0 offset:4096
	v_mfma_f32_16x16x32_bf16 v[58:61], v[216:219], v[78:81], v[58:61]
	v_mfma_f32_16x16x32_bf16 v[54:57], v[220:223], v[78:81], v[54:57]
	v_mfma_f32_16x16x32_bf16 v[50:53], v[224:227], v[78:81], v[50:53]
	v_mfma_f32_16x16x32_bf16 v[2:5], v[228:231], v[78:81], v[2:5]
	ds_read_b128 v[78:81], v0 offset:6144
	ds_read_b128 v[216:219], v91 offset:33792
	ds_read_b128 v[220:223], v91 offset:35840
	ds_read_b128 v[224:227], v91 offset:37888
	ds_read_b128 v[228:231], v91 offset:39936
	s_waitcnt lgkmcnt(7)
	v_mfma_f32_16x16x32_bf16 v[6:9], v[82:85], v[66:69], v[6:9]
	v_mfma_f32_16x16x32_bf16 v[30:33], v[86:89], v[66:69], v[30:33]
	v_mfma_f32_16x16x32_bf16 v[38:41], v[208:211], v[66:69], v[38:41]
	v_mfma_f32_16x16x32_bf16 v[42:45], v[212:215], v[66:69], v[42:45]
	ds_read_b128 v[66:69], v255 offset:0
	s_waitcnt lgkmcnt(7)
	v_mfma_f32_16x16x32_bf16 v[46:49], v[82:85], v[70:73], v[46:49]
	v_mfma_f32_16x16x32_bf16 v[26:29], v[86:89], v[70:73], v[26:29]
	v_mfma_f32_16x16x32_bf16 v[14:17], v[208:211], v[70:73], v[14:17]
	v_mfma_f32_16x16x32_bf16 v[10:13], v[212:215], v[70:73], v[10:13]
	ds_read_b128 v[70:73], v255 offset:2048
	s_waitcnt lgkmcnt(7)
	v_mfma_f32_16x16x32_bf16 v[34:37], v[82:85], v[74:77], v[34:37]
	v_mfma_f32_16x16x32_bf16 v[22:25], v[86:89], v[74:77], v[22:25]
	v_mfma_f32_16x16x32_bf16 v[18:21], v[208:211], v[74:77], v[18:21]
	v_mfma_f32_16x16x32_bf16 v[62:65], v[212:215], v[74:77], v[62:65]
	ds_read_b128 v[74:77], v255 offset:4096
	s_waitcnt lgkmcnt(7)
	v_mfma_f32_16x16x32_bf16 v[58:61], v[82:85], v[78:81], v[58:61]
	v_mfma_f32_16x16x32_bf16 v[54:57], v[86:89], v[78:81], v[54:57]
	v_mfma_f32_16x16x32_bf16 v[50:53], v[208:211], v[78:81], v[50:53]
	v_mfma_f32_16x16x32_bf16 v[2:5], v[212:215], v[78:81], v[2:5]
	ds_read_b128 v[78:81], v255 offset:6144
	s_waitcnt lgkmcnt(3)
	v_mfma_f32_16x16x32_bf16 v[6:9], v[216:219], v[66:69], v[6:9]
	v_mfma_f32_16x16x32_bf16 v[30:33], v[220:223], v[66:69], v[30:33]
	v_mfma_f32_16x16x32_bf16 v[38:41], v[224:227], v[66:69], v[38:41]
	v_mfma_f32_16x16x32_bf16 v[42:45], v[228:231], v[66:69], v[42:45]
	s_waitcnt lgkmcnt(2)
	v_mfma_f32_16x16x32_bf16 v[46:49], v[216:219], v[70:73], v[46:49]
	v_mfma_f32_16x16x32_bf16 v[26:29], v[220:223], v[70:73], v[26:29]
	v_mfma_f32_16x16x32_bf16 v[14:17], v[224:227], v[70:73], v[14:17]
	v_mfma_f32_16x16x32_bf16 v[10:13], v[228:231], v[70:73], v[10:13]
	s_waitcnt vmcnt(6)
	s_waitcnt lgkmcnt(0)
	s_barrier
	s_add_i32 m0, s67, 0x10000
	s_nop 0
	global_load_lds_dwordx4 v188, s[80:81]
	s_add_i32 m0, s67, 0x12000
	s_nop 0
	global_load_lds_dwordx4 v189, s[80:81]
	s_add_i32 m0, s67, 0x14000
	s_nop 0
	global_load_lds_dwordx4 v190, s[80:81]
	s_add_i32 m0, s67, 0x16000
	s_nop 0
	global_load_lds_dwordx4 v191, s[80:81]
	s_add_i32 m0, s67, 0x20400
	s_nop 0
	global_load_lds_dwordx4 v205, s[96:97]
	s_add_i32 m0, s67, 0x22400
	s_nop 0
	global_load_lds_dwordx4 v206, s[96:97]
	s_add_u32 s80, s80, 0x80
	s_addc_u32 s81, s81, 0
	s_add_u32 s96, s96, 0x80
	s_addc_u32 s97, s97, 0
	ds_read_b128 v[82:85], v90 offset:0
	ds_read_b128 v[86:89], v90 offset:2048
	ds_read_b128 v[208:211], v90 offset:4096
	ds_read_b128 v[212:215], v90 offset:6144
	ds_read_b128 v[66:69], v207 offset:0
	ds_read_b128 v[70:73], v207 offset:2048
	v_mfma_f32_16x16x32_bf16 v[34:37], v[216:219], v[74:77], v[34:37]
	v_mfma_f32_16x16x32_bf16 v[22:25], v[220:223], v[74:77], v[22:25]
	v_mfma_f32_16x16x32_bf16 v[18:21], v[224:227], v[74:77], v[18:21]
	v_mfma_f32_16x16x32_bf16 v[62:65], v[228:231], v[74:77], v[62:65]
	ds_read_b128 v[74:77], v207 offset:4096
	v_mfma_f32_16x16x32_bf16 v[58:61], v[216:219], v[78:81], v[58:61]
	v_mfma_f32_16x16x32_bf16 v[54:57], v[220:223], v[78:81], v[54:57]
	v_mfma_f32_16x16x32_bf16 v[50:53], v[224:227], v[78:81], v[50:53]
	v_mfma_f32_16x16x32_bf16 v[2:5], v[228:231], v[78:81], v[2:5]
	ds_read_b128 v[78:81], v207 offset:6144
	ds_read_b128 v[216:219], v91 offset:0
	ds_read_b128 v[220:223], v91 offset:2048
	ds_read_b128 v[224:227], v91 offset:4096
	ds_read_b128 v[228:231], v91 offset:6144
	s_waitcnt lgkmcnt(7)
	v_mfma_f32_16x16x32_bf16 v[6:9], v[82:85], v[66:69], v[6:9]
	v_mfma_f32_16x16x32_bf16 v[30:33], v[86:89], v[66:69], v[30:33]
	v_mfma_f32_16x16x32_bf16 v[38:41], v[208:211], v[66:69], v[38:41]
	v_mfma_f32_16x16x32_bf16 v[42:45], v[212:215], v[66:69], v[42:45]
	ds_read_b128 v[66:69], v119 offset:0
	s_waitcnt lgkmcnt(7)
	v_mfma_f32_16x16x32_bf16 v[46:49], v[82:85], v[70:73], v[46:49]
	v_mfma_f32_16x16x32_bf16 v[26:29], v[86:89], v[70:73], v[26:29]
	v_mfma_f32_16x16x32_bf16 v[14:17], v[208:211], v[70:73], v[14:17]
	v_mfma_f32_16x16x32_bf16 v[10:13], v[212:215], v[70:73], v[10:13]
	ds_read_b128 v[70:73], v119 offset:2048
	s_waitcnt lgkmcnt(7)
	v_mfma_f32_16x16x32_bf16 v[34:37], v[82:85], v[74:77], v[34:37]
	v_mfma_f32_16x16x32_bf16 v[22:25], v[86:89], v[74:77], v[22:25]
	v_mfma_f32_16x16x32_bf16 v[18:21], v[208:211], v[74:77], v[18:21]
	v_mfma_f32_16x16x32_bf16 v[62:65], v[212:215], v[74:77], v[62:65]
	ds_read_b128 v[74:77], v119 offset:4096
	s_waitcnt lgkmcnt(7)
	v_mfma_f32_16x16x32_bf16 v[58:61], v[82:85], v[78:81], v[58:61]
	v_mfma_f32_16x16x32_bf16 v[54:57], v[86:89], v[78:81], v[54:57]
	v_mfma_f32_16x16x32_bf16 v[50:53], v[208:211], v[78:81], v[50:53]
	v_mfma_f32_16x16x32_bf16 v[2:5], v[212:215], v[78:81], v[2:5]
	ds_read_b128 v[78:81], v119 offset:6144
	s_waitcnt lgkmcnt(3)
	v_mfma_f32_16x16x32_bf16 v[6:9], v[216:219], v[66:69], v[6:9]
	s_waitcnt vmcnt(18)
	v_mfma_f32_16x16x32_bf16 v[30:33], v[220:223], v[66:69], v[30:33]
	v_mfma_f32_16x16x32_bf16 v[38:41], v[224:227], v[66:69], v[38:41]
	v_mfma_f32_16x16x32_bf16 v[42:45], v[228:231], v[66:69], v[42:45]
	v_cvt_f32_ubyte0_e32 v248, v232
	v_cvt_f32_ubyte1_e32 v249, v232
	v_cvt_f32_ubyte2_e32 v250, v232
	v_cvt_f32_ubyte3_e32 v251, v232
	v_mul_f32_e32 v248, s34, v248
	v_mul_f32_e32 v249, s34, v249
	v_mul_f32_e32 v250, s34, v250
	v_mul_f32_e32 v251, s34, v251
	v_fma_f32 v184, v6, v248, v184
	v_fma_f32 v185, v7, v249, v185
	v_fma_f32 v186, v8, v250, v186
	v_fma_f32 v187, v9, v251, v187
	s_waitcnt lgkmcnt(2)
	v_mfma_f32_16x16x32_bf16 v[46:49], v[216:219], v[70:73], v[46:49]
	v_cvt_f32_ubyte0_e32 v248, v233
	v_cvt_f32_ubyte1_e32 v249, v233
	v_cvt_f32_ubyte2_e32 v250, v233
	v_cvt_f32_ubyte3_e32 v251, v233
	v_mul_f32_e32 v248, s34, v248
	v_mul_f32_e32 v249, s34, v249
	v_mul_f32_e32 v250, s34, v250
	v_mul_f32_e32 v251, s34, v251
	v_fma_f32 v180, v30, v248, v180
	v_fma_f32 v181, v31, v249, v181
	v_fma_f32 v182, v32, v250, v182
	v_fma_f32 v183, v33, v251, v183
	v_mfma_f32_16x16x32_bf16 v[26:29], v[220:223], v[70:73], v[26:29]
	v_cvt_f32_ubyte0_e32 v248, v234
	v_cvt_f32_ubyte1_e32 v249, v234
	v_cvt_f32_ubyte2_e32 v250, v234
	v_cvt_f32_ubyte3_e32 v251, v234
	v_mul_f32_e32 v248, s34, v248
	v_mul_f32_e32 v249, s34, v249
	v_mul_f32_e32 v250, s34, v250
	v_mul_f32_e32 v251, s34, v251
	v_fma_f32 v176, v38, v248, v176
	v_fma_f32 v177, v39, v249, v177
	v_fma_f32 v178, v40, v250, v178
	v_fma_f32 v179, v41, v251, v179
	v_mfma_f32_16x16x32_bf16 v[14:17], v[224:227], v[70:73], v[14:17]
	v_cvt_f32_ubyte0_e32 v248, v235
	v_cvt_f32_ubyte1_e32 v249, v235
	v_cvt_f32_ubyte2_e32 v250, v235
	v_cvt_f32_ubyte3_e32 v251, v235
	v_mul_f32_e32 v248, s34, v248
	v_mul_f32_e32 v249, s34, v249
	v_mul_f32_e32 v250, s34, v250
	v_mul_f32_e32 v251, s34, v251
	v_fma_f32 v172, v42, v248, v172
	v_fma_f32 v173, v43, v249, v173
	v_fma_f32 v174, v44, v250, v174
	v_fma_f32 v175, v45, v251, v175
	v_mfma_f32_16x16x32_bf16 v[10:13], v[228:231], v[70:73], v[10:13]
	v_cvt_f32_ubyte0_e32 v248, v236
	v_cvt_f32_ubyte1_e32 v249, v236
	v_cvt_f32_ubyte2_e32 v250, v236
	v_cvt_f32_ubyte3_e32 v251, v236
	v_mul_f32_e32 v248, s34, v248
	v_mul_f32_e32 v249, s34, v249
	v_mul_f32_e32 v250, s34, v250
	v_mul_f32_e32 v251, s34, v251
	v_fma_f32 v168, v46, v248, v168
	v_fma_f32 v169, v47, v249, v169
	v_fma_f32 v170, v48, v250, v170
	v_fma_f32 v171, v49, v251, v171
	s_waitcnt vmcnt(6)
	s_waitcnt lgkmcnt(0)
	s_barrier
	s_add_i32 m0, s67, 0x0
	s_nop 0
	global_load_lds_dwordx4 v188, s[80:81]
	s_add_i32 m0, s67, 0x2000
	s_nop 0
	global_load_lds_dwordx4 v189, s[80:81]
	s_add_i32 m0, s67, 0x4000
	s_nop 0
	global_load_lds_dwordx4 v190, s[80:81]
	s_add_i32 m0, s67, 0x6000
	s_nop 0
	global_load_lds_dwordx4 v191, s[80:81]
	s_add_i32 m0, s67, 0x18000
	s_nop 0
	global_load_lds_dwordx4 v205, s[96:97]
	s_add_i32 m0, s67, 0x1a000
	s_nop 0
	global_load_lds_dwordx4 v206, s[96:97]
	s_add_u32 s80, s80, 0x80
	s_addc_u32 s81, s81, 0
	s_add_u32 s96, s96, 0x80
	s_addc_u32 s97, s97, 0
	ds_read_b128 v[82:85], v90 offset:16384
	ds_read_b128 v[86:89], v90 offset:18432
	ds_read_b128 v[208:211], v90 offset:20480
	ds_read_b128 v[212:215], v90 offset:22528
	ds_read_b128 v[66:69], v207 offset:32768
	ds_read_b128 v[70:73], v207 offset:34816
	v_mfma_f32_16x16x32_bf16 v[34:37], v[216:219], v[74:77], v[34:37]
	v_cvt_f32_ubyte0_e32 v248, v237
	v_cvt_f32_ubyte1_e32 v249, v237
	v_cvt_f32_ubyte2_e32 v250, v237
	v_cvt_f32_ubyte3_e32 v251, v237
	v_mul_f32_e32 v248, s34, v248
	v_mul_f32_e32 v249, s34, v249
	v_mul_f32_e32 v250, s34, v250
	v_mul_f32_e32 v251, s34, v251
	v_fma_f32 v164, v26, v248, v164
	v_fma_f32 v165, v27, v249, v165
	v_fma_f32 v166, v28, v250, v166
	v_fma_f32 v167, v29, v251, v167
	v_mfma_f32_16x16x32_bf16 v[22:25], v[220:223], v[74:77], v[22:25]
	v_cvt_f32_ubyte0_e32 v248, v238
	v_cvt_f32_ubyte1_e32 v249, v238
	v_cvt_f32_ubyte2_e32 v250, v238
	v_cvt_f32_ubyte3_e32 v251, v238
	v_mul_f32_e32 v248, s34, v248
	v_mul_f32_e32 v249, s34, v249
	v_mul_f32_e32 v250, s34, v250
	v_mul_f32_e32 v251, s34, v251
	v_fma_f32 v160, v14, v248, v160
	v_fma_f32 v161, v15, v249, v161
	v_fma_f32 v162, v16, v250, v162
	v_fma_f32 v163, v17, v251, v163
	v_mfma_f32_16x16x32_bf16 v[18:21], v[224:227], v[74:77], v[18:21]
	v_cvt_f32_ubyte0_e32 v248, v239
	v_cvt_f32_ubyte1_e32 v249, v239
	v_cvt_f32_ubyte2_e32 v250, v239
	v_cvt_f32_ubyte3_e32 v251, v239
	v_mul_f32_e32 v248, s34, v248
	v_mul_f32_e32 v249, s34, v249
	v_mul_f32_e32 v250, s34, v250
	v_mul_f32_e32 v251, s34, v251
	v_fma_f32 v156, v10, v248, v156
	v_fma_f32 v157, v11, v249, v157
	v_fma_f32 v158, v12, v250, v158
	v_fma_f32 v159, v13, v251, v159
	v_mfma_f32_16x16x32_bf16 v[62:65], v[228:231], v[74:77], v[62:65]
	v_cvt_f32_ubyte0_e32 v248, v240
	v_cvt_f32_ubyte1_e32 v249, v240
	v_cvt_f32_ubyte2_e32 v250, v240
	v_cvt_f32_ubyte3_e32 v251, v240
	v_mul_f32_e32 v248, s34, v248
	v_mul_f32_e32 v249, s34, v249
	v_mul_f32_e32 v250, s34, v250
	v_mul_f32_e32 v251, s34, v251
	v_fma_f32 v136, v34, v248, v136
	v_fma_f32 v137, v35, v249, v137
	v_fma_f32 v150, v36, v250, v150
	v_fma_f32 v151, v37, v251, v151
	ds_read_b128 v[74:77], v207 offset:36864
	v_mfma_f32_16x16x32_bf16 v[58:61], v[216:219], v[78:81], v[58:61]
	v_cvt_f32_ubyte0_e32 v248, v241
	v_cvt_f32_ubyte1_e32 v249, v241
	v_cvt_f32_ubyte2_e32 v250, v241
	v_cvt_f32_ubyte3_e32 v251, v241
	v_mul_f32_e32 v248, s34, v248
	v_mul_f32_e32 v249, s34, v249
	v_mul_f32_e32 v250, s34, v250
	v_mul_f32_e32 v251, s34, v251
	v_fma_f32 v130, v22, v248, v130
	v_fma_f32 v131, v23, v249, v131
	v_fma_f32 v134, v24, v250, v134
	v_fma_f32 v135, v25, v251, v135
	v_mfma_f32_16x16x32_bf16 v[54:57], v[220:223], v[78:81], v[54:57]
	v_cvt_f32_ubyte0_e32 v248, v242
	v_cvt_f32_ubyte1_e32 v249, v242
	v_cvt_f32_ubyte2_e32 v250, v242
	v_cvt_f32_ubyte3_e32 v251, v242
	v_mul_f32_e32 v248, s34, v248
	v_mul_f32_e32 v249, s34, v249
	v_mul_f32_e32 v250, s34, v250
	v_mul_f32_e32 v251, s34, v251
	v_fma_f32 v124, v18, v248, v124
	v_fma_f32 v125, v19, v249, v125
	v_fma_f32 v126, v20, v250, v126
	v_fma_f32 v127, v21, v251, v127
	v_mfma_f32_16x16x32_bf16 v[50:53], v[224:227], v[78:81], v[50:53]
	v_cvt_f32_ubyte0_e32 v248, v243
	v_cvt_f32_ubyte1_e32 v249, v243
	v_cvt_f32_ubyte2_e32 v250, v243
	v_cvt_f32_ubyte3_e32 v251, v243
	v_mul_f32_e32 v248, s34, v248
	v_mul_f32_e32 v249, s34, v249
	v_mul_f32_e32 v250, s34, v250
	v_mul_f32_e32 v251, s34, v251
	v_fma_f32 v120, v62, v248, v120
	v_fma_f32 v121, v63, v249, v121
	v_fma_f32 v122, v64, v250, v122
	v_fma_f32 v123, v65, v251, v123
	v_mfma_f32_16x16x32_bf16 v[2:5], v[228:231], v[78:81], v[2:5]
	v_cvt_f32_ubyte0_e32 v248, v244
	v_cvt_f32_ubyte1_e32 v249, v244
	v_cvt_f32_ubyte2_e32 v250, v244
	v_cvt_f32_ubyte3_e32 v251, v244
	v_mul_f32_e32 v248, s34, v248
	v_mul_f32_e32 v249, s34, v249
	v_mul_f32_e32 v250, s34, v250
	v_mul_f32_e32 v251, s34, v251
	v_fma_f32 v114, v58, v248, v114
	v_fma_f32 v115, v59, v249, v115
	v_fma_f32 v116, v60, v250, v116
	v_fma_f32 v117, v61, v251, v117
	ds_read_b128 v[78:81], v207 offset:38912
	s_nop 7
	s_nop 3
	v_cvt_f32_ubyte0_e32 v248, v245
	v_cvt_f32_ubyte1_e32 v249, v245
	v_cvt_f32_ubyte2_e32 v250, v245
	v_cvt_f32_ubyte3_e32 v251, v245
	v_mul_f32_e32 v248, s34, v248
	v_mul_f32_e32 v249, s34, v249
	v_mul_f32_e32 v250, s34, v250
	v_mul_f32_e32 v251, s34, v251
	v_fma_f32 v106, v54, v248, v106
	v_fma_f32 v107, v55, v249, v107
	v_fma_f32 v108, v56, v250, v108
	v_fma_f32 v109, v57, v251, v109
	v_cvt_f32_ubyte0_e32 v248, v246
	v_cvt_f32_ubyte1_e32 v249, v246
	v_cvt_f32_ubyte2_e32 v250, v246
	v_cvt_f32_ubyte3_e32 v251, v246
	v_mul_f32_e32 v248, s34, v248
	v_mul_f32_e32 v249, s34, v249
	v_mul_f32_e32 v250, s34, v250
	v_mul_f32_e32 v251, s34, v251
	v_fma_f32 v100, v50, v248, v100
	v_fma_f32 v101, v51, v249, v101
	v_fma_f32 v102, v52, v250, v102
	v_fma_f32 v103, v53, v251, v103
	v_cvt_f32_ubyte0_e32 v248, v247
	v_cvt_f32_ubyte1_e32 v249, v247
	v_cvt_f32_ubyte2_e32 v250, v247
	v_cvt_f32_ubyte3_e32 v251, v247
	v_mul_f32_e32 v248, s34, v248
	v_mul_f32_e32 v249, s34, v249
	v_mul_f32_e32 v250, s34, v250
	v_mul_f32_e32 v251, s34, v251
	v_fma_f32 v96, v2, v248, v96
	v_fma_f32 v97, v3, v249, v97
	v_fma_f32 v98, v4, v250, v98
	v_fma_f32 v99, v5, v251, v99
	ds_read_b128 v[216:219], v91 offset:16384
	ds_read_b128 v[220:223], v91 offset:18432
	ds_read_b128 v[224:227], v91 offset:20480
	ds_read_b128 v[228:231], v91 offset:22528
	s_waitcnt lgkmcnt(7)
	v_mfma_f32_16x16x32_bf16 v[6:9], v[82:85], v[66:69], 0
	v_mfma_f32_16x16x32_bf16 v[30:33], v[86:89], v[66:69], 0
	v_mfma_f32_16x16x32_bf16 v[38:41], v[208:211], v[66:69], 0
	v_mfma_f32_16x16x32_bf16 v[42:45], v[212:215], v[66:69], 0
	ds_read_b128 v[66:69], v119 offset:32768
	s_waitcnt lgkmcnt(7)
	v_mfma_f32_16x16x32_bf16 v[46:49], v[82:85], v[70:73], 0
	v_mfma_f32_16x16x32_bf16 v[26:29], v[86:89], v[70:73], 0
	v_mfma_f32_16x16x32_bf16 v[14:17], v[208:211], v[70:73], 0
	v_mfma_f32_16x16x32_bf16 v[10:13], v[212:215], v[70:73], 0
	ds_read_b128 v[70:73], v119 offset:34816
	s_waitcnt lgkmcnt(7)
	v_mfma_f32_16x16x32_bf16 v[34:37], v[82:85], v[74:77], 0
	v_mfma_f32_16x16x32_bf16 v[22:25], v[86:89], v[74:77], 0
	v_mfma_f32_16x16x32_bf16 v[18:21], v[208:211], v[74:77], 0
	v_mfma_f32_16x16x32_bf16 v[62:65], v[212:215], v[74:77], 0
	ds_read_b128 v[74:77], v119 offset:36864
	s_waitcnt lgkmcnt(7)
	v_mfma_f32_16x16x32_bf16 v[58:61], v[82:85], v[78:81], 0
	v_mfma_f32_16x16x32_bf16 v[54:57], v[86:89], v[78:81], 0
	v_mfma_f32_16x16x32_bf16 v[50:53], v[208:211], v[78:81], 0
	v_mfma_f32_16x16x32_bf16 v[2:5], v[212:215], v[78:81], 0
	ds_read_b128 v[78:81], v119 offset:38912
	s_waitcnt lgkmcnt(3)
	v_mfma_f32_16x16x32_bf16 v[6:9], v[216:219], v[66:69], v[6:9]
	v_mfma_f32_16x16x32_bf16 v[30:33], v[220:223], v[66:69], v[30:33]
	v_mfma_f32_16x16x32_bf16 v[38:41], v[224:227], v[66:69], v[38:41]
	v_mfma_f32_16x16x32_bf16 v[42:45], v[228:231], v[66:69], v[42:45]
	s_waitcnt lgkmcnt(2)
	v_mfma_f32_16x16x32_bf16 v[46:49], v[216:219], v[70:73], v[46:49]
	v_mfma_f32_16x16x32_bf16 v[26:29], v[220:223], v[70:73], v[26:29]
	v_mfma_f32_16x16x32_bf16 v[14:17], v[224:227], v[70:73], v[14:17]
	v_mfma_f32_16x16x32_bf16 v[10:13], v[228:231], v[70:73], v[10:13]
	s_waitcnt vmcnt(6)
	s_waitcnt lgkmcnt(0)
	s_barrier
	s_add_i32 m0, s67, 0x8000
	s_nop 0
	global_load_lds_dwordx4 v188, s[80:81]
	s_add_i32 m0, s67, 0xa000
	s_nop 0
	global_load_lds_dwordx4 v189, s[80:81]
	s_add_i32 m0, s67, 0xc000
	s_nop 0
	global_load_lds_dwordx4 v190, s[80:81]
	s_add_i32 m0, s67, 0xe000
	s_nop 0
	global_load_lds_dwordx4 v191, s[80:81]
	s_add_i32 m0, s67, 0x1c000
	s_nop 0
	global_load_lds_dwordx4 v205, s[96:97]
	s_add_i32 m0, s67, 0x1e000
	s_nop 0
	global_load_lds_dwordx4 v206, s[96:97]
	s_add_u32 s80, s80, 0x80
	s_addc_u32 s81, s81, 0
	s_add_u32 s96, s96, 0x80
	s_addc_u32 s97, s97, 0
	ds_read_b128 v[82:85], v90 offset:33792
	ds_read_b128 v[86:89], v90 offset:35840
	ds_read_b128 v[208:211], v90 offset:37888
	ds_read_b128 v[212:215], v90 offset:39936
	ds_read_b128 v[66:69], v0 offset:0
	ds_read_b128 v[70:73], v0 offset:2048
	v_mfma_f32_16x16x32_bf16 v[34:37], v[216:219], v[74:77], v[34:37]
	v_mfma_f32_16x16x32_bf16 v[22:25], v[220:223], v[74:77], v[22:25]
	v_mfma_f32_16x16x32_bf16 v[18:21], v[224:227], v[74:77], v[18:21]
	v_mfma_f32_16x16x32_bf16 v[62:65], v[228:231], v[74:77], v[62:65]
	ds_read_b128 v[74:77], v0 offset:4096
	v_mfma_f32_16x16x32_bf16 v[58:61], v[216:219], v[78:81], v[58:61]
	v_mfma_f32_16x16x32_bf16 v[54:57], v[220:223], v[78:81], v[54:57]
	v_mfma_f32_16x16x32_bf16 v[50:53], v[224:227], v[78:81], v[50:53]
	v_mfma_f32_16x16x32_bf16 v[2:5], v[228:231], v[78:81], v[2:5]
	ds_read_b128 v[78:81], v0 offset:6144
	ds_read_b128 v[216:219], v91 offset:33792
	ds_read_b128 v[220:223], v91 offset:35840
	ds_read_b128 v[224:227], v91 offset:37888
	ds_read_b128 v[228:231], v91 offset:39936
	s_waitcnt lgkmcnt(7)
	v_mfma_f32_16x16x32_bf16 v[6:9], v[82:85], v[66:69], v[6:9]
	v_mfma_f32_16x16x32_bf16 v[30:33], v[86:89], v[66:69], v[30:33]
	v_mfma_f32_16x16x32_bf16 v[38:41], v[208:211], v[66:69], v[38:41]
	v_mfma_f32_16x16x32_bf16 v[42:45], v[212:215], v[66:69], v[42:45]
	ds_read_b128 v[66:69], v255 offset:0
	s_waitcnt lgkmcnt(7)
	v_mfma_f32_16x16x32_bf16 v[46:49], v[82:85], v[70:73], v[46:49]
	v_mfma_f32_16x16x32_bf16 v[26:29], v[86:89], v[70:73], v[26:29]
	v_mfma_f32_16x16x32_bf16 v[14:17], v[208:211], v[70:73], v[14:17]
	v_mfma_f32_16x16x32_bf16 v[10:13], v[212:215], v[70:73], v[10:13]
	ds_read_b128 v[70:73], v255 offset:2048
	s_waitcnt lgkmcnt(7)
	v_mfma_f32_16x16x32_bf16 v[34:37], v[82:85], v[74:77], v[34:37]
	v_mfma_f32_16x16x32_bf16 v[22:25], v[86:89], v[74:77], v[22:25]
	v_mfma_f32_16x16x32_bf16 v[18:21], v[208:211], v[74:77], v[18:21]
	v_mfma_f32_16x16x32_bf16 v[62:65], v[212:215], v[74:77], v[62:65]
	ds_read_b128 v[74:77], v255 offset:4096
	s_waitcnt lgkmcnt(7)
	v_mfma_f32_16x16x32_bf16 v[58:61], v[82:85], v[78:81], v[58:61]
	v_mfma_f32_16x16x32_bf16 v[54:57], v[86:89], v[78:81], v[54:57]
	v_mfma_f32_16x16x32_bf16 v[50:53], v[208:211], v[78:81], v[50:53]
	v_mfma_f32_16x16x32_bf16 v[2:5], v[212:215], v[78:81], v[2:5]
	ds_read_b128 v[78:81], v255 offset:6144
	s_waitcnt lgkmcnt(3)
	v_mfma_f32_16x16x32_bf16 v[6:9], v[216:219], v[66:69], v[6:9]
	v_mfma_f32_16x16x32_bf16 v[30:33], v[220:223], v[66:69], v[30:33]
	v_mfma_f32_16x16x32_bf16 v[38:41], v[224:227], v[66:69], v[38:41]
	v_mfma_f32_16x16x32_bf16 v[42:45], v[228:231], v[66:69], v[42:45]
	s_waitcnt lgkmcnt(2)
	v_mfma_f32_16x16x32_bf16 v[46:49], v[216:219], v[70:73], v[46:49]
	v_mfma_f32_16x16x32_bf16 v[26:29], v[220:223], v[70:73], v[26:29]
	v_mfma_f32_16x16x32_bf16 v[14:17], v[224:227], v[70:73], v[14:17]
	v_mfma_f32_16x16x32_bf16 v[10:13], v[228:231], v[70:73], v[10:13]
	s_waitcnt vmcnt(6)
	s_waitcnt lgkmcnt(0)
	s_barrier
	s_add_i32 m0, s67, 0x10000
	s_nop 0
	global_load_lds_dwordx4 v188, s[80:81]
	s_add_i32 m0, s67, 0x12000
	s_nop 0
	global_load_lds_dwordx4 v189, s[80:81]
	s_add_i32 m0, s67, 0x14000
	s_nop 0
	global_load_lds_dwordx4 v190, s[80:81]
	s_add_i32 m0, s67, 0x16000
	s_nop 0
	global_load_lds_dwordx4 v191, s[80:81]
	s_add_i32 m0, s67, 0x20400
	s_nop 0
	global_load_lds_dwordx4 v205, s[96:97]
	s_add_i32 m0, s67, 0x22400
	s_nop 0
	global_load_lds_dwordx4 v206, s[96:97]
	s_add_u32 s80, s80, 0x80
	s_addc_u32 s81, s81, 0
	s_add_u32 s96, s96, 0x80
	s_addc_u32 s97, s97, 0
	ds_read_b128 v[82:85], v90 offset:0
	ds_read_b128 v[86:89], v90 offset:2048
	ds_read_b128 v[208:211], v90 offset:4096
	ds_read_b128 v[212:215], v90 offset:6144
	ds_read_b128 v[66:69], v207 offset:0
	ds_read_b128 v[70:73], v207 offset:2048
	v_mfma_f32_16x16x32_bf16 v[34:37], v[216:219], v[74:77], v[34:37]
	v_mfma_f32_16x16x32_bf16 v[22:25], v[220:223], v[74:77], v[22:25]
	v_mfma_f32_16x16x32_bf16 v[18:21], v[224:227], v[74:77], v[18:21]
	v_mfma_f32_16x16x32_bf16 v[62:65], v[228:231], v[74:77], v[62:65]
	ds_read_b128 v[74:77], v207 offset:4096
	v_mfma_f32_16x16x32_bf16 v[58:61], v[216:219], v[78:81], v[58:61]
	v_mfma_f32_16x16x32_bf16 v[54:57], v[220:223], v[78:81], v[54:57]
	v_mfma_f32_16x16x32_bf16 v[50:53], v[224:227], v[78:81], v[50:53]
	v_mfma_f32_16x16x32_bf16 v[2:5], v[228:231], v[78:81], v[2:5]
	ds_read_b128 v[78:81], v207 offset:6144
	ds_read_b128 v[216:219], v91 offset:0
	ds_read_b128 v[220:223], v91 offset:2048
	ds_read_b128 v[224:227], v91 offset:4096
	ds_read_b128 v[228:231], v91 offset:6144
	s_waitcnt lgkmcnt(7)
	v_mfma_f32_16x16x32_bf16 v[6:9], v[82:85], v[66:69], v[6:9]
	v_mfma_f32_16x16x32_bf16 v[30:33], v[86:89], v[66:69], v[30:33]
	v_mfma_f32_16x16x32_bf16 v[38:41], v[208:211], v[66:69], v[38:41]
	v_mfma_f32_16x16x32_bf16 v[42:45], v[212:215], v[66:69], v[42:45]
	ds_read_b128 v[66:69], v119 offset:0
	s_waitcnt lgkmcnt(7)
	v_mfma_f32_16x16x32_bf16 v[46:49], v[82:85], v[70:73], v[46:49]
	v_mfma_f32_16x16x32_bf16 v[26:29], v[86:89], v[70:73], v[26:29]
	v_mfma_f32_16x16x32_bf16 v[14:17], v[208:211], v[70:73], v[14:17]
	v_mfma_f32_16x16x32_bf16 v[10:13], v[212:215], v[70:73], v[10:13]
	ds_read_b128 v[70:73], v119 offset:2048
	s_waitcnt lgkmcnt(7)
	v_mfma_f32_16x16x32_bf16 v[34:37], v[82:85], v[74:77], v[34:37]
	v_mfma_f32_16x16x32_bf16 v[22:25], v[86:89], v[74:77], v[22:25]
	v_mfma_f32_16x16x32_bf16 v[18:21], v[208:211], v[74:77], v[18:21]
	v_mfma_f32_16x16x32_bf16 v[62:65], v[212:215], v[74:77], v[62:65]
	ds_read_b128 v[74:77], v119 offset:4096
	s_waitcnt lgkmcnt(7)
	v_mfma_f32_16x16x32_bf16 v[58:61], v[82:85], v[78:81], v[58:61]
	v_mfma_f32_16x16x32_bf16 v[54:57], v[86:89], v[78:81], v[54:57]
	v_mfma_f32_16x16x32_bf16 v[50:53], v[208:211], v[78:81], v[50:53]
	v_mfma_f32_16x16x32_bf16 v[2:5], v[212:215], v[78:81], v[2:5]
	ds_read_b128 v[78:81], v119 offset:6144
	s_waitcnt lgkmcnt(3)
	v_mfma_f32_16x16x32_bf16 v[6:9], v[216:219], v[66:69], v[6:9]
	v_mfma_f32_16x16x32_bf16 v[30:33], v[220:223], v[66:69], v[30:33]
	v_mfma_f32_16x16x32_bf16 v[38:41], v[224:227], v[66:69], v[38:41]
	v_mfma_f32_16x16x32_bf16 v[42:45], v[228:231], v[66:69], v[42:45]
	s_waitcnt lgkmcnt(2)
	v_mfma_f32_16x16x32_bf16 v[46:49], v[216:219], v[70:73], v[46:49]
	v_mfma_f32_16x16x32_bf16 v[26:29], v[220:223], v[70:73], v[26:29]
	v_mfma_f32_16x16x32_bf16 v[14:17], v[224:227], v[70:73], v[14:17]
	v_mfma_f32_16x16x32_bf16 v[10:13], v[228:231], v[70:73], v[10:13]
	s_waitcnt vmcnt(6)
	s_waitcnt lgkmcnt(0)
	s_barrier
	s_add_i32 m0, s67, 0x0
	s_nop 0
	global_load_lds_dwordx4 v188, s[80:81]
	s_add_i32 m0, s67, 0x2000
	s_nop 0
	global_load_lds_dwordx4 v189, s[80:81]
	s_add_i32 m0, s67, 0x4000
	s_nop 0
	global_load_lds_dwordx4 v190, s[80:81]
	s_add_i32 m0, s67, 0x6000
	s_nop 0
	global_load_lds_dwordx4 v191, s[80:81]
	s_add_i32 m0, s67, 0x18000
	s_nop 0
	global_load_lds_dwordx4 v205, s[96:97]
	s_add_i32 m0, s67, 0x1a000
	s_nop 0
	global_load_lds_dwordx4 v206, s[96:97]
	s_add_u32 s80, s80, 0x80
	s_addc_u32 s81, s81, 0
	s_add_u32 s96, s96, 0x80
	s_addc_u32 s97, s97, 0
	ds_read_b128 v[82:85], v90 offset:16384
	ds_read_b128 v[86:89], v90 offset:18432
	ds_read_b128 v[208:211], v90 offset:20480
	ds_read_b128 v[212:215], v90 offset:22528
	ds_read_b128 v[66:69], v207 offset:32768
	ds_read_b128 v[70:73], v207 offset:34816
	v_mfma_f32_16x16x32_bf16 v[34:37], v[216:219], v[74:77], v[34:37]
	v_mfma_f32_16x16x32_bf16 v[22:25], v[220:223], v[74:77], v[22:25]
	v_mfma_f32_16x16x32_bf16 v[18:21], v[224:227], v[74:77], v[18:21]
	v_mfma_f32_16x16x32_bf16 v[62:65], v[228:231], v[74:77], v[62:65]
	ds_read_b128 v[74:77], v207 offset:36864
	v_mfma_f32_16x16x32_bf16 v[58:61], v[216:219], v[78:81], v[58:61]
	v_mfma_f32_16x16x32_bf16 v[54:57], v[220:223], v[78:81], v[54:57]
	v_mfma_f32_16x16x32_bf16 v[50:53], v[224:227], v[78:81], v[50:53]
	v_mfma_f32_16x16x32_bf16 v[2:5], v[228:231], v[78:81], v[2:5]
	ds_read_b128 v[78:81], v207 offset:38912
	ds_read_b128 v[216:219], v91 offset:16384
	ds_read_b128 v[220:223], v91 offset:18432
	ds_read_b128 v[224:227], v91 offset:20480
	ds_read_b128 v[228:231], v91 offset:22528
	s_waitcnt lgkmcnt(7)
	v_mfma_f32_16x16x32_bf16 v[6:9], v[82:85], v[66:69], v[6:9]
	v_mfma_f32_16x16x32_bf16 v[30:33], v[86:89], v[66:69], v[30:33]
	v_mfma_f32_16x16x32_bf16 v[38:41], v[208:211], v[66:69], v[38:41]
	v_mfma_f32_16x16x32_bf16 v[42:45], v[212:215], v[66:69], v[42:45]
	ds_read_b128 v[66:69], v119 offset:32768
	s_waitcnt lgkmcnt(7)
	v_mfma_f32_16x16x32_bf16 v[46:49], v[82:85], v[70:73], v[46:49]
	v_mfma_f32_16x16x32_bf16 v[26:29], v[86:89], v[70:73], v[26:29]
	v_mfma_f32_16x16x32_bf16 v[14:17], v[208:211], v[70:73], v[14:17]
	v_mfma_f32_16x16x32_bf16 v[10:13], v[212:215], v[70:73], v[10:13]
	ds_read_b128 v[70:73], v119 offset:34816
	s_waitcnt lgkmcnt(7)
	v_mfma_f32_16x16x32_bf16 v[34:37], v[82:85], v[74:77], v[34:37]
	v_mfma_f32_16x16x32_bf16 v[22:25], v[86:89], v[74:77], v[22:25]
	v_mfma_f32_16x16x32_bf16 v[18:21], v[208:211], v[74:77], v[18:21]
	v_mfma_f32_16x16x32_bf16 v[62:65], v[212:215], v[74:77], v[62:65]
	ds_read_b128 v[74:77], v119 offset:36864
	s_waitcnt lgkmcnt(7)
	v_mfma_f32_16x16x32_bf16 v[58:61], v[82:85], v[78:81], v[58:61]
	v_mfma_f32_16x16x32_bf16 v[54:57], v[86:89], v[78:81], v[54:57]
	v_mfma_f32_16x16x32_bf16 v[50:53], v[208:211], v[78:81], v[50:53]
	v_mfma_f32_16x16x32_bf16 v[2:5], v[212:215], v[78:81], v[2:5]
	ds_read_b128 v[78:81], v119 offset:38912
	s_waitcnt lgkmcnt(3)
	v_mfma_f32_16x16x32_bf16 v[6:9], v[216:219], v[66:69], v[6:9]
	v_mfma_f32_16x16x32_bf16 v[30:33], v[220:223], v[66:69], v[30:33]
	v_mfma_f32_16x16x32_bf16 v[38:41], v[224:227], v[66:69], v[38:41]
	v_mfma_f32_16x16x32_bf16 v[42:45], v[228:231], v[66:69], v[42:45]
	s_waitcnt lgkmcnt(2)
	v_mfma_f32_16x16x32_bf16 v[46:49], v[216:219], v[70:73], v[46:49]
	v_mfma_f32_16x16x32_bf16 v[26:29], v[220:223], v[70:73], v[26:29]
	v_mfma_f32_16x16x32_bf16 v[14:17], v[224:227], v[70:73], v[14:17]
	v_mfma_f32_16x16x32_bf16 v[10:13], v[228:231], v[70:73], v[10:13]
	s_waitcnt vmcnt(6)
	s_waitcnt lgkmcnt(0)
	s_barrier
	s_add_i32 m0, s67, 0x8000
	s_nop 0
	global_load_lds_dwordx4 v188, s[80:81]
	s_add_i32 m0, s67, 0xa000
	s_nop 0
	global_load_lds_dwordx4 v189, s[80:81]
	s_add_i32 m0, s67, 0xc000
	s_nop 0
	global_load_lds_dwordx4 v190, s[80:81]
	s_add_i32 m0, s67, 0xe000
	s_nop 0
	global_load_lds_dwordx4 v191, s[80:81]
	s_add_i32 m0, s67, 0x1c000
	s_nop 0
	global_load_lds_dwordx4 v205, s[96:97]
	s_add_i32 m0, s67, 0x1e000
	s_nop 0
	global_load_lds_dwordx4 v206, s[96:97]
	s_add_u32 s80, s80, 0x80
	s_addc_u32 s81, s81, 0
	s_add_u32 s96, s96, 0x80
	s_addc_u32 s97, s97, 0
	s_movk_i32 s10, 0x800
	s_mov_b32 s11, 0
	v_lshl_add_u64 v[248:249], v[128:129], 0, s[10:11]
	global_load_dwordx2 v[232:233], v[248:249], off
	global_load_dwordx2 v[234:235], v[248:249], off offset:32
	v_lshl_add_u64 v[248:249], v[132:133], 0, s[10:11]
	global_load_dwordx2 v[236:237], v[248:249], off
	global_load_dwordx2 v[238:239], v[248:249], off offset:32
	v_lshl_add_u64 v[248:249], v[152:153], 0, s[10:11]
	global_load_dwordx2 v[240:241], v[248:249], off
	global_load_dwordx2 v[242:243], v[248:249], off offset:32
	v_lshl_add_u64 v[248:249], v[154:155], 0, s[10:11]
	global_load_dwordx2 v[244:245], v[248:249], off
	global_load_dwordx2 v[246:247], v[248:249], off offset:32
	ds_read_b128 v[82:85], v90 offset:33792
	ds_read_b128 v[86:89], v90 offset:35840
	ds_read_b128 v[208:211], v90 offset:37888
	ds_read_b128 v[212:215], v90 offset:39936
	ds_read_b128 v[66:69], v0 offset:0
	ds_read_b128 v[70:73], v0 offset:2048
	v_mfma_f32_16x16x32_bf16 v[34:37], v[216:219], v[74:77], v[34:37]
	v_mfma_f32_16x16x32_bf16 v[22:25], v[220:223], v[74:77], v[22:25]
	v_mfma_f32_16x16x32_bf16 v[18:21], v[224:227], v[74:77], v[18:21]
	v_mfma_f32_16x16x32_bf16 v[62:65], v[228:231], v[74:77], v[62:65]
	ds_read_b128 v[74:77], v0 offset:4096
	v_mfma_f32_16x16x32_bf16 v[58:61], v[216:219], v[78:81], v[58:61]
	v_mfma_f32_16x16x32_bf16 v[54:57], v[220:223], v[78:81], v[54:57]
	v_mfma_f32_16x16x32_bf16 v[50:53], v[224:227], v[78:81], v[50:53]
	v_mfma_f32_16x16x32_bf16 v[2:5], v[228:231], v[78:81], v[2:5]
	ds_read_b128 v[78:81], v0 offset:6144
	ds_read_b128 v[216:219], v91 offset:33792
	ds_read_b128 v[220:223], v91 offset:35840
	ds_read_b128 v[224:227], v91 offset:37888
	ds_read_b128 v[228:231], v91 offset:39936
	s_waitcnt lgkmcnt(7)
	v_mfma_f32_16x16x32_bf16 v[6:9], v[82:85], v[66:69], v[6:9]
	v_mfma_f32_16x16x32_bf16 v[30:33], v[86:89], v[66:69], v[30:33]
	v_mfma_f32_16x16x32_bf16 v[38:41], v[208:211], v[66:69], v[38:41]
	v_mfma_f32_16x16x32_bf16 v[42:45], v[212:215], v[66:69], v[42:45]
	ds_read_b128 v[66:69], v255 offset:0
	s_waitcnt lgkmcnt(7)
	v_mfma_f32_16x16x32_bf16 v[46:49], v[82:85], v[70:73], v[46:49]
	v_mfma_f32_16x16x32_bf16 v[26:29], v[86:89], v[70:73], v[26:29]
	v_mfma_f32_16x16x32_bf16 v[14:17], v[208:211], v[70:73], v[14:17]
	v_mfma_f32_16x16x32_bf16 v[10:13], v[212:215], v[70:73], v[10:13]
	ds_read_b128 v[70:73], v255 offset:2048
	s_waitcnt lgkmcnt(7)
	v_mfma_f32_16x16x32_bf16 v[34:37], v[82:85], v[74:77], v[34:37]
	v_mfma_f32_16x16x32_bf16 v[22:25], v[86:89], v[74:77], v[22:25]
	v_mfma_f32_16x16x32_bf16 v[18:21], v[208:211], v[74:77], v[18:21]
	v_mfma_f32_16x16x32_bf16 v[62:65], v[212:215], v[74:77], v[62:65]
	ds_read_b128 v[74:77], v255 offset:4096
	s_waitcnt lgkmcnt(7)
	v_mfma_f32_16x16x32_bf16 v[58:61], v[82:85], v[78:81], v[58:61]
	v_mfma_f32_16x16x32_bf16 v[54:57], v[86:89], v[78:81], v[54:57]
	v_mfma_f32_16x16x32_bf16 v[50:53], v[208:211], v[78:81], v[50:53]
	v_mfma_f32_16x16x32_bf16 v[2:5], v[212:215], v[78:81], v[2:5]
	ds_read_b128 v[78:81], v255 offset:6144
	s_waitcnt lgkmcnt(3)
	v_mfma_f32_16x16x32_bf16 v[6:9], v[216:219], v[66:69], v[6:9]
	v_mfma_f32_16x16x32_bf16 v[30:33], v[220:223], v[66:69], v[30:33]
	v_mfma_f32_16x16x32_bf16 v[38:41], v[224:227], v[66:69], v[38:41]
	v_mfma_f32_16x16x32_bf16 v[42:45], v[228:231], v[66:69], v[42:45]
	s_waitcnt lgkmcnt(2)
	v_mfma_f32_16x16x32_bf16 v[46:49], v[216:219], v[70:73], v[46:49]
	v_mfma_f32_16x16x32_bf16 v[26:29], v[220:223], v[70:73], v[26:29]
	v_mfma_f32_16x16x32_bf16 v[14:17], v[224:227], v[70:73], v[14:17]
	v_mfma_f32_16x16x32_bf16 v[10:13], v[228:231], v[70:73], v[10:13]
	s_waitcnt vmcnt(14)
	s_waitcnt lgkmcnt(0)
	s_barrier
	s_add_i32 m0, s67, 0x10000
	s_nop 0
	global_load_lds_dwordx4 v188, s[80:81]
	s_add_i32 m0, s67, 0x12000
	s_nop 0
	global_load_lds_dwordx4 v189, s[80:81]
	s_add_i32 m0, s67, 0x14000
	s_nop 0
	global_load_lds_dwordx4 v190, s[80:81]
	s_add_i32 m0, s67, 0x16000
	s_nop 0
	global_load_lds_dwordx4 v191, s[80:81]
	s_add_i32 m0, s67, 0x20400
	s_nop 0
	global_load_lds_dwordx4 v205, s[96:97]
	s_add_i32 m0, s67, 0x22400
	s_nop 0
	global_load_lds_dwordx4 v206, s[96:97]
	s_add_u32 s80, s80, 0x880
	s_addc_u32 s81, s81, 0
	s_add_u32 s96, s96, 0xffc80
	s_addc_u32 s97, s97, 0
	ds_read_b128 v[82:85], v90 offset:0
	ds_read_b128 v[86:89], v90 offset:2048
	ds_read_b128 v[208:211], v90 offset:4096
	ds_read_b128 v[212:215], v90 offset:6144
	ds_read_b128 v[66:69], v207 offset:0
	ds_read_b128 v[70:73], v207 offset:2048
	v_mfma_f32_16x16x32_bf16 v[34:37], v[216:219], v[74:77], v[34:37]
	v_mfma_f32_16x16x32_bf16 v[22:25], v[220:223], v[74:77], v[22:25]
	v_mfma_f32_16x16x32_bf16 v[18:21], v[224:227], v[74:77], v[18:21]
	v_mfma_f32_16x16x32_bf16 v[62:65], v[228:231], v[74:77], v[62:65]
	ds_read_b128 v[74:77], v207 offset:4096
	v_mfma_f32_16x16x32_bf16 v[58:61], v[216:219], v[78:81], v[58:61]
	v_mfma_f32_16x16x32_bf16 v[54:57], v[220:223], v[78:81], v[54:57]
	v_mfma_f32_16x16x32_bf16 v[50:53], v[224:227], v[78:81], v[50:53]
	v_mfma_f32_16x16x32_bf16 v[2:5], v[228:231], v[78:81], v[2:5]
	ds_read_b128 v[78:81], v207 offset:6144
	ds_read_b128 v[216:219], v91 offset:0
	ds_read_b128 v[220:223], v91 offset:2048
	ds_read_b128 v[224:227], v91 offset:4096
	ds_read_b128 v[228:231], v91 offset:6144
	s_waitcnt lgkmcnt(7)
	v_mfma_f32_16x16x32_bf16 v[6:9], v[82:85], v[66:69], v[6:9]
	v_mfma_f32_16x16x32_bf16 v[30:33], v[86:89], v[66:69], v[30:33]
	v_mfma_f32_16x16x32_bf16 v[38:41], v[208:211], v[66:69], v[38:41]
	v_mfma_f32_16x16x32_bf16 v[42:45], v[212:215], v[66:69], v[42:45]
	ds_read_b128 v[66:69], v119 offset:0
	s_waitcnt lgkmcnt(7)
	v_mfma_f32_16x16x32_bf16 v[46:49], v[82:85], v[70:73], v[46:49]
	v_mfma_f32_16x16x32_bf16 v[26:29], v[86:89], v[70:73], v[26:29]
	v_mfma_f32_16x16x32_bf16 v[14:17], v[208:211], v[70:73], v[14:17]
	v_mfma_f32_16x16x32_bf16 v[10:13], v[212:215], v[70:73], v[10:13]
	ds_read_b128 v[70:73], v119 offset:2048
	s_waitcnt lgkmcnt(7)
	v_mfma_f32_16x16x32_bf16 v[34:37], v[82:85], v[74:77], v[34:37]
	v_mfma_f32_16x16x32_bf16 v[22:25], v[86:89], v[74:77], v[22:25]
	v_mfma_f32_16x16x32_bf16 v[18:21], v[208:211], v[74:77], v[18:21]
	v_mfma_f32_16x16x32_bf16 v[62:65], v[212:215], v[74:77], v[62:65]
	ds_read_b128 v[74:77], v119 offset:4096
	s_waitcnt lgkmcnt(7)
	v_mfma_f32_16x16x32_bf16 v[58:61], v[82:85], v[78:81], v[58:61]
	v_mfma_f32_16x16x32_bf16 v[54:57], v[86:89], v[78:81], v[54:57]
	v_mfma_f32_16x16x32_bf16 v[50:53], v[208:211], v[78:81], v[50:53]
	v_mfma_f32_16x16x32_bf16 v[2:5], v[212:215], v[78:81], v[2:5]
	ds_read_b128 v[78:81], v119 offset:6144
	s_waitcnt lgkmcnt(3)
	v_mfma_f32_16x16x32_bf16 v[6:9], v[216:219], v[66:69], v[6:9]
	v_mfma_f32_16x16x32_bf16 v[30:33], v[220:223], v[66:69], v[30:33]
	v_mfma_f32_16x16x32_bf16 v[38:41], v[224:227], v[66:69], v[38:41]
	v_mfma_f32_16x16x32_bf16 v[42:45], v[228:231], v[66:69], v[42:45]
	s_waitcnt lgkmcnt(2)
	v_mfma_f32_16x16x32_bf16 v[46:49], v[216:219], v[70:73], v[46:49]
	v_mfma_f32_16x16x32_bf16 v[26:29], v[220:223], v[70:73], v[26:29]
	v_mfma_f32_16x16x32_bf16 v[14:17], v[224:227], v[70:73], v[14:17]
	v_mfma_f32_16x16x32_bf16 v[10:13], v[228:231], v[70:73], v[10:13]
	s_waitcnt vmcnt(14)
	s_waitcnt lgkmcnt(0)
	s_barrier
	s_add_i32 m0, s67, 0x0
	s_nop 0
	global_load_lds_dwordx4 v188, s[80:81]
	s_add_i32 m0, s67, 0x2000
	s_nop 0
	global_load_lds_dwordx4 v189, s[80:81]
	s_add_i32 m0, s67, 0x4000
	s_nop 0
	global_load_lds_dwordx4 v190, s[80:81]
	s_add_i32 m0, s67, 0x6000
	s_nop 0
	global_load_lds_dwordx4 v191, s[80:81]
	s_add_i32 m0, s67, 0x18000
	s_nop 0
	global_load_lds_dwordx4 v205, s[96:97]
	s_add_i32 m0, s67, 0x1a000
	s_nop 0
	global_load_lds_dwordx4 v206, s[96:97]
	s_add_u32 s80, s80, 0x80
	s_addc_u32 s81, s81, 0
	s_add_u32 s96, s96, 0x80
	s_addc_u32 s97, s97, 0
	ds_read_b128 v[82:85], v90 offset:16384
	ds_read_b128 v[86:89], v90 offset:18432
	ds_read_b128 v[208:211], v90 offset:20480
	ds_read_b128 v[212:215], v90 offset:22528
	ds_read_b128 v[66:69], v207 offset:32768
	ds_read_b128 v[70:73], v207 offset:34816
	v_mfma_f32_16x16x32_bf16 v[34:37], v[216:219], v[74:77], v[34:37]
	v_mfma_f32_16x16x32_bf16 v[22:25], v[220:223], v[74:77], v[22:25]
	v_mfma_f32_16x16x32_bf16 v[18:21], v[224:227], v[74:77], v[18:21]
	v_mfma_f32_16x16x32_bf16 v[62:65], v[228:231], v[74:77], v[62:65]
	ds_read_b128 v[74:77], v207 offset:36864
	v_mfma_f32_16x16x32_bf16 v[58:61], v[216:219], v[78:81], v[58:61]
	v_mfma_f32_16x16x32_bf16 v[54:57], v[220:223], v[78:81], v[54:57]
	v_mfma_f32_16x16x32_bf16 v[50:53], v[224:227], v[78:81], v[50:53]
	v_mfma_f32_16x16x32_bf16 v[2:5], v[228:231], v[78:81], v[2:5]
	ds_read_b128 v[78:81], v207 offset:38912
	ds_read_b128 v[216:219], v91 offset:16384
	ds_read_b128 v[220:223], v91 offset:18432
	ds_read_b128 v[224:227], v91 offset:20480
	ds_read_b128 v[228:231], v91 offset:22528
	s_waitcnt lgkmcnt(7)
	v_mfma_f32_16x16x32_bf16 v[6:9], v[82:85], v[66:69], v[6:9]
	v_mfma_f32_16x16x32_bf16 v[30:33], v[86:89], v[66:69], v[30:33]
	v_mfma_f32_16x16x32_bf16 v[38:41], v[208:211], v[66:69], v[38:41]
	v_mfma_f32_16x16x32_bf16 v[42:45], v[212:215], v[66:69], v[42:45]
	ds_read_b128 v[66:69], v119 offset:32768
	s_waitcnt lgkmcnt(7)
	v_mfma_f32_16x16x32_bf16 v[46:49], v[82:85], v[70:73], v[46:49]
	v_mfma_f32_16x16x32_bf16 v[26:29], v[86:89], v[70:73], v[26:29]
	v_mfma_f32_16x16x32_bf16 v[14:17], v[208:211], v[70:73], v[14:17]
	v_mfma_f32_16x16x32_bf16 v[10:13], v[212:215], v[70:73], v[10:13]
	ds_read_b128 v[70:73], v119 offset:34816
	s_waitcnt lgkmcnt(7)
	v_mfma_f32_16x16x32_bf16 v[34:37], v[82:85], v[74:77], v[34:37]
	v_mfma_f32_16x16x32_bf16 v[22:25], v[86:89], v[74:77], v[22:25]
	v_mfma_f32_16x16x32_bf16 v[18:21], v[208:211], v[74:77], v[18:21]
	v_mfma_f32_16x16x32_bf16 v[62:65], v[212:215], v[74:77], v[62:65]
	ds_read_b128 v[74:77], v119 offset:36864
	s_waitcnt lgkmcnt(7)
	v_mfma_f32_16x16x32_bf16 v[58:61], v[82:85], v[78:81], v[58:61]
	v_mfma_f32_16x16x32_bf16 v[54:57], v[86:89], v[78:81], v[54:57]
	v_mfma_f32_16x16x32_bf16 v[50:53], v[208:211], v[78:81], v[50:53]
	v_mfma_f32_16x16x32_bf16 v[2:5], v[212:215], v[78:81], v[2:5]
	ds_read_b128 v[78:81], v119 offset:38912
	s_waitcnt lgkmcnt(3)
	v_mfma_f32_16x16x32_bf16 v[6:9], v[216:219], v[66:69], v[6:9]
	v_mfma_f32_16x16x32_bf16 v[30:33], v[220:223], v[66:69], v[30:33]
	v_mfma_f32_16x16x32_bf16 v[38:41], v[224:227], v[66:69], v[38:41]
	v_mfma_f32_16x16x32_bf16 v[42:45], v[228:231], v[66:69], v[42:45]
	s_waitcnt lgkmcnt(2)
	v_mfma_f32_16x16x32_bf16 v[46:49], v[216:219], v[70:73], v[46:49]
	v_mfma_f32_16x16x32_bf16 v[26:29], v[220:223], v[70:73], v[26:29]
	v_mfma_f32_16x16x32_bf16 v[14:17], v[224:227], v[70:73], v[14:17]
	v_mfma_f32_16x16x32_bf16 v[10:13], v[228:231], v[70:73], v[10:13]
	s_waitcnt vmcnt(6)
	s_waitcnt lgkmcnt(0)
	s_barrier
	s_add_i32 m0, s67, 0x8000
	s_nop 0
	global_load_lds_dwordx4 v188, s[80:81]
	s_add_i32 m0, s67, 0xa000
	s_nop 0
	global_load_lds_dwordx4 v189, s[80:81]
	s_add_i32 m0, s67, 0xc000
	s_nop 0
	global_load_lds_dwordx4 v190, s[80:81]
	s_add_i32 m0, s67, 0xe000
	s_nop 0
	global_load_lds_dwordx4 v191, s[80:81]
	s_add_i32 m0, s67, 0x1c000
	s_nop 0
	global_load_lds_dwordx4 v205, s[96:97]
	s_add_i32 m0, s67, 0x1e000
	s_nop 0
	global_load_lds_dwordx4 v206, s[96:97]
	s_add_u32 s80, s80, 0x80
	s_addc_u32 s81, s81, 0
	s_add_u32 s96, s96, 0x80
	s_addc_u32 s97, s97, 0
	ds_read_b128 v[82:85], v90 offset:33792
	ds_read_b128 v[86:89], v90 offset:35840
	ds_read_b128 v[208:211], v90 offset:37888
	ds_read_b128 v[212:215], v90 offset:39936
	ds_read_b128 v[66:69], v0 offset:0
	ds_read_b128 v[70:73], v0 offset:2048
	v_mfma_f32_16x16x32_bf16 v[34:37], v[216:219], v[74:77], v[34:37]
	v_mfma_f32_16x16x32_bf16 v[22:25], v[220:223], v[74:77], v[22:25]
	v_mfma_f32_16x16x32_bf16 v[18:21], v[224:227], v[74:77], v[18:21]
	v_mfma_f32_16x16x32_bf16 v[62:65], v[228:231], v[74:77], v[62:65]
	ds_read_b128 v[74:77], v0 offset:4096
	v_mfma_f32_16x16x32_bf16 v[58:61], v[216:219], v[78:81], v[58:61]
	v_mfma_f32_16x16x32_bf16 v[54:57], v[220:223], v[78:81], v[54:57]
	v_mfma_f32_16x16x32_bf16 v[50:53], v[224:227], v[78:81], v[50:53]
	v_mfma_f32_16x16x32_bf16 v[2:5], v[228:231], v[78:81], v[2:5]
	ds_read_b128 v[78:81], v0 offset:6144
	ds_read_b128 v[216:219], v91 offset:33792
	ds_read_b128 v[220:223], v91 offset:35840
	ds_read_b128 v[224:227], v91 offset:37888
	ds_read_b128 v[228:231], v91 offset:39936
	s_waitcnt lgkmcnt(7)
	v_mfma_f32_16x16x32_bf16 v[6:9], v[82:85], v[66:69], v[6:9]
	v_mfma_f32_16x16x32_bf16 v[30:33], v[86:89], v[66:69], v[30:33]
	v_mfma_f32_16x16x32_bf16 v[38:41], v[208:211], v[66:69], v[38:41]
	v_mfma_f32_16x16x32_bf16 v[42:45], v[212:215], v[66:69], v[42:45]
	ds_read_b128 v[66:69], v255 offset:0
	s_waitcnt lgkmcnt(7)
	v_mfma_f32_16x16x32_bf16 v[46:49], v[82:85], v[70:73], v[46:49]
	v_mfma_f32_16x16x32_bf16 v[26:29], v[86:89], v[70:73], v[26:29]
	v_mfma_f32_16x16x32_bf16 v[14:17], v[208:211], v[70:73], v[14:17]
	v_mfma_f32_16x16x32_bf16 v[10:13], v[212:215], v[70:73], v[10:13]
	ds_read_b128 v[70:73], v255 offset:2048
	s_waitcnt lgkmcnt(7)
	v_mfma_f32_16x16x32_bf16 v[34:37], v[82:85], v[74:77], v[34:37]
	v_mfma_f32_16x16x32_bf16 v[22:25], v[86:89], v[74:77], v[22:25]
	v_mfma_f32_16x16x32_bf16 v[18:21], v[208:211], v[74:77], v[18:21]
	v_mfma_f32_16x16x32_bf16 v[62:65], v[212:215], v[74:77], v[62:65]
	ds_read_b128 v[74:77], v255 offset:4096
	s_waitcnt lgkmcnt(7)
	v_mfma_f32_16x16x32_bf16 v[58:61], v[82:85], v[78:81], v[58:61]
	v_mfma_f32_16x16x32_bf16 v[54:57], v[86:89], v[78:81], v[54:57]
	v_mfma_f32_16x16x32_bf16 v[50:53], v[208:211], v[78:81], v[50:53]
	v_mfma_f32_16x16x32_bf16 v[2:5], v[212:215], v[78:81], v[2:5]
	ds_read_b128 v[78:81], v255 offset:6144
	s_waitcnt lgkmcnt(3)
	v_mfma_f32_16x16x32_bf16 v[6:9], v[216:219], v[66:69], v[6:9]
	s_waitcnt vmcnt(18)
	v_mfma_f32_16x16x32_bf16 v[30:33], v[220:223], v[66:69], v[30:33]
	v_mfma_f32_16x16x32_bf16 v[38:41], v[224:227], v[66:69], v[38:41]
	v_mfma_f32_16x16x32_bf16 v[42:45], v[228:231], v[66:69], v[42:45]
	v_cvt_f32_ubyte0_e32 v248, v232
	v_cvt_f32_ubyte1_e32 v249, v232
	v_cvt_f32_ubyte2_e32 v250, v232
	v_cvt_f32_ubyte3_e32 v251, v232
	v_mul_f32_e32 v248, s34, v248
	v_mul_f32_e32 v249, s34, v249
	v_mul_f32_e32 v250, s34, v250
	v_mul_f32_e32 v251, s34, v251
	v_fma_f32 v184, v6, v248, v184
	v_fma_f32 v185, v7, v249, v185
	v_fma_f32 v186, v8, v250, v186
	v_fma_f32 v187, v9, v251, v187
	s_waitcnt lgkmcnt(2)
	v_mfma_f32_16x16x32_bf16 v[46:49], v[216:219], v[70:73], v[46:49]
	v_cvt_f32_ubyte0_e32 v248, v233
	v_cvt_f32_ubyte1_e32 v249, v233
	v_cvt_f32_ubyte2_e32 v250, v233
	v_cvt_f32_ubyte3_e32 v251, v233
	v_mul_f32_e32 v248, s34, v248
	v_mul_f32_e32 v249, s34, v249
	v_mul_f32_e32 v250, s34, v250
	v_mul_f32_e32 v251, s34, v251
	v_fma_f32 v180, v30, v248, v180
	v_fma_f32 v181, v31, v249, v181
	v_fma_f32 v182, v32, v250, v182
	v_fma_f32 v183, v33, v251, v183
	v_mfma_f32_16x16x32_bf16 v[26:29], v[220:223], v[70:73], v[26:29]
	v_cvt_f32_ubyte0_e32 v248, v234
	v_cvt_f32_ubyte1_e32 v249, v234
	v_cvt_f32_ubyte2_e32 v250, v234
	v_cvt_f32_ubyte3_e32 v251, v234
	v_mul_f32_e32 v248, s34, v248
	v_mul_f32_e32 v249, s34, v249
	v_mul_f32_e32 v250, s34, v250
	v_mul_f32_e32 v251, s34, v251
	v_fma_f32 v176, v38, v248, v176
	v_fma_f32 v177, v39, v249, v177
	v_fma_f32 v178, v40, v250, v178
	v_fma_f32 v179, v41, v251, v179
	v_mfma_f32_16x16x32_bf16 v[14:17], v[224:227], v[70:73], v[14:17]
	v_cvt_f32_ubyte0_e32 v248, v235
	v_cvt_f32_ubyte1_e32 v249, v235
	v_cvt_f32_ubyte2_e32 v250, v235
	v_cvt_f32_ubyte3_e32 v251, v235
	v_mul_f32_e32 v248, s34, v248
	v_mul_f32_e32 v249, s34, v249
	v_mul_f32_e32 v250, s34, v250
	v_mul_f32_e32 v251, s34, v251
	v_fma_f32 v172, v42, v248, v172
	v_fma_f32 v173, v43, v249, v173
	v_fma_f32 v174, v44, v250, v174
	v_fma_f32 v175, v45, v251, v175
	v_mfma_f32_16x16x32_bf16 v[10:13], v[228:231], v[70:73], v[10:13]
	v_cvt_f32_ubyte0_e32 v248, v236
	v_cvt_f32_ubyte1_e32 v249, v236
	v_cvt_f32_ubyte2_e32 v250, v236
	v_cvt_f32_ubyte3_e32 v251, v236
	v_mul_f32_e32 v248, s34, v248
	v_mul_f32_e32 v249, s34, v249
	v_mul_f32_e32 v250, s34, v250
	v_mul_f32_e32 v251, s34, v251
	v_fma_f32 v168, v46, v248, v168
	v_fma_f32 v169, v47, v249, v169
	v_fma_f32 v170, v48, v250, v170
	v_fma_f32 v171, v49, v251, v171
	s_waitcnt vmcnt(6)
	s_waitcnt lgkmcnt(0)
	s_barrier
	s_add_i32 m0, s67, 0x10000
	s_nop 0
	global_load_lds_dwordx4 v188, s[80:81]
	s_add_i32 m0, s67, 0x12000
	s_nop 0
	global_load_lds_dwordx4 v189, s[80:81]
	s_add_i32 m0, s67, 0x14000
	s_nop 0
	global_load_lds_dwordx4 v190, s[80:81]
	s_add_i32 m0, s67, 0x16000
	s_nop 0
	global_load_lds_dwordx4 v191, s[80:81]
	s_add_i32 m0, s67, 0x20400
	s_nop 0
	global_load_lds_dwordx4 v205, s[96:97]
	s_add_i32 m0, s67, 0x22400
	s_nop 0
	global_load_lds_dwordx4 v206, s[96:97]
	s_add_u32 s80, s80, 0x80
	s_addc_u32 s81, s81, 0
	s_add_u32 s96, s96, 0x80
	s_addc_u32 s97, s97, 0
	ds_read_b128 v[82:85], v90 offset:0
	ds_read_b128 v[86:89], v90 offset:2048
	ds_read_b128 v[208:211], v90 offset:4096
	ds_read_b128 v[212:215], v90 offset:6144
	ds_read_b128 v[66:69], v207 offset:0
	ds_read_b128 v[70:73], v207 offset:2048
	v_mfma_f32_16x16x32_bf16 v[34:37], v[216:219], v[74:77], v[34:37]
	v_cvt_f32_ubyte0_e32 v248, v237
	v_cvt_f32_ubyte1_e32 v249, v237
	v_cvt_f32_ubyte2_e32 v250, v237
	v_cvt_f32_ubyte3_e32 v251, v237
	v_mul_f32_e32 v248, s34, v248
	v_mul_f32_e32 v249, s34, v249
	v_mul_f32_e32 v250, s34, v250
	v_mul_f32_e32 v251, s34, v251
	v_fma_f32 v164, v26, v248, v164
	v_fma_f32 v165, v27, v249, v165
	v_fma_f32 v166, v28, v250, v166
	v_fma_f32 v167, v29, v251, v167
	v_mfma_f32_16x16x32_bf16 v[22:25], v[220:223], v[74:77], v[22:25]
	v_cvt_f32_ubyte0_e32 v248, v238
	v_cvt_f32_ubyte1_e32 v249, v238
	v_cvt_f32_ubyte2_e32 v250, v238
	v_cvt_f32_ubyte3_e32 v251, v238
	v_mul_f32_e32 v248, s34, v248
	v_mul_f32_e32 v249, s34, v249
	v_mul_f32_e32 v250, s34, v250
	v_mul_f32_e32 v251, s34, v251
	v_fma_f32 v160, v14, v248, v160
	v_fma_f32 v161, v15, v249, v161
	v_fma_f32 v162, v16, v250, v162
	v_fma_f32 v163, v17, v251, v163
	v_mfma_f32_16x16x32_bf16 v[18:21], v[224:227], v[74:77], v[18:21]
	v_cvt_f32_ubyte0_e32 v248, v239
	v_cvt_f32_ubyte1_e32 v249, v239
	v_cvt_f32_ubyte2_e32 v250, v239
	v_cvt_f32_ubyte3_e32 v251, v239
	v_mul_f32_e32 v248, s34, v248
	v_mul_f32_e32 v249, s34, v249
	v_mul_f32_e32 v250, s34, v250
	v_mul_f32_e32 v251, s34, v251
	v_fma_f32 v156, v10, v248, v156
	v_fma_f32 v157, v11, v249, v157
	v_fma_f32 v158, v12, v250, v158
	v_fma_f32 v159, v13, v251, v159
	v_mfma_f32_16x16x32_bf16 v[62:65], v[228:231], v[74:77], v[62:65]
	v_cvt_f32_ubyte0_e32 v248, v240
	v_cvt_f32_ubyte1_e32 v249, v240
	v_cvt_f32_ubyte2_e32 v250, v240
	v_cvt_f32_ubyte3_e32 v251, v240
	v_mul_f32_e32 v248, s34, v248
	v_mul_f32_e32 v249, s34, v249
	v_mul_f32_e32 v250, s34, v250
	v_mul_f32_e32 v251, s34, v251
	v_fma_f32 v136, v34, v248, v136
	v_fma_f32 v137, v35, v249, v137
	v_fma_f32 v150, v36, v250, v150
	v_fma_f32 v151, v37, v251, v151
	ds_read_b128 v[74:77], v207 offset:4096
	v_mfma_f32_16x16x32_bf16 v[58:61], v[216:219], v[78:81], v[58:61]
	v_cvt_f32_ubyte0_e32 v248, v241
	v_cvt_f32_ubyte1_e32 v249, v241
	v_cvt_f32_ubyte2_e32 v250, v241
	v_cvt_f32_ubyte3_e32 v251, v241
	v_mul_f32_e32 v248, s34, v248
	v_mul_f32_e32 v249, s34, v249
	v_mul_f32_e32 v250, s34, v250
	v_mul_f32_e32 v251, s34, v251
	v_fma_f32 v130, v22, v248, v130
	v_fma_f32 v131, v23, v249, v131
	v_fma_f32 v134, v24, v250, v134
	v_fma_f32 v135, v25, v251, v135
	v_mfma_f32_16x16x32_bf16 v[54:57], v[220:223], v[78:81], v[54:57]
	v_cvt_f32_ubyte0_e32 v248, v242
	v_cvt_f32_ubyte1_e32 v249, v242
	v_cvt_f32_ubyte2_e32 v250, v242
	v_cvt_f32_ubyte3_e32 v251, v242
	v_mul_f32_e32 v248, s34, v248
	v_mul_f32_e32 v249, s34, v249
	v_mul_f32_e32 v250, s34, v250
	v_mul_f32_e32 v251, s34, v251
	v_fma_f32 v124, v18, v248, v124
	v_fma_f32 v125, v19, v249, v125
	v_fma_f32 v126, v20, v250, v126
	v_fma_f32 v127, v21, v251, v127
	v_mfma_f32_16x16x32_bf16 v[50:53], v[224:227], v[78:81], v[50:53]
	v_cvt_f32_ubyte0_e32 v248, v243
	v_cvt_f32_ubyte1_e32 v249, v243
	v_cvt_f32_ubyte2_e32 v250, v243
	v_cvt_f32_ubyte3_e32 v251, v243
	v_mul_f32_e32 v248, s34, v248
	v_mul_f32_e32 v249, s34, v249
	v_mul_f32_e32 v250, s34, v250
	v_mul_f32_e32 v251, s34, v251
	v_fma_f32 v120, v62, v248, v120
	v_fma_f32 v121, v63, v249, v121
	v_fma_f32 v122, v64, v250, v122
	v_fma_f32 v123, v65, v251, v123
	v_mfma_f32_16x16x32_bf16 v[2:5], v[228:231], v[78:81], v[2:5]
	v_cvt_f32_ubyte0_e32 v248, v244
	v_cvt_f32_ubyte1_e32 v249, v244
	v_cvt_f32_ubyte2_e32 v250, v244
	v_cvt_f32_ubyte3_e32 v251, v244
	v_mul_f32_e32 v248, s34, v248
	v_mul_f32_e32 v249, s34, v249
	v_mul_f32_e32 v250, s34, v250
	v_mul_f32_e32 v251, s34, v251
	v_fma_f32 v114, v58, v248, v114
	v_fma_f32 v115, v59, v249, v115
	v_fma_f32 v116, v60, v250, v116
	v_fma_f32 v117, v61, v251, v117
	ds_read_b128 v[78:81], v207 offset:6144
	s_nop 7
	s_nop 3
	v_cvt_f32_ubyte0_e32 v248, v245
	v_cvt_f32_ubyte1_e32 v249, v245
	v_cvt_f32_ubyte2_e32 v250, v245
	v_cvt_f32_ubyte3_e32 v251, v245
	v_mul_f32_e32 v248, s34, v248
	v_mul_f32_e32 v249, s34, v249
	v_mul_f32_e32 v250, s34, v250
	v_mul_f32_e32 v251, s34, v251
	v_fma_f32 v106, v54, v248, v106
	v_fma_f32 v107, v55, v249, v107
	v_fma_f32 v108, v56, v250, v108
	v_fma_f32 v109, v57, v251, v109
	v_cvt_f32_ubyte0_e32 v248, v246
	v_cvt_f32_ubyte1_e32 v249, v246
	v_cvt_f32_ubyte2_e32 v250, v246
	v_cvt_f32_ubyte3_e32 v251, v246
	v_mul_f32_e32 v248, s34, v248
	v_mul_f32_e32 v249, s34, v249
	v_mul_f32_e32 v250, s34, v250
	v_mul_f32_e32 v251, s34, v251
	v_fma_f32 v100, v50, v248, v100
	v_fma_f32 v101, v51, v249, v101
	v_fma_f32 v102, v52, v250, v102
	v_fma_f32 v103, v53, v251, v103
	v_cvt_f32_ubyte0_e32 v248, v247
	v_cvt_f32_ubyte1_e32 v249, v247
	v_cvt_f32_ubyte2_e32 v250, v247
	v_cvt_f32_ubyte3_e32 v251, v247
	v_mul_f32_e32 v248, s34, v248
	v_mul_f32_e32 v249, s34, v249
	v_mul_f32_e32 v250, s34, v250
	v_mul_f32_e32 v251, s34, v251
	v_fma_f32 v96, v2, v248, v96
	v_fma_f32 v97, v3, v249, v97
	v_fma_f32 v98, v4, v250, v98
	v_fma_f32 v99, v5, v251, v99
	ds_read_b128 v[216:219], v91 offset:0
	ds_read_b128 v[220:223], v91 offset:2048
	ds_read_b128 v[224:227], v91 offset:4096
	ds_read_b128 v[228:231], v91 offset:6144
	s_waitcnt lgkmcnt(7)
	v_mfma_f32_16x16x32_bf16 v[6:9], v[82:85], v[66:69], 0
	v_mfma_f32_16x16x32_bf16 v[30:33], v[86:89], v[66:69], 0
	v_mfma_f32_16x16x32_bf16 v[38:41], v[208:211], v[66:69], 0
	v_mfma_f32_16x16x32_bf16 v[42:45], v[212:215], v[66:69], 0
	ds_read_b128 v[66:69], v119 offset:0
	s_waitcnt lgkmcnt(7)
	v_mfma_f32_16x16x32_bf16 v[46:49], v[82:85], v[70:73], 0
	v_mfma_f32_16x16x32_bf16 v[26:29], v[86:89], v[70:73], 0
	v_mfma_f32_16x16x32_bf16 v[14:17], v[208:211], v[70:73], 0
	v_mfma_f32_16x16x32_bf16 v[10:13], v[212:215], v[70:73], 0
	ds_read_b128 v[70:73], v119 offset:2048
	s_waitcnt lgkmcnt(7)
	v_mfma_f32_16x16x32_bf16 v[34:37], v[82:85], v[74:77], 0
	v_mfma_f32_16x16x32_bf16 v[22:25], v[86:89], v[74:77], 0
	v_mfma_f32_16x16x32_bf16 v[18:21], v[208:211], v[74:77], 0
	v_mfma_f32_16x16x32_bf16 v[62:65], v[212:215], v[74:77], 0
	ds_read_b128 v[74:77], v119 offset:4096
	s_waitcnt lgkmcnt(7)
	v_mfma_f32_16x16x32_bf16 v[58:61], v[82:85], v[78:81], 0
	v_mfma_f32_16x16x32_bf16 v[54:57], v[86:89], v[78:81], 0
	v_mfma_f32_16x16x32_bf16 v[50:53], v[208:211], v[78:81], 0
	v_mfma_f32_16x16x32_bf16 v[2:5], v[212:215], v[78:81], 0
	ds_read_b128 v[78:81], v119 offset:6144
	s_waitcnt lgkmcnt(3)
	v_mfma_f32_16x16x32_bf16 v[6:9], v[216:219], v[66:69], v[6:9]
	v_mfma_f32_16x16x32_bf16 v[30:33], v[220:223], v[66:69], v[30:33]
	v_mfma_f32_16x16x32_bf16 v[38:41], v[224:227], v[66:69], v[38:41]
	v_mfma_f32_16x16x32_bf16 v[42:45], v[228:231], v[66:69], v[42:45]
	s_waitcnt lgkmcnt(2)
	v_mfma_f32_16x16x32_bf16 v[46:49], v[216:219], v[70:73], v[46:49]
	v_mfma_f32_16x16x32_bf16 v[26:29], v[220:223], v[70:73], v[26:29]
	v_mfma_f32_16x16x32_bf16 v[14:17], v[224:227], v[70:73], v[14:17]
	v_mfma_f32_16x16x32_bf16 v[10:13], v[228:231], v[70:73], v[10:13]
	s_waitcnt vmcnt(6)
	s_waitcnt lgkmcnt(0)
	s_barrier
	s_add_i32 m0, s67, 0x0
	s_nop 0
	global_load_lds_dwordx4 v188, s[80:81]
	s_add_i32 m0, s67, 0x2000
	s_nop 0
	global_load_lds_dwordx4 v189, s[80:81]
	s_add_i32 m0, s67, 0x4000
	s_nop 0
	global_load_lds_dwordx4 v190, s[80:81]
	s_add_i32 m0, s67, 0x6000
	s_nop 0
	global_load_lds_dwordx4 v191, s[80:81]
	s_add_i32 m0, s67, 0x18000
	s_nop 0
	global_load_lds_dwordx4 v205, s[96:97]
	s_add_i32 m0, s67, 0x1a000
	s_nop 0
	global_load_lds_dwordx4 v206, s[96:97]
	s_add_u32 s80, s80, 0x80
	s_addc_u32 s81, s81, 0
	s_add_u32 s96, s96, 0x80
	s_addc_u32 s97, s97, 0
	ds_read_b128 v[82:85], v90 offset:16384
	ds_read_b128 v[86:89], v90 offset:18432
	ds_read_b128 v[208:211], v90 offset:20480
	ds_read_b128 v[212:215], v90 offset:22528
	ds_read_b128 v[66:69], v207 offset:32768
	ds_read_b128 v[70:73], v207 offset:34816
	v_mfma_f32_16x16x32_bf16 v[34:37], v[216:219], v[74:77], v[34:37]
	v_mfma_f32_16x16x32_bf16 v[22:25], v[220:223], v[74:77], v[22:25]
	v_mfma_f32_16x16x32_bf16 v[18:21], v[224:227], v[74:77], v[18:21]
	v_mfma_f32_16x16x32_bf16 v[62:65], v[228:231], v[74:77], v[62:65]
	ds_read_b128 v[74:77], v207 offset:36864
	v_mfma_f32_16x16x32_bf16 v[58:61], v[216:219], v[78:81], v[58:61]
	v_mfma_f32_16x16x32_bf16 v[54:57], v[220:223], v[78:81], v[54:57]
	v_mfma_f32_16x16x32_bf16 v[50:53], v[224:227], v[78:81], v[50:53]
	v_mfma_f32_16x16x32_bf16 v[2:5], v[228:231], v[78:81], v[2:5]
	ds_read_b128 v[78:81], v207 offset:38912
	ds_read_b128 v[216:219], v91 offset:16384
	ds_read_b128 v[220:223], v91 offset:18432
	ds_read_b128 v[224:227], v91 offset:20480
	ds_read_b128 v[228:231], v91 offset:22528
	s_waitcnt lgkmcnt(7)
	v_mfma_f32_16x16x32_bf16 v[6:9], v[82:85], v[66:69], v[6:9]
	v_mfma_f32_16x16x32_bf16 v[30:33], v[86:89], v[66:69], v[30:33]
	v_mfma_f32_16x16x32_bf16 v[38:41], v[208:211], v[66:69], v[38:41]
	v_mfma_f32_16x16x32_bf16 v[42:45], v[212:215], v[66:69], v[42:45]
	ds_read_b128 v[66:69], v119 offset:32768
	s_waitcnt lgkmcnt(7)
	v_mfma_f32_16x16x32_bf16 v[46:49], v[82:85], v[70:73], v[46:49]
	v_mfma_f32_16x16x32_bf16 v[26:29], v[86:89], v[70:73], v[26:29]
	v_mfma_f32_16x16x32_bf16 v[14:17], v[208:211], v[70:73], v[14:17]
	v_mfma_f32_16x16x32_bf16 v[10:13], v[212:215], v[70:73], v[10:13]
	ds_read_b128 v[70:73], v119 offset:34816
	s_waitcnt lgkmcnt(7)
	v_mfma_f32_16x16x32_bf16 v[34:37], v[82:85], v[74:77], v[34:37]
	v_mfma_f32_16x16x32_bf16 v[22:25], v[86:89], v[74:77], v[22:25]
	v_mfma_f32_16x16x32_bf16 v[18:21], v[208:211], v[74:77], v[18:21]
	v_mfma_f32_16x16x32_bf16 v[62:65], v[212:215], v[74:77], v[62:65]
	ds_read_b128 v[74:77], v119 offset:36864
	s_waitcnt lgkmcnt(7)
	v_mfma_f32_16x16x32_bf16 v[58:61], v[82:85], v[78:81], v[58:61]
	v_mfma_f32_16x16x32_bf16 v[54:57], v[86:89], v[78:81], v[54:57]
	v_mfma_f32_16x16x32_bf16 v[50:53], v[208:211], v[78:81], v[50:53]
	v_mfma_f32_16x16x32_bf16 v[2:5], v[212:215], v[78:81], v[2:5]
	ds_read_b128 v[78:81], v119 offset:38912
	s_waitcnt lgkmcnt(3)
	v_mfma_f32_16x16x32_bf16 v[6:9], v[216:219], v[66:69], v[6:9]
	v_mfma_f32_16x16x32_bf16 v[30:33], v[220:223], v[66:69], v[30:33]
	v_mfma_f32_16x16x32_bf16 v[38:41], v[224:227], v[66:69], v[38:41]
	v_mfma_f32_16x16x32_bf16 v[42:45], v[228:231], v[66:69], v[42:45]
	s_waitcnt lgkmcnt(2)
	v_mfma_f32_16x16x32_bf16 v[46:49], v[216:219], v[70:73], v[46:49]
	v_mfma_f32_16x16x32_bf16 v[26:29], v[220:223], v[70:73], v[26:29]
	v_mfma_f32_16x16x32_bf16 v[14:17], v[224:227], v[70:73], v[14:17]
	v_mfma_f32_16x16x32_bf16 v[10:13], v[228:231], v[70:73], v[10:13]
	s_waitcnt vmcnt(6)
	s_waitcnt lgkmcnt(0)
	s_barrier
	s_add_i32 m0, s67, 0x8000
	s_nop 0
	global_load_lds_dwordx4 v188, s[80:81]
	s_add_i32 m0, s67, 0xa000
	s_nop 0
	global_load_lds_dwordx4 v189, s[80:81]
	s_add_i32 m0, s67, 0xc000
	s_nop 0
	global_load_lds_dwordx4 v190, s[80:81]
	s_add_i32 m0, s67, 0xe000
	s_nop 0
	global_load_lds_dwordx4 v191, s[80:81]
	s_add_i32 m0, s67, 0x1c000
	s_nop 0
	global_load_lds_dwordx4 v205, s[96:97]
	s_add_i32 m0, s67, 0x1e000
	s_nop 0
	global_load_lds_dwordx4 v206, s[96:97]
	s_add_u32 s80, s80, 0x80
	s_addc_u32 s81, s81, 0
	s_add_u32 s96, s96, 0x80
	s_addc_u32 s97, s97, 0
	ds_read_b128 v[82:85], v90 offset:33792
	ds_read_b128 v[86:89], v90 offset:35840
	ds_read_b128 v[208:211], v90 offset:37888
	ds_read_b128 v[212:215], v90 offset:39936
	ds_read_b128 v[66:69], v0 offset:0
	ds_read_b128 v[70:73], v0 offset:2048
	v_mfma_f32_16x16x32_bf16 v[34:37], v[216:219], v[74:77], v[34:37]
	v_mfma_f32_16x16x32_bf16 v[22:25], v[220:223], v[74:77], v[22:25]
	v_mfma_f32_16x16x32_bf16 v[18:21], v[224:227], v[74:77], v[18:21]
	v_mfma_f32_16x16x32_bf16 v[62:65], v[228:231], v[74:77], v[62:65]
	ds_read_b128 v[74:77], v0 offset:4096
	v_mfma_f32_16x16x32_bf16 v[58:61], v[216:219], v[78:81], v[58:61]
	v_mfma_f32_16x16x32_bf16 v[54:57], v[220:223], v[78:81], v[54:57]
	v_mfma_f32_16x16x32_bf16 v[50:53], v[224:227], v[78:81], v[50:53]
	v_mfma_f32_16x16x32_bf16 v[2:5], v[228:231], v[78:81], v[2:5]
	ds_read_b128 v[78:81], v0 offset:6144
	ds_read_b128 v[216:219], v91 offset:33792
	ds_read_b128 v[220:223], v91 offset:35840
	ds_read_b128 v[224:227], v91 offset:37888
	ds_read_b128 v[228:231], v91 offset:39936
	s_waitcnt lgkmcnt(7)
	v_mfma_f32_16x16x32_bf16 v[6:9], v[82:85], v[66:69], v[6:9]
	v_mfma_f32_16x16x32_bf16 v[30:33], v[86:89], v[66:69], v[30:33]
	v_mfma_f32_16x16x32_bf16 v[38:41], v[208:211], v[66:69], v[38:41]
	v_mfma_f32_16x16x32_bf16 v[42:45], v[212:215], v[66:69], v[42:45]
	ds_read_b128 v[66:69], v255 offset:0
	s_waitcnt lgkmcnt(7)
	v_mfma_f32_16x16x32_bf16 v[46:49], v[82:85], v[70:73], v[46:49]
	v_mfma_f32_16x16x32_bf16 v[26:29], v[86:89], v[70:73], v[26:29]
	v_mfma_f32_16x16x32_bf16 v[14:17], v[208:211], v[70:73], v[14:17]
	v_mfma_f32_16x16x32_bf16 v[10:13], v[212:215], v[70:73], v[10:13]
	ds_read_b128 v[70:73], v255 offset:2048
	s_waitcnt lgkmcnt(7)
	v_mfma_f32_16x16x32_bf16 v[34:37], v[82:85], v[74:77], v[34:37]
	v_mfma_f32_16x16x32_bf16 v[22:25], v[86:89], v[74:77], v[22:25]
	v_mfma_f32_16x16x32_bf16 v[18:21], v[208:211], v[74:77], v[18:21]
	v_mfma_f32_16x16x32_bf16 v[62:65], v[212:215], v[74:77], v[62:65]
	ds_read_b128 v[74:77], v255 offset:4096
	s_waitcnt lgkmcnt(7)
	v_mfma_f32_16x16x32_bf16 v[58:61], v[82:85], v[78:81], v[58:61]
	v_mfma_f32_16x16x32_bf16 v[54:57], v[86:89], v[78:81], v[54:57]
	v_mfma_f32_16x16x32_bf16 v[50:53], v[208:211], v[78:81], v[50:53]
	v_mfma_f32_16x16x32_bf16 v[2:5], v[212:215], v[78:81], v[2:5]
	ds_read_b128 v[78:81], v255 offset:6144
	s_waitcnt lgkmcnt(3)
	v_mfma_f32_16x16x32_bf16 v[6:9], v[216:219], v[66:69], v[6:9]
	v_mfma_f32_16x16x32_bf16 v[30:33], v[220:223], v[66:69], v[30:33]
	v_mfma_f32_16x16x32_bf16 v[38:41], v[224:227], v[66:69], v[38:41]
	v_mfma_f32_16x16x32_bf16 v[42:45], v[228:231], v[66:69], v[42:45]
	s_waitcnt lgkmcnt(2)
	v_mfma_f32_16x16x32_bf16 v[46:49], v[216:219], v[70:73], v[46:49]
	v_mfma_f32_16x16x32_bf16 v[26:29], v[220:223], v[70:73], v[26:29]
	v_mfma_f32_16x16x32_bf16 v[14:17], v[224:227], v[70:73], v[14:17]
	v_mfma_f32_16x16x32_bf16 v[10:13], v[228:231], v[70:73], v[10:13]
	s_waitcnt vmcnt(6)
	s_waitcnt lgkmcnt(0)
	s_barrier
	s_add_i32 m0, s67, 0x10000
	s_nop 0
	global_load_lds_dwordx4 v188, s[80:81]
	s_add_i32 m0, s67, 0x12000
	s_nop 0
	global_load_lds_dwordx4 v189, s[80:81]
	s_add_i32 m0, s67, 0x14000
	s_nop 0
	global_load_lds_dwordx4 v190, s[80:81]
	s_add_i32 m0, s67, 0x16000
	s_nop 0
	global_load_lds_dwordx4 v191, s[80:81]
	s_add_i32 m0, s67, 0x20400
	s_nop 0
	global_load_lds_dwordx4 v205, s[96:97]
	s_add_i32 m0, s67, 0x22400
	s_nop 0
	global_load_lds_dwordx4 v206, s[96:97]
	s_add_u32 s80, s80, 0x80
	s_addc_u32 s81, s81, 0
	s_add_u32 s96, s96, 0x80
	s_addc_u32 s97, s97, 0
	ds_read_b128 v[82:85], v90 offset:0
	ds_read_b128 v[86:89], v90 offset:2048
	ds_read_b128 v[208:211], v90 offset:4096
	ds_read_b128 v[212:215], v90 offset:6144
	ds_read_b128 v[66:69], v207 offset:0
	ds_read_b128 v[70:73], v207 offset:2048
	v_mfma_f32_16x16x32_bf16 v[34:37], v[216:219], v[74:77], v[34:37]
	v_mfma_f32_16x16x32_bf16 v[22:25], v[220:223], v[74:77], v[22:25]
	v_mfma_f32_16x16x32_bf16 v[18:21], v[224:227], v[74:77], v[18:21]
	v_mfma_f32_16x16x32_bf16 v[62:65], v[228:231], v[74:77], v[62:65]
	ds_read_b128 v[74:77], v207 offset:4096
	v_mfma_f32_16x16x32_bf16 v[58:61], v[216:219], v[78:81], v[58:61]
	v_mfma_f32_16x16x32_bf16 v[54:57], v[220:223], v[78:81], v[54:57]
	v_mfma_f32_16x16x32_bf16 v[50:53], v[224:227], v[78:81], v[50:53]
	v_mfma_f32_16x16x32_bf16 v[2:5], v[228:231], v[78:81], v[2:5]
	ds_read_b128 v[78:81], v207 offset:6144
	ds_read_b128 v[216:219], v91 offset:0
	ds_read_b128 v[220:223], v91 offset:2048
	ds_read_b128 v[224:227], v91 offset:4096
	ds_read_b128 v[228:231], v91 offset:6144
	s_waitcnt lgkmcnt(7)
	v_mfma_f32_16x16x32_bf16 v[6:9], v[82:85], v[66:69], v[6:9]
	v_mfma_f32_16x16x32_bf16 v[30:33], v[86:89], v[66:69], v[30:33]
	v_mfma_f32_16x16x32_bf16 v[38:41], v[208:211], v[66:69], v[38:41]
	v_mfma_f32_16x16x32_bf16 v[42:45], v[212:215], v[66:69], v[42:45]
	ds_read_b128 v[66:69], v119 offset:0
	s_waitcnt lgkmcnt(7)
	v_mfma_f32_16x16x32_bf16 v[46:49], v[82:85], v[70:73], v[46:49]
	v_mfma_f32_16x16x32_bf16 v[26:29], v[86:89], v[70:73], v[26:29]
	v_mfma_f32_16x16x32_bf16 v[14:17], v[208:211], v[70:73], v[14:17]
	v_mfma_f32_16x16x32_bf16 v[10:13], v[212:215], v[70:73], v[10:13]
	ds_read_b128 v[70:73], v119 offset:2048
	s_waitcnt lgkmcnt(7)
	v_mfma_f32_16x16x32_bf16 v[34:37], v[82:85], v[74:77], v[34:37]
	v_mfma_f32_16x16x32_bf16 v[22:25], v[86:89], v[74:77], v[22:25]
	v_mfma_f32_16x16x32_bf16 v[18:21], v[208:211], v[74:77], v[18:21]
	v_mfma_f32_16x16x32_bf16 v[62:65], v[212:215], v[74:77], v[62:65]
	ds_read_b128 v[74:77], v119 offset:4096
	s_waitcnt lgkmcnt(7)
	v_mfma_f32_16x16x32_bf16 v[58:61], v[82:85], v[78:81], v[58:61]
	v_mfma_f32_16x16x32_bf16 v[54:57], v[86:89], v[78:81], v[54:57]
	v_mfma_f32_16x16x32_bf16 v[50:53], v[208:211], v[78:81], v[50:53]
	v_mfma_f32_16x16x32_bf16 v[2:5], v[212:215], v[78:81], v[2:5]
	ds_read_b128 v[78:81], v119 offset:6144
	s_waitcnt lgkmcnt(3)
	v_mfma_f32_16x16x32_bf16 v[6:9], v[216:219], v[66:69], v[6:9]
	v_mfma_f32_16x16x32_bf16 v[30:33], v[220:223], v[66:69], v[30:33]
	v_mfma_f32_16x16x32_bf16 v[38:41], v[224:227], v[66:69], v[38:41]
	v_mfma_f32_16x16x32_bf16 v[42:45], v[228:231], v[66:69], v[42:45]
	s_waitcnt lgkmcnt(2)
	v_mfma_f32_16x16x32_bf16 v[46:49], v[216:219], v[70:73], v[46:49]
	v_mfma_f32_16x16x32_bf16 v[26:29], v[220:223], v[70:73], v[26:29]
	v_mfma_f32_16x16x32_bf16 v[14:17], v[224:227], v[70:73], v[14:17]
	v_mfma_f32_16x16x32_bf16 v[10:13], v[228:231], v[70:73], v[10:13]
	s_waitcnt vmcnt(6)
	s_waitcnt lgkmcnt(0)
	s_barrier
	s_add_i32 m0, s67, 0x0
	s_nop 0
	global_load_lds_dwordx4 v188, s[80:81]
	s_add_i32 m0, s67, 0x2000
	s_nop 0
	global_load_lds_dwordx4 v189, s[80:81]
	s_add_i32 m0, s67, 0x4000
	s_nop 0
	global_load_lds_dwordx4 v190, s[80:81]
	s_add_i32 m0, s67, 0x6000
	s_nop 0
	global_load_lds_dwordx4 v191, s[80:81]
	s_add_i32 m0, s67, 0x18000
	s_nop 0
	global_load_lds_dwordx4 v205, s[96:97]
	s_add_i32 m0, s67, 0x1a000
	s_nop 0
	global_load_lds_dwordx4 v206, s[96:97]
	s_add_u32 s80, s80, 0x80
	s_addc_u32 s81, s81, 0
	s_add_u32 s96, s96, 0x80
	s_addc_u32 s97, s97, 0
	s_movk_i32 s10, 0xc00
	s_mov_b32 s11, 0
	v_lshl_add_u64 v[248:249], v[128:129], 0, s[10:11]
	global_load_dwordx2 v[232:233], v[248:249], off
	global_load_dwordx2 v[234:235], v[248:249], off offset:32
	v_lshl_add_u64 v[248:249], v[132:133], 0, s[10:11]
	global_load_dwordx2 v[236:237], v[248:249], off
	global_load_dwordx2 v[238:239], v[248:249], off offset:32
	v_lshl_add_u64 v[248:249], v[152:153], 0, s[10:11]
	global_load_dwordx2 v[240:241], v[248:249], off
	global_load_dwordx2 v[242:243], v[248:249], off offset:32
	v_lshl_add_u64 v[248:249], v[154:155], 0, s[10:11]
	global_load_dwordx2 v[244:245], v[248:249], off
	global_load_dwordx2 v[246:247], v[248:249], off offset:32
	ds_read_b128 v[82:85], v90 offset:16384
	ds_read_b128 v[86:89], v90 offset:18432
	ds_read_b128 v[208:211], v90 offset:20480
	ds_read_b128 v[212:215], v90 offset:22528
	ds_read_b128 v[66:69], v207 offset:32768
	ds_read_b128 v[70:73], v207 offset:34816
	v_mfma_f32_16x16x32_bf16 v[34:37], v[216:219], v[74:77], v[34:37]
	v_mfma_f32_16x16x32_bf16 v[22:25], v[220:223], v[74:77], v[22:25]
	v_mfma_f32_16x16x32_bf16 v[18:21], v[224:227], v[74:77], v[18:21]
	v_mfma_f32_16x16x32_bf16 v[62:65], v[228:231], v[74:77], v[62:65]
	ds_read_b128 v[74:77], v207 offset:36864
	v_mfma_f32_16x16x32_bf16 v[58:61], v[216:219], v[78:81], v[58:61]
	v_mfma_f32_16x16x32_bf16 v[54:57], v[220:223], v[78:81], v[54:57]
	v_mfma_f32_16x16x32_bf16 v[50:53], v[224:227], v[78:81], v[50:53]
	v_mfma_f32_16x16x32_bf16 v[2:5], v[228:231], v[78:81], v[2:5]
	ds_read_b128 v[78:81], v207 offset:38912
	ds_read_b128 v[216:219], v91 offset:16384
	ds_read_b128 v[220:223], v91 offset:18432
	ds_read_b128 v[224:227], v91 offset:20480
	ds_read_b128 v[228:231], v91 offset:22528
	s_waitcnt lgkmcnt(7)
	v_mfma_f32_16x16x32_bf16 v[6:9], v[82:85], v[66:69], v[6:9]
	v_mfma_f32_16x16x32_bf16 v[30:33], v[86:89], v[66:69], v[30:33]
	v_mfma_f32_16x16x32_bf16 v[38:41], v[208:211], v[66:69], v[38:41]
	v_mfma_f32_16x16x32_bf16 v[42:45], v[212:215], v[66:69], v[42:45]
	ds_read_b128 v[66:69], v119 offset:32768
	s_waitcnt lgkmcnt(7)
	v_mfma_f32_16x16x32_bf16 v[46:49], v[82:85], v[70:73], v[46:49]
	v_mfma_f32_16x16x32_bf16 v[26:29], v[86:89], v[70:73], v[26:29]
	v_mfma_f32_16x16x32_bf16 v[14:17], v[208:211], v[70:73], v[14:17]
	v_mfma_f32_16x16x32_bf16 v[10:13], v[212:215], v[70:73], v[10:13]
	ds_read_b128 v[70:73], v119 offset:34816
	s_waitcnt lgkmcnt(7)
	v_mfma_f32_16x16x32_bf16 v[34:37], v[82:85], v[74:77], v[34:37]
	v_mfma_f32_16x16x32_bf16 v[22:25], v[86:89], v[74:77], v[22:25]
	v_mfma_f32_16x16x32_bf16 v[18:21], v[208:211], v[74:77], v[18:21]
	v_mfma_f32_16x16x32_bf16 v[62:65], v[212:215], v[74:77], v[62:65]
	ds_read_b128 v[74:77], v119 offset:36864
	s_waitcnt lgkmcnt(7)
	v_mfma_f32_16x16x32_bf16 v[58:61], v[82:85], v[78:81], v[58:61]
	v_mfma_f32_16x16x32_bf16 v[54:57], v[86:89], v[78:81], v[54:57]
	v_mfma_f32_16x16x32_bf16 v[50:53], v[208:211], v[78:81], v[50:53]
	v_mfma_f32_16x16x32_bf16 v[2:5], v[212:215], v[78:81], v[2:5]
	ds_read_b128 v[78:81], v119 offset:38912
	s_waitcnt lgkmcnt(3)
	v_mfma_f32_16x16x32_bf16 v[6:9], v[216:219], v[66:69], v[6:9]
	v_mfma_f32_16x16x32_bf16 v[30:33], v[220:223], v[66:69], v[30:33]
	v_mfma_f32_16x16x32_bf16 v[38:41], v[224:227], v[66:69], v[38:41]
	v_mfma_f32_16x16x32_bf16 v[42:45], v[228:231], v[66:69], v[42:45]
	s_waitcnt lgkmcnt(2)
	v_mfma_f32_16x16x32_bf16 v[46:49], v[216:219], v[70:73], v[46:49]
	v_mfma_f32_16x16x32_bf16 v[26:29], v[220:223], v[70:73], v[26:29]
	v_mfma_f32_16x16x32_bf16 v[14:17], v[224:227], v[70:73], v[14:17]
	v_mfma_f32_16x16x32_bf16 v[10:13], v[228:231], v[70:73], v[10:13]
	s_waitcnt vmcnt(14)
	s_waitcnt lgkmcnt(0)
	s_barrier
	s_add_i32 m0, s67, 0x8000
	s_nop 0
	global_load_lds_dwordx4 v188, s[80:81]
	s_add_i32 m0, s67, 0xa000
	s_nop 0
	global_load_lds_dwordx4 v189, s[80:81]
	s_add_i32 m0, s67, 0xc000
	s_nop 0
	global_load_lds_dwordx4 v190, s[80:81]
	s_add_i32 m0, s67, 0xe000
	s_nop 0
	global_load_lds_dwordx4 v191, s[80:81]
	s_add_i32 m0, s67, 0x1c000
	s_nop 0
	global_load_lds_dwordx4 v205, s[96:97]
	s_add_i32 m0, s67, 0x1e000
	s_nop 0
	global_load_lds_dwordx4 v206, s[96:97]
	ds_read_b128 v[82:85], v90 offset:33792
	ds_read_b128 v[86:89], v90 offset:35840
	ds_read_b128 v[208:211], v90 offset:37888
	ds_read_b128 v[212:215], v90 offset:39936
	ds_read_b128 v[66:69], v0 offset:0
	ds_read_b128 v[70:73], v0 offset:2048
	v_mfma_f32_16x16x32_bf16 v[34:37], v[216:219], v[74:77], v[34:37]
	v_mfma_f32_16x16x32_bf16 v[22:25], v[220:223], v[74:77], v[22:25]
	v_mfma_f32_16x16x32_bf16 v[18:21], v[224:227], v[74:77], v[18:21]
	v_mfma_f32_16x16x32_bf16 v[62:65], v[228:231], v[74:77], v[62:65]
	ds_read_b128 v[74:77], v0 offset:4096
	v_mfma_f32_16x16x32_bf16 v[58:61], v[216:219], v[78:81], v[58:61]
	v_mfma_f32_16x16x32_bf16 v[54:57], v[220:223], v[78:81], v[54:57]
	v_mfma_f32_16x16x32_bf16 v[50:53], v[224:227], v[78:81], v[50:53]
	v_mfma_f32_16x16x32_bf16 v[2:5], v[228:231], v[78:81], v[2:5]
	ds_read_b128 v[78:81], v0 offset:6144
	ds_read_b128 v[216:219], v91 offset:33792
	ds_read_b128 v[220:223], v91 offset:35840
	ds_read_b128 v[224:227], v91 offset:37888
	ds_read_b128 v[228:231], v91 offset:39936
	s_waitcnt lgkmcnt(7)
	v_mfma_f32_16x16x32_bf16 v[6:9], v[82:85], v[66:69], v[6:9]
	v_mfma_f32_16x16x32_bf16 v[30:33], v[86:89], v[66:69], v[30:33]
	v_mfma_f32_16x16x32_bf16 v[38:41], v[208:211], v[66:69], v[38:41]
	v_mfma_f32_16x16x32_bf16 v[42:45], v[212:215], v[66:69], v[42:45]
	ds_read_b128 v[66:69], v255 offset:0
	s_waitcnt lgkmcnt(7)
	v_mfma_f32_16x16x32_bf16 v[46:49], v[82:85], v[70:73], v[46:49]
	v_mfma_f32_16x16x32_bf16 v[26:29], v[86:89], v[70:73], v[26:29]
	v_mfma_f32_16x16x32_bf16 v[14:17], v[208:211], v[70:73], v[14:17]
	v_mfma_f32_16x16x32_bf16 v[10:13], v[212:215], v[70:73], v[10:13]
	ds_read_b128 v[70:73], v255 offset:2048
	s_waitcnt lgkmcnt(7)
	v_mfma_f32_16x16x32_bf16 v[34:37], v[82:85], v[74:77], v[34:37]
	v_mfma_f32_16x16x32_bf16 v[22:25], v[86:89], v[74:77], v[22:25]
	v_mfma_f32_16x16x32_bf16 v[18:21], v[208:211], v[74:77], v[18:21]
	v_mfma_f32_16x16x32_bf16 v[62:65], v[212:215], v[74:77], v[62:65]
	ds_read_b128 v[74:77], v255 offset:4096
	s_waitcnt lgkmcnt(7)
	v_mfma_f32_16x16x32_bf16 v[58:61], v[82:85], v[78:81], v[58:61]
	v_mfma_f32_16x16x32_bf16 v[54:57], v[86:89], v[78:81], v[54:57]
	v_mfma_f32_16x16x32_bf16 v[50:53], v[208:211], v[78:81], v[50:53]
	v_mfma_f32_16x16x32_bf16 v[2:5], v[212:215], v[78:81], v[2:5]
	ds_read_b128 v[78:81], v255 offset:6144
	s_waitcnt lgkmcnt(3)
	v_mfma_f32_16x16x32_bf16 v[6:9], v[216:219], v[66:69], v[6:9]
	v_mfma_f32_16x16x32_bf16 v[30:33], v[220:223], v[66:69], v[30:33]
	v_mfma_f32_16x16x32_bf16 v[38:41], v[224:227], v[66:69], v[38:41]
	v_mfma_f32_16x16x32_bf16 v[42:45], v[228:231], v[66:69], v[42:45]
	s_waitcnt lgkmcnt(2)
	v_mfma_f32_16x16x32_bf16 v[46:49], v[216:219], v[70:73], v[46:49]
	v_mfma_f32_16x16x32_bf16 v[26:29], v[220:223], v[70:73], v[26:29]
	v_mfma_f32_16x16x32_bf16 v[14:17], v[224:227], v[70:73], v[14:17]
	v_mfma_f32_16x16x32_bf16 v[10:13], v[228:231], v[70:73], v[10:13]
	s_waitcnt vmcnt(14)
	s_waitcnt lgkmcnt(0)
	s_barrier
	ds_read_b128 v[82:85], v90 offset:0
	ds_read_b128 v[86:89], v90 offset:2048
	ds_read_b128 v[208:211], v90 offset:4096
	ds_read_b128 v[212:215], v90 offset:6144
	ds_read_b128 v[66:69], v207 offset:0
	ds_read_b128 v[70:73], v207 offset:2048
	v_mfma_f32_16x16x32_bf16 v[34:37], v[216:219], v[74:77], v[34:37]
	v_mfma_f32_16x16x32_bf16 v[22:25], v[220:223], v[74:77], v[22:25]
	v_mfma_f32_16x16x32_bf16 v[18:21], v[224:227], v[74:77], v[18:21]
	v_mfma_f32_16x16x32_bf16 v[62:65], v[228:231], v[74:77], v[62:65]
	ds_read_b128 v[74:77], v207 offset:4096
	v_mfma_f32_16x16x32_bf16 v[58:61], v[216:219], v[78:81], v[58:61]
	v_mfma_f32_16x16x32_bf16 v[54:57], v[220:223], v[78:81], v[54:57]
	v_mfma_f32_16x16x32_bf16 v[50:53], v[224:227], v[78:81], v[50:53]
	v_mfma_f32_16x16x32_bf16 v[2:5], v[228:231], v[78:81], v[2:5]
	ds_read_b128 v[78:81], v207 offset:6144
	ds_read_b128 v[216:219], v91 offset:0
	ds_read_b128 v[220:223], v91 offset:2048
	ds_read_b128 v[224:227], v91 offset:4096
	ds_read_b128 v[228:231], v91 offset:6144
	s_waitcnt lgkmcnt(7)
	v_mfma_f32_16x16x32_bf16 v[6:9], v[82:85], v[66:69], v[6:9]
	v_mfma_f32_16x16x32_bf16 v[30:33], v[86:89], v[66:69], v[30:33]
	v_mfma_f32_16x16x32_bf16 v[38:41], v[208:211], v[66:69], v[38:41]
	v_mfma_f32_16x16x32_bf16 v[42:45], v[212:215], v[66:69], v[42:45]
	ds_read_b128 v[66:69], v119 offset:0
	s_waitcnt lgkmcnt(7)
	v_mfma_f32_16x16x32_bf16 v[46:49], v[82:85], v[70:73], v[46:49]
	v_mfma_f32_16x16x32_bf16 v[26:29], v[86:89], v[70:73], v[26:29]
	v_mfma_f32_16x16x32_bf16 v[14:17], v[208:211], v[70:73], v[14:17]
	v_mfma_f32_16x16x32_bf16 v[10:13], v[212:215], v[70:73], v[10:13]
	ds_read_b128 v[70:73], v119 offset:2048
	s_waitcnt lgkmcnt(7)
	v_mfma_f32_16x16x32_bf16 v[34:37], v[82:85], v[74:77], v[34:37]
	v_mfma_f32_16x16x32_bf16 v[22:25], v[86:89], v[74:77], v[22:25]
	v_mfma_f32_16x16x32_bf16 v[18:21], v[208:211], v[74:77], v[18:21]
	v_mfma_f32_16x16x32_bf16 v[62:65], v[212:215], v[74:77], v[62:65]
	ds_read_b128 v[74:77], v119 offset:4096
	s_waitcnt lgkmcnt(7)
	v_mfma_f32_16x16x32_bf16 v[58:61], v[82:85], v[78:81], v[58:61]
	v_mfma_f32_16x16x32_bf16 v[54:57], v[86:89], v[78:81], v[54:57]
	v_mfma_f32_16x16x32_bf16 v[50:53], v[208:211], v[78:81], v[50:53]
	v_mfma_f32_16x16x32_bf16 v[2:5], v[212:215], v[78:81], v[2:5]
	ds_read_b128 v[78:81], v119 offset:6144
	s_waitcnt lgkmcnt(3)
	v_mfma_f32_16x16x32_bf16 v[6:9], v[216:219], v[66:69], v[6:9]
	v_mfma_f32_16x16x32_bf16 v[30:33], v[220:223], v[66:69], v[30:33]
	v_mfma_f32_16x16x32_bf16 v[38:41], v[224:227], v[66:69], v[38:41]
	v_mfma_f32_16x16x32_bf16 v[42:45], v[228:231], v[66:69], v[42:45]
	s_waitcnt lgkmcnt(2)
	v_mfma_f32_16x16x32_bf16 v[46:49], v[216:219], v[70:73], v[46:49]
	v_mfma_f32_16x16x32_bf16 v[26:29], v[220:223], v[70:73], v[26:29]
	v_mfma_f32_16x16x32_bf16 v[14:17], v[224:227], v[70:73], v[14:17]
	v_mfma_f32_16x16x32_bf16 v[10:13], v[228:231], v[70:73], v[10:13]
	s_waitcnt vmcnt(0)
	s_waitcnt lgkmcnt(0)
	s_barrier
	ds_read_b128 v[82:85], v90 offset:16384
	ds_read_b128 v[86:89], v90 offset:18432
	ds_read_b128 v[208:211], v90 offset:20480
	ds_read_b128 v[212:215], v90 offset:22528
	ds_read_b128 v[66:69], v207 offset:32768
	ds_read_b128 v[70:73], v207 offset:34816
	v_mfma_f32_16x16x32_bf16 v[34:37], v[216:219], v[74:77], v[34:37]
	v_mfma_f32_16x16x32_bf16 v[22:25], v[220:223], v[74:77], v[22:25]
	v_mfma_f32_16x16x32_bf16 v[18:21], v[224:227], v[74:77], v[18:21]
	v_mfma_f32_16x16x32_bf16 v[62:65], v[228:231], v[74:77], v[62:65]
	ds_read_b128 v[74:77], v207 offset:36864
	v_mfma_f32_16x16x32_bf16 v[58:61], v[216:219], v[78:81], v[58:61]
	v_mfma_f32_16x16x32_bf16 v[54:57], v[220:223], v[78:81], v[54:57]
	v_mfma_f32_16x16x32_bf16 v[50:53], v[224:227], v[78:81], v[50:53]
	v_mfma_f32_16x16x32_bf16 v[2:5], v[228:231], v[78:81], v[2:5]
	ds_read_b128 v[78:81], v207 offset:38912
	ds_read_b128 v[216:219], v91 offset:16384
	ds_read_b128 v[220:223], v91 offset:18432
	ds_read_b128 v[224:227], v91 offset:20480
	ds_read_b128 v[228:231], v91 offset:22528
	s_waitcnt lgkmcnt(7)
	v_mfma_f32_16x16x32_bf16 v[6:9], v[82:85], v[66:69], v[6:9]
	v_mfma_f32_16x16x32_bf16 v[30:33], v[86:89], v[66:69], v[30:33]
	v_mfma_f32_16x16x32_bf16 v[38:41], v[208:211], v[66:69], v[38:41]
	v_mfma_f32_16x16x32_bf16 v[42:45], v[212:215], v[66:69], v[42:45]
	ds_read_b128 v[66:69], v119 offset:32768
	s_waitcnt lgkmcnt(7)
	v_mfma_f32_16x16x32_bf16 v[46:49], v[82:85], v[70:73], v[46:49]
	v_mfma_f32_16x16x32_bf16 v[26:29], v[86:89], v[70:73], v[26:29]
	v_mfma_f32_16x16x32_bf16 v[14:17], v[208:211], v[70:73], v[14:17]
	v_mfma_f32_16x16x32_bf16 v[10:13], v[212:215], v[70:73], v[10:13]
	ds_read_b128 v[70:73], v119 offset:34816
	s_waitcnt lgkmcnt(7)
	v_mfma_f32_16x16x32_bf16 v[34:37], v[82:85], v[74:77], v[34:37]
	v_mfma_f32_16x16x32_bf16 v[22:25], v[86:89], v[74:77], v[22:25]
	v_mfma_f32_16x16x32_bf16 v[18:21], v[208:211], v[74:77], v[18:21]
	v_mfma_f32_16x16x32_bf16 v[62:65], v[212:215], v[74:77], v[62:65]
	ds_read_b128 v[74:77], v119 offset:36864
	s_waitcnt lgkmcnt(7)
	v_mfma_f32_16x16x32_bf16 v[58:61], v[82:85], v[78:81], v[58:61]
	v_mfma_f32_16x16x32_bf16 v[54:57], v[86:89], v[78:81], v[54:57]
	v_mfma_f32_16x16x32_bf16 v[50:53], v[208:211], v[78:81], v[50:53]
	v_mfma_f32_16x16x32_bf16 v[2:5], v[212:215], v[78:81], v[2:5]
	ds_read_b128 v[78:81], v119 offset:38912
	s_waitcnt lgkmcnt(3)
	v_mfma_f32_16x16x32_bf16 v[6:9], v[216:219], v[66:69], v[6:9]
	s_waitcnt vmcnt(6)
	v_mfma_f32_16x16x32_bf16 v[30:33], v[220:223], v[66:69], v[30:33]
	v_mfma_f32_16x16x32_bf16 v[38:41], v[224:227], v[66:69], v[38:41]
	v_mfma_f32_16x16x32_bf16 v[42:45], v[228:231], v[66:69], v[42:45]
	v_cvt_f32_ubyte0_e32 v248, v232
	v_cvt_f32_ubyte1_e32 v249, v232
	v_cvt_f32_ubyte2_e32 v250, v232
	v_cvt_f32_ubyte3_e32 v251, v232
	v_mul_f32_e32 v248, s34, v248
	v_mul_f32_e32 v249, s34, v249
	v_mul_f32_e32 v250, s34, v250
	v_mul_f32_e32 v251, s34, v251
	v_fma_f32 v184, v6, v248, v184
	v_fma_f32 v185, v7, v249, v185
	v_fma_f32 v186, v8, v250, v186
	v_fma_f32 v187, v9, v251, v187
	s_waitcnt lgkmcnt(2)
	v_mfma_f32_16x16x32_bf16 v[46:49], v[216:219], v[70:73], v[46:49]
	v_cvt_f32_ubyte0_e32 v248, v233
	v_cvt_f32_ubyte1_e32 v249, v233
	v_cvt_f32_ubyte2_e32 v250, v233
	v_cvt_f32_ubyte3_e32 v251, v233
	v_mul_f32_e32 v248, s34, v248
	v_mul_f32_e32 v249, s34, v249
	v_mul_f32_e32 v250, s34, v250
	v_mul_f32_e32 v251, s34, v251
	v_fma_f32 v180, v30, v248, v180
	v_fma_f32 v181, v31, v249, v181
	v_fma_f32 v182, v32, v250, v182
	v_fma_f32 v183, v33, v251, v183
	v_mfma_f32_16x16x32_bf16 v[26:29], v[220:223], v[70:73], v[26:29]
	v_cvt_f32_ubyte0_e32 v248, v234
	v_cvt_f32_ubyte1_e32 v249, v234
	v_cvt_f32_ubyte2_e32 v250, v234
	v_cvt_f32_ubyte3_e32 v251, v234
	v_mul_f32_e32 v248, s34, v248
	v_mul_f32_e32 v249, s34, v249
	v_mul_f32_e32 v250, s34, v250
	v_mul_f32_e32 v251, s34, v251
	v_fma_f32 v176, v38, v248, v176
	v_fma_f32 v177, v39, v249, v177
	v_fma_f32 v178, v40, v250, v178
	v_fma_f32 v179, v41, v251, v179
	v_mfma_f32_16x16x32_bf16 v[14:17], v[224:227], v[70:73], v[14:17]
	v_cvt_f32_ubyte0_e32 v248, v235
	v_cvt_f32_ubyte1_e32 v249, v235
	v_cvt_f32_ubyte2_e32 v250, v235
	v_cvt_f32_ubyte3_e32 v251, v235
	v_mul_f32_e32 v248, s34, v248
	v_mul_f32_e32 v249, s34, v249
	v_mul_f32_e32 v250, s34, v250
	v_mul_f32_e32 v251, s34, v251
	v_fma_f32 v172, v42, v248, v172
	v_fma_f32 v173, v43, v249, v173
	v_fma_f32 v174, v44, v250, v174
	v_fma_f32 v175, v45, v251, v175
	v_mfma_f32_16x16x32_bf16 v[10:13], v[228:231], v[70:73], v[10:13]
	v_cvt_f32_ubyte0_e32 v248, v236
	v_cvt_f32_ubyte1_e32 v249, v236
	v_cvt_f32_ubyte2_e32 v250, v236
	v_cvt_f32_ubyte3_e32 v251, v236
	v_mul_f32_e32 v248, s34, v248
	v_mul_f32_e32 v249, s34, v249
	v_mul_f32_e32 v250, s34, v250
	v_mul_f32_e32 v251, s34, v251
	v_fma_f32 v168, v46, v248, v168
	v_fma_f32 v169, v47, v249, v169
	v_fma_f32 v170, v48, v250, v170
	v_fma_f32 v171, v49, v251, v171
	s_waitcnt lgkmcnt(0)
	s_barrier
	v_mfma_f32_16x16x32_bf16 v[34:37], v[216:219], v[74:77], v[34:37]
	v_cvt_f32_ubyte0_e32 v248, v237
	v_cvt_f32_ubyte1_e32 v249, v237
	v_cvt_f32_ubyte2_e32 v250, v237
	v_cvt_f32_ubyte3_e32 v251, v237
	v_mul_f32_e32 v248, s34, v248
	v_mul_f32_e32 v249, s34, v249
	v_mul_f32_e32 v250, s34, v250
	v_mul_f32_e32 v251, s34, v251
	v_fma_f32 v164, v26, v248, v164
	v_fma_f32 v165, v27, v249, v165
	v_fma_f32 v166, v28, v250, v166
	v_fma_f32 v167, v29, v251, v167
	v_mfma_f32_16x16x32_bf16 v[22:25], v[220:223], v[74:77], v[22:25]
	v_cvt_f32_ubyte0_e32 v248, v238
	v_cvt_f32_ubyte1_e32 v249, v238
	v_cvt_f32_ubyte2_e32 v250, v238
	v_cvt_f32_ubyte3_e32 v251, v238
	v_mul_f32_e32 v248, s34, v248
	v_mul_f32_e32 v249, s34, v249
	v_mul_f32_e32 v250, s34, v250
	v_mul_f32_e32 v251, s34, v251
	v_fma_f32 v160, v14, v248, v160
	v_fma_f32 v161, v15, v249, v161
	v_fma_f32 v162, v16, v250, v162
	v_fma_f32 v163, v17, v251, v163
	v_mfma_f32_16x16x32_bf16 v[18:21], v[224:227], v[74:77], v[18:21]
	v_cvt_f32_ubyte0_e32 v248, v239
	v_cvt_f32_ubyte1_e32 v249, v239
	v_cvt_f32_ubyte2_e32 v250, v239
	v_cvt_f32_ubyte3_e32 v251, v239
	v_mul_f32_e32 v248, s34, v248
	v_mul_f32_e32 v249, s34, v249
	v_mul_f32_e32 v250, s34, v250
	v_mul_f32_e32 v251, s34, v251
	v_fma_f32 v156, v10, v248, v156
	v_fma_f32 v157, v11, v249, v157
	v_fma_f32 v158, v12, v250, v158
	v_fma_f32 v159, v13, v251, v159
	v_mfma_f32_16x16x32_bf16 v[62:65], v[228:231], v[74:77], v[62:65]
	v_cvt_f32_ubyte0_e32 v248, v240
	v_cvt_f32_ubyte1_e32 v249, v240
	v_cvt_f32_ubyte2_e32 v250, v240
	v_cvt_f32_ubyte3_e32 v251, v240
	v_mul_f32_e32 v248, s34, v248
	v_mul_f32_e32 v249, s34, v249
	v_mul_f32_e32 v250, s34, v250
	v_mul_f32_e32 v251, s34, v251
	v_fma_f32 v136, v34, v248, v136
	v_fma_f32 v137, v35, v249, v137
	v_fma_f32 v150, v36, v250, v150
	v_fma_f32 v151, v37, v251, v151
	v_mfma_f32_16x16x32_bf16 v[58:61], v[216:219], v[78:81], v[58:61]
	v_cvt_f32_ubyte0_e32 v248, v241
	v_cvt_f32_ubyte1_e32 v249, v241
	v_cvt_f32_ubyte2_e32 v250, v241
	v_cvt_f32_ubyte3_e32 v251, v241
	v_mul_f32_e32 v248, s34, v248
	v_mul_f32_e32 v249, s34, v249
	v_mul_f32_e32 v250, s34, v250
	v_mul_f32_e32 v251, s34, v251
	v_fma_f32 v130, v22, v248, v130
	v_fma_f32 v131, v23, v249, v131
	v_fma_f32 v134, v24, v250, v134
	v_fma_f32 v135, v25, v251, v135
	v_mfma_f32_16x16x32_bf16 v[54:57], v[220:223], v[78:81], v[54:57]
	v_cvt_f32_ubyte0_e32 v248, v242
	v_cvt_f32_ubyte1_e32 v249, v242
	v_cvt_f32_ubyte2_e32 v250, v242
	v_cvt_f32_ubyte3_e32 v251, v242
	v_mul_f32_e32 v248, s34, v248
	v_mul_f32_e32 v249, s34, v249
	v_mul_f32_e32 v250, s34, v250
	v_mul_f32_e32 v251, s34, v251
	v_fma_f32 v124, v18, v248, v124
	v_fma_f32 v125, v19, v249, v125
	v_fma_f32 v126, v20, v250, v126
	v_fma_f32 v127, v21, v251, v127
	v_mfma_f32_16x16x32_bf16 v[50:53], v[224:227], v[78:81], v[50:53]
	v_cvt_f32_ubyte0_e32 v248, v243
	v_cvt_f32_ubyte1_e32 v249, v243
	v_cvt_f32_ubyte2_e32 v250, v243
	v_cvt_f32_ubyte3_e32 v251, v243
	v_mul_f32_e32 v248, s34, v248
	v_mul_f32_e32 v249, s34, v249
	v_mul_f32_e32 v250, s34, v250
	v_mul_f32_e32 v251, s34, v251
	v_fma_f32 v120, v62, v248, v120
	v_fma_f32 v121, v63, v249, v121
	v_fma_f32 v122, v64, v250, v122
	v_fma_f32 v123, v65, v251, v123
	v_mfma_f32_16x16x32_bf16 v[2:5], v[228:231], v[78:81], v[2:5]
	v_cvt_f32_ubyte0_e32 v248, v244
	v_cvt_f32_ubyte1_e32 v249, v244
	v_cvt_f32_ubyte2_e32 v250, v244
	v_cvt_f32_ubyte3_e32 v251, v244
	v_mul_f32_e32 v248, s34, v248
	v_mul_f32_e32 v249, s34, v249
	v_mul_f32_e32 v250, s34, v250
	v_mul_f32_e32 v251, s34, v251
	v_fma_f32 v114, v58, v248, v114
	v_fma_f32 v115, v59, v249, v115
	v_fma_f32 v116, v60, v250, v116
	v_fma_f32 v117, v61, v251, v117
	s_nop 7
	s_nop 3
	v_cvt_f32_ubyte0_e32 v248, v245
	v_cvt_f32_ubyte1_e32 v249, v245
	v_cvt_f32_ubyte2_e32 v250, v245
	v_cvt_f32_ubyte3_e32 v251, v245
	v_mul_f32_e32 v248, s34, v248
	v_mul_f32_e32 v249, s34, v249
	v_mul_f32_e32 v250, s34, v250
	v_mul_f32_e32 v251, s34, v251
	v_fma_f32 v106, v54, v248, v106
	v_fma_f32 v107, v55, v249, v107
	v_fma_f32 v108, v56, v250, v108
	v_fma_f32 v109, v57, v251, v109
	v_cvt_f32_ubyte0_e32 v248, v246
	v_cvt_f32_ubyte1_e32 v249, v246
	v_cvt_f32_ubyte2_e32 v250, v246
	v_cvt_f32_ubyte3_e32 v251, v246
	v_mul_f32_e32 v248, s34, v248
	v_mul_f32_e32 v249, s34, v249
	v_mul_f32_e32 v250, s34, v250
	v_mul_f32_e32 v251, s34, v251
	v_fma_f32 v100, v50, v248, v100
	v_fma_f32 v101, v51, v249, v101
	v_fma_f32 v102, v52, v250, v102
	v_fma_f32 v103, v53, v251, v103
	v_cvt_f32_ubyte0_e32 v248, v247
	v_cvt_f32_ubyte1_e32 v249, v247
	v_cvt_f32_ubyte2_e32 v250, v247
	v_cvt_f32_ubyte3_e32 v251, v247
	v_mul_f32_e32 v248, s34, v248
	v_mul_f32_e32 v249, s34, v249
	v_mul_f32_e32 v250, s34, v250
	v_mul_f32_e32 v251, s34, v251
	v_fma_f32 v96, v2, v248, v96
	v_fma_f32 v97, v3, v249, v97
	v_fma_f32 v98, v4, v250, v98
	v_fma_f32 v99, v5, v251, v99
	s_cmp_eq_u32 0, 0
	s_cbranch_scc0 .LBB0_1004
	v_lshlrev_b32_e32 v0, 1, v118
	v_lshl_add_u64 v[6:7], s[4:5], 0, v[0:1]
	v_lshlrev_b64 v[2:3], 11, v[112:113]
	v_lshl_add_u64 v[8:9], v[6:7], 0, v[2:3]
	v_cvt_pk_bf16_f32 v2, v184, v185
	v_cvt_pk_bf16_f32 v3, v186, v187
	v_cvt_pk_bf16_f32 v4, v180, v181
	v_cvt_pk_bf16_f32 v5, v182, v183
	global_store_dwordx4 v[8:9], v[2:5], off
	v_readlane_b32 s46, v254, 29
	s_mov_b32 s38, 0
	v_cvt_pk_bf16_f32 v2, v176, v177
	v_cvt_pk_bf16_f32 v3, v178, v179
	v_cvt_pk_bf16_f32 v4, v172, v173
	v_cvt_pk_bf16_f32 v5, v174, v175
	global_store_dwordx4 v[8:9], v[2:5], off offset:64
	v_readlane_b32 s47, v254, 30
	s_nop 0
	v_lshlrev_b64 v[2:3], 11, v[110:111]
	v_lshl_add_u64 v[8:9], v[6:7], 0, v[2:3]
	v_cvt_pk_bf16_f32 v2, v168, v169
	v_cvt_pk_bf16_f32 v3, v170, v171
	v_cvt_pk_bf16_f32 v4, v164, v165
	v_cvt_pk_bf16_f32 v5, v166, v167
	global_store_dwordx4 v[8:9], v[2:5], off
	s_nop 1
	v_cvt_pk_bf16_f32 v2, v160, v161
	v_cvt_pk_bf16_f32 v3, v162, v163
	v_cvt_pk_bf16_f32 v4, v156, v157
	v_cvt_pk_bf16_f32 v5, v158, v159
	global_store_dwordx4 v[8:9], v[2:5], off offset:64
	s_nop 1
	v_lshlrev_b64 v[2:3], 11, v[104:105]
	v_lshl_add_u64 v[8:9], v[6:7], 0, v[2:3]
	v_cvt_pk_bf16_f32 v2, v136, v137
	v_cvt_pk_bf16_f32 v3, v150, v151
	v_cvt_pk_bf16_f32 v4, v130, v131
	v_cvt_pk_bf16_f32 v5, v134, v135
	global_store_dwordx4 v[8:9], v[2:5], off
	s_nop 1
	v_cvt_pk_bf16_f32 v2, v124, v125
	v_cvt_pk_bf16_f32 v3, v126, v127
	v_cvt_pk_bf16_f32 v4, v120, v121
	v_cvt_pk_bf16_f32 v5, v122, v123
	global_store_dwordx4 v[8:9], v[2:5], off offset:64
	s_nop 1
	v_lshlrev_b64 v[2:3], 11, v[94:95]
	v_lshl_add_u64 v[6:7], v[6:7], 0, v[2:3]
	v_cvt_pk_bf16_f32 v2, v114, v115
	v_cvt_pk_bf16_f32 v3, v116, v117
	v_cvt_pk_bf16_f32 v4, v106, v107
	v_cvt_pk_bf16_f32 v5, v108, v109
	global_store_dwordx4 v[6:7], v[2:5], off
	s_nop 1
	v_cvt_pk_bf16_f32 v2, v100, v101
	v_cvt_pk_bf16_f32 v3, v102, v103
	v_cvt_pk_bf16_f32 v4, v96, v97
	v_cvt_pk_bf16_f32 v5, v98, v99
	global_store_dwordx4 v[6:7], v[2:5], off offset:64

	.amdhsa_kernel _Z14fwd_megakernel6Params
		.amdhsa_group_segment_fixed_size 16384
		.amdhsa_private_segment_fixed_size 0
		.amdhsa_kernarg_size 464
		.amdhsa_user_sgpr_count 2
		.amdhsa_user_sgpr_dispatch_ptr 0
		.amdhsa_user_sgpr_queue_ptr 0
		.amdhsa_user_sgpr_kernarg_segment_ptr 1
		.amdhsa_user_sgpr_dispatch_id 0
		.amdhsa_user_sgpr_kernarg_preload_length 0
		.amdhsa_user_sgpr_kernarg_preload_offset 0
		.amdhsa_user_sgpr_private_segment_size 0
		.amdhsa_uses_dynamic_stack 0
		.amdhsa_enable_private_segment 0
		.amdhsa_system_sgpr_workgroup_id_x 1
		.amdhsa_system_sgpr_workgroup_id_y 0
		.amdhsa_system_sgpr_workgroup_id_z 0
		.amdhsa_system_sgpr_workgroup_info 0
		.amdhsa_system_vgpr_workitem_id 2
		.amdhsa_next_free_vgpr 256
		.amdhsa_next_free_sgpr 100
		.amdhsa_accum_offset 256
		.amdhsa_reserve_vcc 1
		.amdhsa_float_round_mode_32 0
		.amdhsa_float_round_mode_16_64 0
		.amdhsa_float_denorm_mode_32 3
		.amdhsa_float_denorm_mode_16_64 3
		.amdhsa_dx10_clamp 1
		.amdhsa_ieee_mode 1
		.amdhsa_fp16_overflow 0
		.amdhsa_tg_split 0
		.amdhsa_exception_fp_ieee_invalid_op 0
		.amdhsa_exception_fp_denorm_src 0
		.amdhsa_exception_fp_ieee_div_zero 0
		.amdhsa_exception_fp_ieee_overflow 0
		.amdhsa_exception_fp_ieee_underflow 0
		.amdhsa_exception_fp_ieee_inexact 0
		.amdhsa_exception_int_div_zero 0
	.end_amdhsa_kernel

amdhsa.kernels:
  - .agpr_count:     0
    .args:
      - .offset:         0
        .size:           208
        .value_kind:     by_value
      - .offset:         208
        .size:           4
        .value_kind:     hidden_block_count_x
      - .offset:         212
        .size:           4
        .value_kind:     hidden_block_count_y
      - .offset:         216
        .size:           4
        .value_kind:     hidden_block_count_z
      - .offset:         220
        .size:           2
        .value_kind:     hidden_group_size_x
      - .offset:         222
        .size:           2
        .value_kind:     hidden_group_size_y
      - .offset:         224
        .size:           2
        .value_kind:     hidden_group_size_z
      - .offset:         226
        .size:           2
        .value_kind:     hidden_remainder_x
      - .offset:         228
        .size:           2
        .value_kind:     hidden_remainder_y
      - .offset:         230
        .size:           2
        .value_kind:     hidden_remainder_z
      - .offset:         248
        .size:           8
        .value_kind:     hidden_global_offset_x
      - .offset:         256
        .size:           8
        .value_kind:     hidden_global_offset_y
      - .offset:         264
        .size:           8
        .value_kind:     hidden_global_offset_z
      - .offset:         272
        .size:           2
        .value_kind:     hidden_grid_dims
      - .offset:         296
        .size:           8
        .value_kind:     hidden_multigrid_sync_arg
      - .offset:         328
        .size:           4
        .value_kind:     hidden_dynamic_lds_size
    .group_segment_fixed_size: 16384
    .kernarg_segment_align: 8
    .kernarg_segment_size: 464
    .language:       OpenCL C
    .language_version:
      - 2
      - 0
    .max_flat_workgroup_size: 512
    .name:           _Z14fwd_megakernel6Params
    .private_segment_fixed_size: 0
    .sgpr_count:     106
    .sgpr_spill_count: 133
    .symbol:         _Z14fwd_megakernel6Params.kd
    .uniform_work_group_size: 1
    .uses_dynamic_stack: false
    .vgpr_count:     256
    .vgpr_spill_count: 0
    .wavefront_size: 64
